# v16 + back-edge rotation in the six GEMM K-loops (counter/pointer updates and exit test in front of the loop-back barrier) + final-phase write-after-read guard address fixed (ws-relative via s[52:53])
# speedup vs baseline: 1.0009x; 1.0009x over previous
; #define PG8_STAGE(bufoff, gbase, voff) do { _Pragma("unroll") for (int _i = 0; _i < 2; ++_i) \
;         __builtin_amdgcn_global_load_lds((const unsigned*)((const char*)(gbase) + (voff)[_i]), (LAS unsigned*)(lds + (bufoff) + ldsw + _i * 8192), 16, 0, 0); } while (0)
; #define PG8_LDA(dst, b, h) do { _Pragma("unroll") for (int m = 0; m < 4; ++m) _Pragma("unroll") for (int k = 0; k < 2; ++k) dst[m][k] = *(const LAS bf16x8*)(lds + PG8_SA(b, h) + aoff + m * 2048 + k * 1024); } while (0)
; #define PG8_LDB(dst, b, h) do { _Pragma("unroll") for (int n = 0; n < 2; ++n) _Pragma("unroll") for (int k = 0; k < 2; ++k) dst[n][k] = *(const LAS bf16x8*)(lds + PG8_SB(b, h) + boff + n * 2048 + k * 1024); } while (0)
; #define PG8_MMA(ai, bj, At, Bt) do { __builtin_amdgcn_s_setprio(1); _Pragma("unroll") for (int m = 0; m < 4; ++m) _Pragma("unroll") for (int n = 0; n < 2; ++n) _Pragma("unroll") for (int k = 0; k < 2; ++k) \
;         acc[ai][bj][m][n] = __builtin_amdgcn_mfma_f32_16x16x32_bf16(Bt[n][k], At[m][k], acc[ai][bj][m][n], 0, 0, 0); __builtin_amdgcn_s_setprio(0); } while (0)
; #define PG8_WAIT_V(n) asm volatile("s_waitcnt vmcnt(" #n ")" ::: "memory")
; #define PG8_WAIT_L(n) asm volatile("s_waitcnt lgkmcnt(" #n ")" ::: "memory")
; #define PG8_BAR __builtin_amdgcn_s_barrier()
; template <class Epi, bool ALIGN_EPI = false, bool SP2 = true>
; __device__ __forceinline__ void gemm_phase(LAS unsigned char* lds, const Gemm g, const StaticOrder& S, const Epi& E) {
;     ...
;         for (int t = 0; t < nt; t += 2) {
;             const bool last = (t == nt - 2);
;             const char* a1 = cA + (size_t)(t + 1) * kstep;
;             const char* a2 = last ? nA : cA + (size_t)(t + 2) * kstep; const char* b2 = last ? nB : cB + (size_t)(t + 2) * kstep;
;             const char* a3 = a2 + kstep; const char* b3 = b2 + kstep;
;             if constexpr (SP2) {
;             PG8_LDB(B0, 0, 0); PG8_LDB(B1, 0, 1); PG8_SCHED; PG8_LDA(At, 0, 0); PG8_STAGE(PG8_SA(1, 1), a1 + hstep, voffA);
;             PG8_WAIT_V(8); PG8_WAIT_L(0); PG8_BAR; PG8_MMA(0, 0, At, B0); PG8_MMA(0, 1, At, B1); PG8_BAR; PG8_SCHED;
;             PG8_LDA(At, 0, 1); PG8_STAGE(PG8_SB(0, 0), b2, voffB); PG8_STAGE(PG8_SB(0, 1), b2 + hstep, voffB); PG8_STAGE(PG8_SA(0, 0), a2, voffA);
;             PG8_WAIT_V(8); PG8_WAIT_L(0); PG8_BAR; PG8_MMA(1, 0, At, B0); PG8_MMA(1, 1, At, B1); PG8_BAR; PG8_SCHED;
.LBB0_155:
	ds_read_b128 v[146:149], v157
	s_waitcnt lgkmcnt(0)
	ds_read_b128 v[150:153], v157 offset:1024
	ds_read_b128 v[166:169], v157 offset:2048
	ds_read_b128 v[170:173], v157 offset:3072
	ds_read_b128 v[174:177], v158
	ds_read_b128 v[178:181], v158 offset:1024
	ds_read_b128 v[182:185], v158 offset:2048
	ds_read_b128 v[186:189], v158 offset:3072
	s_add_u32 s74, s72, 0xfff80080
	s_addc_u32 s75, s73, -1
	s_cmp_eq_u32 s96, 28
	s_cselect_b32 s77, s65, s75
	s_cselect_b32 s76, s91, s74
	s_cselect_b32 s75, s63, s95
	s_cselect_b32 s74, s93, s94
	v_lshl_add_u64 v[162:163], s[72:73], 0, v[138:139]
	s_add_i32 m0, s71, 0xc000
	ds_read_b128 v[190:193], v159
	ds_read_b128 v[194:197], v159 offset:1024
	ds_read_b128 v[198:201], v159 offset:2048
	ds_read_b128 v[202:205], v159 offset:3072
	ds_read_b128 v[206:209], v159 offset:4096
	ds_read_b128 v[210:213], v159 offset:5120
	ds_read_b128 v[216:219], v159 offset:6144
	ds_read_b128 v[220:223], v159 offset:7168
	global_load_lds_dwordx4 v[162:163], off
	v_lshl_add_u64 v[162:163], s[72:73], 0, v[140:141]
	s_add_i32 m0, s71, 0xe000
	s_nop 0
	global_load_lds_dwordx4 v[162:163], off
	s_waitcnt vmcnt(8)
	s_waitcnt lgkmcnt(0)
	s_barrier
	s_setprio 1
	s_waitcnt lgkmcnt(0)
	v_mfma_f32_16x16x32_bf16 v[124:127], v[146:149], v[190:193], v[124:127]
	v_mfma_f32_16x16x32_bf16 v[120:123], v[166:169], v[190:193], v[120:123]
	v_mfma_f32_16x16x32_bf16 v[108:111], v[146:149], v[198:201], v[108:111]
	v_mfma_f32_16x16x32_bf16 v[104:107], v[166:169], v[198:201], v[104:107]
	v_mfma_f32_16x16x32_bf16 v[92:95], v[146:149], v[206:209], v[92:95]
	v_mfma_f32_16x16x32_bf16 v[88:91], v[166:169], v[206:209], v[88:91]
	v_mfma_f32_16x16x32_bf16 v[76:79], v[146:149], v[216:219], v[76:79]
	v_mfma_f32_16x16x32_bf16 v[72:75], v[166:169], v[216:219], v[72:75]
	v_mfma_f32_16x16x32_bf16 v[124:127], v[150:153], v[194:197], v[124:127]
	v_mfma_f32_16x16x32_bf16 v[120:123], v[170:173], v[194:197], v[120:123]
	v_mfma_f32_16x16x32_bf16 v[108:111], v[150:153], v[202:205], v[108:111]
	v_mfma_f32_16x16x32_bf16 v[104:107], v[170:173], v[202:205], v[104:107]
	v_mfma_f32_16x16x32_bf16 v[92:95], v[150:153], v[210:213], v[92:95]
	v_mfma_f32_16x16x32_bf16 v[88:91], v[170:173], v[210:213], v[88:91]
	v_mfma_f32_16x16x32_bf16 v[76:79], v[150:153], v[220:223], v[76:79]
	v_mfma_f32_16x16x32_bf16 v[72:75], v[170:173], v[220:223], v[72:75]
	s_setprio 0
	s_setprio 1
	v_mfma_f32_16x16x32_bf16 v[116:119], v[174:177], v[190:193], v[116:119]
	v_mfma_f32_16x16x32_bf16 v[112:115], v[182:185], v[190:193], v[112:115]
	v_mfma_f32_16x16x32_bf16 v[100:103], v[174:177], v[198:201], v[100:103]
	v_mfma_f32_16x16x32_bf16 v[96:99], v[182:185], v[198:201], v[96:99]
	v_mfma_f32_16x16x32_bf16 v[84:87], v[174:177], v[206:209], v[84:87]
	v_mfma_f32_16x16x32_bf16 v[80:83], v[182:185], v[206:209], v[80:83]
	v_mfma_f32_16x16x32_bf16 v[68:71], v[174:177], v[216:219], v[68:71]
	v_mfma_f32_16x16x32_bf16 v[64:67], v[182:185], v[216:219], v[64:67]
	v_mfma_f32_16x16x32_bf16 v[116:119], v[178:181], v[194:197], v[116:119]
	v_mfma_f32_16x16x32_bf16 v[112:115], v[186:189], v[194:197], v[112:115]
	v_mfma_f32_16x16x32_bf16 v[100:103], v[178:181], v[202:205], v[100:103]
	v_mfma_f32_16x16x32_bf16 v[96:99], v[186:189], v[202:205], v[96:99]
	v_mfma_f32_16x16x32_bf16 v[84:87], v[178:181], v[210:213], v[84:87]
	v_mfma_f32_16x16x32_bf16 v[80:83], v[186:189], v[210:213], v[80:83]
	v_mfma_f32_16x16x32_bf16 v[68:71], v[178:181], v[220:223], v[68:71]
	v_mfma_f32_16x16x32_bf16 v[64:67], v[186:189], v[220:223], v[64:67]
	s_setprio 0
	s_barrier
	s_add_i32 s97, s88, s3
	v_lshl_add_u64 v[162:163], s[74:75], 0, v[130:131]
	s_mov_b32 m0, s97
	ds_read_b128 v[190:193], v159 offset:16384
	ds_read_b128 v[194:197], v159 offset:17408
	ds_read_b128 v[198:201], v159 offset:18432
	ds_read_b128 v[202:205], v159 offset:19456
	ds_read_b128 v[206:209], v159 offset:20480
	ds_read_b128 v[210:213], v159 offset:21504
	ds_read_b128 v[216:219], v159 offset:22528
	ds_read_b128 v[220:223], v159 offset:23552
	global_load_lds_dwordx4 v[162:163], off
	s_add_i32 m0, s97, 0x2000
	s_add_u32 vcc_lo, s74, 0x80000
	v_lshl_add_u64 v[224:225], s[74:75], 0, v[134:135]
	s_addc_u32 vcc_hi, s75, 0
	s_add_i32 s97, s89, s3
	global_load_lds_dwordx4 v[224:225], off
	v_lshl_add_u64 v[226:227], vcc, 0, v[130:131]
	s_mov_b32 m0, s97
	v_lshl_add_u64 v[228:229], s[76:77], 0, v[132:133]
	global_load_lds_dwordx4 v[226:227], off
	v_lshl_add_u64 v[226:227], vcc, 0, v[134:135]
	s_add_i32 m0, s97, 0x2000
	s_nop 0
	global_load_lds_dwordx4 v[226:227], off
	v_lshl_add_u64 v[226:227], s[76:77], 0, v[128:129]
	s_mov_b32 m0, s71
	s_nop 0
	global_load_lds_dwordx4 v[226:227], off
	s_mov_b32 m0, s78
	s_nop 0
	global_load_lds_dwordx4 v[228:229], off
	s_waitcnt vmcnt(8)
	s_waitcnt lgkmcnt(0)
	s_barrier
; #define PG8_STAGE(bufoff, gbase, voff) do { _Pragma("unroll") for (int _i = 0; _i < 2; ++_i) \
;         __builtin_amdgcn_global_load_lds((const unsigned*)((const char*)(gbase) + (voff)[_i]), (LAS unsigned*)(lds + (bufoff) + ldsw + _i * 8192), 16, 0, 0); } while (0)
; #define PG8_LDA(dst, b, h) do { _Pragma("unroll") for (int m = 0; m < 4; ++m) _Pragma("unroll") for (int k = 0; k < 2; ++k) dst[m][k] = *(const LAS bf16x8*)(lds + PG8_SA(b, h) + aoff + m * 2048 + k * 1024); } while (0)
; #define PG8_LDB(dst, b, h) do { _Pragma("unroll") for (int n = 0; n < 2; ++n) _Pragma("unroll") for (int k = 0; k < 2; ++k) dst[n][k] = *(const LAS bf16x8*)(lds + PG8_SB(b, h) + boff + n * 2048 + k * 1024); } while (0)
; #define PG8_MMA(ai, bj, At, Bt) do { __builtin_amdgcn_s_setprio(1); _Pragma("unroll") for (int m = 0; m < 4; ++m) _Pragma("unroll") for (int n = 0; n < 2; ++n) _Pragma("unroll") for (int k = 0; k < 2; ++k) \
;         acc[ai][bj][m][n] = __builtin_amdgcn_mfma_f32_16x16x32_bf16(Bt[n][k], At[m][k], acc[ai][bj][m][n], 0, 0, 0); __builtin_amdgcn_s_setprio(0); } while (0)
; #define PG8_WAIT_V(n) asm volatile("s_waitcnt vmcnt(" #n ")" ::: "memory")
; #define PG8_WAIT_L(n) asm volatile("s_waitcnt lgkmcnt(" #n ")" ::: "memory")
; #define PG8_BAR __builtin_amdgcn_s_barrier()
; #define PG8_SCHED __builtin_amdgcn_sched_barrier(0)
; template <class Epi, bool ALIGN_EPI = false, bool SP2 = true>
; __device__ __forceinline__ void gemm_phase(LAS unsigned char* lds, const Gemm g, const StaticOrder& S, const Epi& E) {
;     ...
;             PG8_WAIT_V(8); PG8_WAIT_L(0); PG8_BAR; PG8_MMA(1, 0, At, B0); PG8_MMA(1, 1, At, B1); PG8_BAR; PG8_SCHED;
;             PG8_LDB(B0, 1, 0); PG8_LDB(B1, 1, 1); PG8_SCHED; PG8_LDA(At, 1, 0); PG8_STAGE(PG8_SA(0, 1), a2 + hstep, voffA);
;             PG8_WAIT_V(8); PG8_WAIT_L(0); PG8_BAR; PG8_MMA(0, 0, At, B0); PG8_MMA(0, 1, At, B1); PG8_BAR; PG8_SCHED;
	s_setprio 1
	s_waitcnt lgkmcnt(0)
	v_mfma_f32_16x16x32_bf16 v[60:63], v[146:149], v[190:193], v[60:63]
	v_mfma_f32_16x16x32_bf16 v[56:59], v[166:169], v[190:193], v[56:59]
	v_mfma_f32_16x16x32_bf16 v[44:47], v[146:149], v[198:201], v[44:47]
	v_mfma_f32_16x16x32_bf16 v[40:43], v[166:169], v[198:201], v[40:43]
	v_mfma_f32_16x16x32_bf16 v[28:31], v[146:149], v[206:209], v[28:31]
	v_mfma_f32_16x16x32_bf16 v[24:27], v[166:169], v[206:209], v[24:27]
	v_mfma_f32_16x16x32_bf16 v[12:15], v[146:149], v[216:219], v[12:15]
	v_mfma_f32_16x16x32_bf16 v[8:11], v[166:169], v[216:219], v[8:11]
	v_mfma_f32_16x16x32_bf16 v[60:63], v[150:153], v[194:197], v[60:63]
	v_mfma_f32_16x16x32_bf16 v[56:59], v[170:173], v[194:197], v[56:59]
	v_mfma_f32_16x16x32_bf16 v[44:47], v[150:153], v[202:205], v[44:47]
	v_mfma_f32_16x16x32_bf16 v[40:43], v[170:173], v[202:205], v[40:43]
	v_mfma_f32_16x16x32_bf16 v[28:31], v[150:153], v[210:213], v[28:31]
	v_mfma_f32_16x16x32_bf16 v[24:27], v[170:173], v[210:213], v[24:27]
	v_mfma_f32_16x16x32_bf16 v[12:15], v[150:153], v[220:223], v[12:15]
	v_mfma_f32_16x16x32_bf16 v[8:11], v[170:173], v[220:223], v[8:11]
	s_setprio 0
	s_setprio 1
	v_mfma_f32_16x16x32_bf16 v[52:55], v[174:177], v[190:193], v[52:55]
	v_mfma_f32_16x16x32_bf16 v[48:51], v[182:185], v[190:193], v[48:51]
	v_mfma_f32_16x16x32_bf16 v[36:39], v[174:177], v[198:201], v[36:39]
	v_mfma_f32_16x16x32_bf16 v[32:35], v[182:185], v[198:201], v[32:35]
	v_mfma_f32_16x16x32_bf16 v[20:23], v[174:177], v[206:209], v[20:23]
	v_mfma_f32_16x16x32_bf16 v[16:19], v[182:185], v[206:209], v[16:19]
	v_mfma_f32_16x16x32_bf16 v[4:7], v[174:177], v[216:219], v[4:7]
	v_mfma_f32_16x16x32_bf16 v[0:3], v[182:185], v[216:219], v[0:3]
	v_mfma_f32_16x16x32_bf16 v[52:55], v[178:181], v[194:197], v[52:55]
	v_mfma_f32_16x16x32_bf16 v[48:51], v[186:189], v[194:197], v[48:51]
	v_mfma_f32_16x16x32_bf16 v[36:39], v[178:181], v[202:205], v[36:39]
	v_mfma_f32_16x16x32_bf16 v[32:35], v[186:189], v[202:205], v[32:35]
	v_mfma_f32_16x16x32_bf16 v[20:23], v[178:181], v[210:213], v[20:23]
	v_mfma_f32_16x16x32_bf16 v[16:19], v[186:189], v[210:213], v[16:19]
	v_mfma_f32_16x16x32_bf16 v[4:7], v[178:181], v[220:223], v[4:7]
	v_mfma_f32_16x16x32_bf16 v[0:3], v[186:189], v[220:223], v[0:3]
	s_setprio 0
	s_barrier
	s_add_i32 s97, 0, 0x18000
	v_add_u32_e32 v136, s97, v155
	s_add_i32 vcc_lo, 0, 0x1c000
	ds_read_b128 v[146:149], v136
	ds_read_b128 v[150:153], v136 offset:1024
	ds_read_b128 v[166:169], v136 offset:2048
	ds_read_b128 v[170:173], v136 offset:3072
	v_add_u32_e32 v136, vcc_lo, v155
	ds_read_b128 v[174:177], v136
	ds_read_b128 v[178:181], v136 offset:1024
	ds_read_b128 v[182:185], v136 offset:2048
	ds_read_b128 v[186:189], v136 offset:3072
	s_add_u32 s76, s76, 0x80000
	s_addc_u32 s77, s77, 0
	s_mov_b32 m0, s79
	v_lshl_add_u64 v[230:231], s[76:77], 0, v[128:129]
	ds_read_b128 v[190:193], v159 offset:32768
	ds_read_b128 v[194:197], v159 offset:33792
	ds_read_b128 v[198:201], v159 offset:34816
	ds_read_b128 v[202:205], v159 offset:35840
	ds_read_b128 v[206:209], v159 offset:36864
	ds_read_b128 v[210:213], v159 offset:37888
	ds_read_b128 v[216:219], v159 offset:38912
	ds_read_b128 v[220:223], v159 offset:39936
	global_load_lds_dwordx4 v[230:231], off
	v_lshl_add_u64 v[230:231], s[76:77], 0, v[132:133]
	s_mov_b32 m0, s80
	s_nop 0
	global_load_lds_dwordx4 v[230:231], off
	s_waitcnt vmcnt(8)
	s_waitcnt lgkmcnt(0)
	s_barrier
	s_setprio 1
	s_waitcnt lgkmcnt(0)
	v_mfma_f32_16x16x32_bf16 v[124:127], v[146:149], v[190:193], v[124:127]
	v_mfma_f32_16x16x32_bf16 v[120:123], v[166:169], v[190:193], v[120:123]
	v_mfma_f32_16x16x32_bf16 v[108:111], v[146:149], v[198:201], v[108:111]
	v_mfma_f32_16x16x32_bf16 v[104:107], v[166:169], v[198:201], v[104:107]
	v_mfma_f32_16x16x32_bf16 v[92:95], v[146:149], v[206:209], v[92:95]
	v_mfma_f32_16x16x32_bf16 v[88:91], v[166:169], v[206:209], v[88:91]
	v_mfma_f32_16x16x32_bf16 v[76:79], v[146:149], v[216:219], v[76:79]
	v_mfma_f32_16x16x32_bf16 v[72:75], v[166:169], v[216:219], v[72:75]
	v_mfma_f32_16x16x32_bf16 v[124:127], v[150:153], v[194:197], v[124:127]
	v_mfma_f32_16x16x32_bf16 v[120:123], v[170:173], v[194:197], v[120:123]
	v_mfma_f32_16x16x32_bf16 v[108:111], v[150:153], v[202:205], v[108:111]
	v_mfma_f32_16x16x32_bf16 v[104:107], v[170:173], v[202:205], v[104:107]
	v_mfma_f32_16x16x32_bf16 v[92:95], v[150:153], v[210:213], v[92:95]
	v_mfma_f32_16x16x32_bf16 v[88:91], v[170:173], v[210:213], v[88:91]
	v_mfma_f32_16x16x32_bf16 v[76:79], v[150:153], v[220:223], v[76:79]
	v_mfma_f32_16x16x32_bf16 v[72:75], v[170:173], v[220:223], v[72:75]
	s_setprio 0
	s_setprio 1
	v_mfma_f32_16x16x32_bf16 v[116:119], v[174:177], v[190:193], v[116:119]
	v_mfma_f32_16x16x32_bf16 v[112:115], v[182:185], v[190:193], v[112:115]
	v_mfma_f32_16x16x32_bf16 v[100:103], v[174:177], v[198:201], v[100:103]
	v_mfma_f32_16x16x32_bf16 v[96:99], v[182:185], v[198:201], v[96:99]
	v_mfma_f32_16x16x32_bf16 v[84:87], v[174:177], v[206:209], v[84:87]
	v_mfma_f32_16x16x32_bf16 v[80:83], v[182:185], v[206:209], v[80:83]
	v_mfma_f32_16x16x32_bf16 v[68:71], v[174:177], v[216:219], v[68:71]
	v_mfma_f32_16x16x32_bf16 v[64:67], v[182:185], v[216:219], v[64:67]
	v_mfma_f32_16x16x32_bf16 v[116:119], v[178:181], v[194:197], v[116:119]
	v_mfma_f32_16x16x32_bf16 v[112:115], v[186:189], v[194:197], v[112:115]
	v_mfma_f32_16x16x32_bf16 v[100:103], v[178:181], v[202:205], v[100:103]
	v_mfma_f32_16x16x32_bf16 v[96:99], v[186:189], v[202:205], v[96:99]
	v_mfma_f32_16x16x32_bf16 v[84:87], v[178:181], v[210:213], v[84:87]
	v_mfma_f32_16x16x32_bf16 v[80:83], v[186:189], v[210:213], v[80:83]
	v_mfma_f32_16x16x32_bf16 v[68:71], v[178:181], v[220:223], v[68:71]
	v_mfma_f32_16x16x32_bf16 v[64:67], v[186:189], v[220:223], v[64:67]
	s_setprio 0
	s_barrier
; #define PG8_STAGE(bufoff, gbase, voff) do { _Pragma("unroll") for (int _i = 0; _i < 2; ++_i) \
;         __builtin_amdgcn_global_load_lds((const unsigned*)((const char*)(gbase) + (voff)[_i]), (LAS unsigned*)(lds + (bufoff) + ldsw + _i * 8192), 16, 0, 0); } while (0)
; #define PG8_LDA(dst, b, h) do { _Pragma("unroll") for (int m = 0; m < 4; ++m) _Pragma("unroll") for (int k = 0; k < 2; ++k) dst[m][k] = *(const LAS bf16x8*)(lds + PG8_SA(b, h) + aoff + m * 2048 + k * 1024); } while (0)
; #define PG8_MMA(ai, bj, At, Bt) do { __builtin_amdgcn_s_setprio(1); _Pragma("unroll") for (int m = 0; m < 4; ++m) _Pragma("unroll") for (int n = 0; n < 2; ++n) _Pragma("unroll") for (int k = 0; k < 2; ++k) \
;         acc[ai][bj][m][n] = __builtin_amdgcn_mfma_f32_16x16x32_bf16(Bt[n][k], At[m][k], acc[ai][bj][m][n], 0, 0, 0); __builtin_amdgcn_s_setprio(0); } while (0)
; #define PG8_WAIT_V(n) asm volatile("s_waitcnt vmcnt(" #n ")" ::: "memory")
; #define PG8_WAIT_L(n) asm volatile("s_waitcnt lgkmcnt(" #n ")" ::: "memory")
; #define PG8_BAR __builtin_amdgcn_s_barrier()
; #define PG8_SCHED __builtin_amdgcn_sched_barrier(0)
; template <class Epi, bool ALIGN_EPI = false, bool SP2 = true>
; __device__ __forceinline__ void gemm_phase(LAS unsigned char* lds, const Gemm g, const StaticOrder& S, const Epi& E) {
;     ...
;             PG8_LDA(At, 1, 1); PG8_STAGE(PG8_SB(1, 0), b3, voffB); PG8_STAGE(PG8_SB(1, 1), b3 + hstep, voffB); PG8_STAGE(PG8_SA(1, 0), a3, voffA);
;             PG8_WAIT_V(8); PG8_WAIT_L(0); PG8_BAR; PG8_MMA(1, 0, At, B0); PG8_MMA(1, 1, At, B1); PG8_BAR; PG8_SCHED;
;     ...
;         if constexpr (ALIGN_EPI) { if (wr == 0) PG8_BAR; }
	s_add_i32 s76, s97, s3
	v_lshl_add_u64 v[162:163], v[162:163], 0, s[36:37]
	s_mov_b32 m0, s76
	ds_read_b128 v[190:193], v159 offset:49152
	ds_read_b128 v[194:197], v159 offset:50176
	ds_read_b128 v[198:201], v159 offset:51200
	ds_read_b128 v[202:205], v159 offset:52224
	ds_read_b128 v[206:209], v159 offset:53248
	ds_read_b128 v[210:213], v159 offset:54272
	ds_read_b128 v[216:219], v159 offset:55296
	ds_read_b128 v[220:223], v159 offset:56320
	global_load_lds_dwordx4 v[162:163], off
	s_add_i32 m0, s76, 0x2000
	s_add_u32 s74, s74, 0x80080
	v_lshl_add_u64 v[162:163], v[224:225], 0, s[36:37]
	s_addc_u32 s75, s75, 0
	s_add_i32 s76, vcc_lo, s3
	global_load_lds_dwordx4 v[162:163], off
	v_lshl_add_u64 v[162:163], s[74:75], 0, v[130:131]
	s_mov_b32 m0, s76
	s_nop 0
	global_load_lds_dwordx4 v[162:163], off
	v_lshl_add_u64 v[162:163], s[74:75], 0, v[134:135]
	s_add_i32 m0, s76, 0x2000
	s_nop 0
	global_load_lds_dwordx4 v[162:163], off
	v_lshl_add_u64 v[162:163], v[226:227], 0, s[36:37]
	s_mov_b32 m0, s82
	s_nop 0
	global_load_lds_dwordx4 v[162:163], off
	v_lshl_add_u64 v[162:163], v[228:229], 0, s[36:37]
	s_mov_b32 m0, s83
	s_nop 0
	global_load_lds_dwordx4 v[162:163], off
	s_waitcnt vmcnt(8)
	s_waitcnt lgkmcnt(0)
	s_barrier
	s_setprio 1
	s_waitcnt lgkmcnt(0)
	v_mfma_f32_16x16x32_bf16 v[60:63], v[146:149], v[190:193], v[60:63]
	v_mfma_f32_16x16x32_bf16 v[56:59], v[166:169], v[190:193], v[56:59]
	v_mfma_f32_16x16x32_bf16 v[44:47], v[146:149], v[198:201], v[44:47]
	v_mfma_f32_16x16x32_bf16 v[40:43], v[166:169], v[198:201], v[40:43]
	v_mfma_f32_16x16x32_bf16 v[28:31], v[146:149], v[206:209], v[28:31]
	v_mfma_f32_16x16x32_bf16 v[24:27], v[166:169], v[206:209], v[24:27]
	v_mfma_f32_16x16x32_bf16 v[12:15], v[146:149], v[216:219], v[12:15]
	v_mfma_f32_16x16x32_bf16 v[8:11], v[166:169], v[216:219], v[8:11]
	v_mfma_f32_16x16x32_bf16 v[60:63], v[150:153], v[194:197], v[60:63]
	v_mfma_f32_16x16x32_bf16 v[56:59], v[170:173], v[194:197], v[56:59]
	v_mfma_f32_16x16x32_bf16 v[44:47], v[150:153], v[202:205], v[44:47]
	v_mfma_f32_16x16x32_bf16 v[40:43], v[170:173], v[202:205], v[40:43]
	v_mfma_f32_16x16x32_bf16 v[28:31], v[150:153], v[210:213], v[28:31]
	v_mfma_f32_16x16x32_bf16 v[24:27], v[170:173], v[210:213], v[24:27]
	v_mfma_f32_16x16x32_bf16 v[12:15], v[150:153], v[220:223], v[12:15]
	v_mfma_f32_16x16x32_bf16 v[8:11], v[170:173], v[220:223], v[8:11]
	s_setprio 0
	s_setprio 1
	v_mfma_f32_16x16x32_bf16 v[52:55], v[174:177], v[190:193], v[52:55]
	v_mfma_f32_16x16x32_bf16 v[48:51], v[182:185], v[190:193], v[48:51]
	v_mfma_f32_16x16x32_bf16 v[36:39], v[174:177], v[198:201], v[36:39]
	v_mfma_f32_16x16x32_bf16 v[32:35], v[182:185], v[198:201], v[32:35]
	v_mfma_f32_16x16x32_bf16 v[20:23], v[174:177], v[206:209], v[20:23]
	v_mfma_f32_16x16x32_bf16 v[16:19], v[182:185], v[206:209], v[16:19]
	v_mfma_f32_16x16x32_bf16 v[4:7], v[174:177], v[216:219], v[4:7]
	v_mfma_f32_16x16x32_bf16 v[0:3], v[182:185], v[216:219], v[0:3]
	v_mfma_f32_16x16x32_bf16 v[52:55], v[178:181], v[194:197], v[52:55]
	v_mfma_f32_16x16x32_bf16 v[48:51], v[186:189], v[194:197], v[48:51]
	v_mfma_f32_16x16x32_bf16 v[36:39], v[178:181], v[202:205], v[36:39]
	v_mfma_f32_16x16x32_bf16 v[32:35], v[186:189], v[202:205], v[32:35]
	v_mfma_f32_16x16x32_bf16 v[20:23], v[178:181], v[210:213], v[20:23]
	v_mfma_f32_16x16x32_bf16 v[16:19], v[186:189], v[210:213], v[16:19]
	v_mfma_f32_16x16x32_bf16 v[4:7], v[178:181], v[220:223], v[4:7]
	v_mfma_f32_16x16x32_bf16 v[0:3], v[186:189], v[220:223], v[0:3]
	s_add_i32 s96, s96, 2
	s_add_u32 s72, s72, 0x100
	s_addc_u32 s73, s73, 0
	s_add_u32 s94, s94, 0x100
	s_addc_u32 s95, s95, 0
	s_cmp_gt_u32 s96, 29
	s_setprio 0
	s_barrier
	s_cbranch_scc0 .LBB0_155
	s_and_b64 vcc, exec, s[60:61]
	s_cbranch_vccz .LBB0_158
	s_barrier

; #define PG8_STAGE(bufoff, gbase, voff) do { _Pragma("unroll") for (int _i = 0; _i < 2; ++_i) \
;         __builtin_amdgcn_global_load_lds((const unsigned*)((const char*)(gbase) + (voff)[_i]), (LAS unsigned*)(lds + (bufoff) + ldsw + _i * 8192), 16, 0, 0); } while (0)
; #define PG8_LDA(dst, b, h) do { _Pragma("unroll") for (int m = 0; m < 4; ++m) _Pragma("unroll") for (int k = 0; k < 2; ++k) dst[m][k] = *(const LAS bf16x8*)(lds + PG8_SA(b, h) + aoff + m * 2048 + k * 1024); } while (0)
; #define PG8_LDB(dst, b, h) do { _Pragma("unroll") for (int n = 0; n < 2; ++n) _Pragma("unroll") for (int k = 0; k < 2; ++k) dst[n][k] = *(const LAS bf16x8*)(lds + PG8_SB(b, h) + boff + n * 2048 + k * 1024); } while (0)
; #define PG8_MMA(ai, bj, At, Bt) do { __builtin_amdgcn_s_setprio(1); _Pragma("unroll") for (int m = 0; m < 4; ++m) _Pragma("unroll") for (int n = 0; n < 2; ++n) _Pragma("unroll") for (int k = 0; k < 2; ++k) \
;         acc[ai][bj][m][n] = __builtin_amdgcn_mfma_f32_16x16x32_bf16(Bt[n][k], At[m][k], acc[ai][bj][m][n], 0, 0, 0); __builtin_amdgcn_s_setprio(0); } while (0)
; #define PG8_WAIT_V(n) asm volatile("s_waitcnt vmcnt(" #n ")" ::: "memory")
; #define PG8_WAIT_L(n) asm volatile("s_waitcnt lgkmcnt(" #n ")" ::: "memory")
; #define PG8_BAR __builtin_amdgcn_s_barrier()
; template <class Epi, bool ALIGN_EPI = false, bool SP2 = true>
; __device__ __forceinline__ void gemm_phase(LAS unsigned char* lds, const Gemm g, const StaticOrder& S, const Epi& E) {
;     ...
;         for (int t = 0; t < nt; t += 2) {
;             const bool last = (t == nt - 2);
;             const char* a1 = cA + (size_t)(t + 1) * kstep;
;             const char* a2 = last ? nA : cA + (size_t)(t + 2) * kstep; const char* b2 = last ? nB : cB + (size_t)(t + 2) * kstep;
;             const char* a3 = a2 + kstep; const char* b3 = b2 + kstep;
;             if constexpr (SP2) {
;             PG8_LDB(B0, 0, 0); PG8_LDB(B1, 0, 1); PG8_SCHED; PG8_LDA(At, 0, 0); PG8_STAGE(PG8_SA(1, 1), a1 + hstep, voffA);
;             PG8_WAIT_V(8); PG8_WAIT_L(0); PG8_BAR; PG8_MMA(0, 0, At, B0); PG8_MMA(0, 1, At, B1); PG8_BAR; PG8_SCHED;
;             PG8_LDA(At, 0, 1); PG8_STAGE(PG8_SB(0, 0), b2, voffB); PG8_STAGE(PG8_SB(0, 1), b2 + hstep, voffB); PG8_STAGE(PG8_SA(0, 0), a2, voffA);
;             PG8_WAIT_V(8); PG8_WAIT_L(0); PG8_BAR; PG8_MMA(1, 0, At, B0); PG8_MMA(1, 1, At, B1); PG8_BAR; PG8_SCHED;
.LBB0_325:
	v_add_u32_e32 v161, s76, v150
	s_waitcnt lgkmcnt(0)
	ds_read_b128 v[152:155], v161
	ds_read_b128 v[156:159], v161 offset:1024
	ds_read_b128 v[166:169], v161 offset:2048
	ds_read_b128 v[170:173], v161 offset:3072
	v_add_u32_e32 v161, s77, v150
	s_add_u32 s62, s0, s60
	ds_read_b128 v[174:177], v161
	ds_read_b128 v[178:181], v161 offset:1024
	ds_read_b128 v[182:185], v161 offset:2048
	ds_read_b128 v[186:189], v161 offset:3072
	s_addc_u32 s63, s1, s61
	s_add_u32 s62, s62, 0x100
	s_addc_u32 s63, s63, 0
	s_add_u32 s84, s79, s60
	s_addc_u32 s85, s80, s61
	s_cmpk_eq_i32 s60, 0xf00
	s_cselect_b32 s65, s29, s63
	s_cselect_b32 s64, s81, s62
	s_cselect_b32 s63, s27, s85
	s_cselect_b32 s62, s82, s84
	v_lshl_add_u64 v[162:163], v[144:145], 0, s[60:61]
	s_add_i32 m0, s68, 0xc000
	ds_read_b128 v[190:193], v151
	ds_read_b128 v[194:197], v151 offset:1024
	ds_read_b128 v[198:201], v151 offset:2048
	ds_read_b128 v[202:205], v151 offset:3072
	ds_read_b128 v[206:209], v151 offset:4096
	ds_read_b128 v[210:213], v151 offset:5120
	ds_read_b128 v[216:219], v151 offset:6144
	ds_read_b128 v[220:223], v151 offset:7168
	global_load_lds_dwordx4 v[162:163], off
	v_lshl_add_u64 v[162:163], v[146:147], 0, s[60:61]
	s_add_i32 m0, s68, 0xe000
	s_nop 0
	global_load_lds_dwordx4 v[162:163], off
	s_waitcnt vmcnt(8)
	s_waitcnt lgkmcnt(0)
	s_barrier
	s_setprio 1
	s_waitcnt lgkmcnt(0)
	v_mfma_f32_16x16x32_bf16 v[124:127], v[152:155], v[190:193], v[124:127]
	v_mfma_f32_16x16x32_bf16 v[120:123], v[166:169], v[190:193], v[120:123]
	v_mfma_f32_16x16x32_bf16 v[108:111], v[152:155], v[198:201], v[108:111]
	v_mfma_f32_16x16x32_bf16 v[104:107], v[166:169], v[198:201], v[104:107]
	v_mfma_f32_16x16x32_bf16 v[92:95], v[152:155], v[206:209], v[92:95]
	v_mfma_f32_16x16x32_bf16 v[88:91], v[166:169], v[206:209], v[88:91]
	v_mfma_f32_16x16x32_bf16 v[76:79], v[152:155], v[216:219], v[76:79]
	v_mfma_f32_16x16x32_bf16 v[72:75], v[166:169], v[216:219], v[72:75]
	v_mfma_f32_16x16x32_bf16 v[124:127], v[156:159], v[194:197], v[124:127]
	v_mfma_f32_16x16x32_bf16 v[120:123], v[170:173], v[194:197], v[120:123]
	v_mfma_f32_16x16x32_bf16 v[108:111], v[156:159], v[202:205], v[108:111]
	v_mfma_f32_16x16x32_bf16 v[104:107], v[170:173], v[202:205], v[104:107]
	v_mfma_f32_16x16x32_bf16 v[92:95], v[156:159], v[210:213], v[92:95]
	v_mfma_f32_16x16x32_bf16 v[88:91], v[170:173], v[210:213], v[88:91]
	v_mfma_f32_16x16x32_bf16 v[76:79], v[156:159], v[220:223], v[76:79]
	v_mfma_f32_16x16x32_bf16 v[72:75], v[170:173], v[220:223], v[72:75]
	s_setprio 0
	s_setprio 1
	v_mfma_f32_16x16x32_bf16 v[116:119], v[174:177], v[190:193], v[116:119]
	v_mfma_f32_16x16x32_bf16 v[112:115], v[182:185], v[190:193], v[112:115]
	v_mfma_f32_16x16x32_bf16 v[100:103], v[174:177], v[198:201], v[100:103]
	v_mfma_f32_16x16x32_bf16 v[96:99], v[182:185], v[198:201], v[96:99]
	v_mfma_f32_16x16x32_bf16 v[84:87], v[174:177], v[206:209], v[84:87]
	v_mfma_f32_16x16x32_bf16 v[80:83], v[182:185], v[206:209], v[80:83]
	v_mfma_f32_16x16x32_bf16 v[68:71], v[174:177], v[216:219], v[68:71]
	v_mfma_f32_16x16x32_bf16 v[64:67], v[182:185], v[216:219], v[64:67]
	v_mfma_f32_16x16x32_bf16 v[116:119], v[178:181], v[194:197], v[116:119]
	v_mfma_f32_16x16x32_bf16 v[112:115], v[186:189], v[194:197], v[112:115]
	v_mfma_f32_16x16x32_bf16 v[100:103], v[178:181], v[202:205], v[100:103]
	v_mfma_f32_16x16x32_bf16 v[96:99], v[186:189], v[202:205], v[96:99]
	v_mfma_f32_16x16x32_bf16 v[84:87], v[178:181], v[210:213], v[84:87]
	v_mfma_f32_16x16x32_bf16 v[80:83], v[186:189], v[210:213], v[80:83]
	v_mfma_f32_16x16x32_bf16 v[68:71], v[178:181], v[220:223], v[68:71]
	v_mfma_f32_16x16x32_bf16 v[64:67], v[186:189], v[220:223], v[64:67]
	s_setprio 0
	s_barrier
	s_add_i32 s84, s76, s67
	v_lshl_add_u64 v[162:163], s[62:63], 0, v[130:131]
	s_mov_b32 m0, s84
	ds_read_b128 v[190:193], v151 offset:16384
	ds_read_b128 v[194:197], v151 offset:17408
	ds_read_b128 v[198:201], v151 offset:18432
	ds_read_b128 v[202:205], v151 offset:19456
	ds_read_b128 v[206:209], v151 offset:20480
	ds_read_b128 v[210:213], v151 offset:21504
	ds_read_b128 v[216:219], v151 offset:22528
	ds_read_b128 v[220:223], v151 offset:23552
	global_load_lds_dwordx4 v[162:163], off
	s_add_i32 m0, s84, 0x2000
	s_add_u32 s84, s62, 0x80000
	v_lshl_add_u64 v[224:225], s[62:63], 0, v[134:135]
	s_addc_u32 s85, s63, 0
	s_add_i32 s86, s77, s67
	global_load_lds_dwordx4 v[224:225], off
	v_lshl_add_u64 v[226:227], s[84:85], 0, v[130:131]
	s_mov_b32 m0, s86
	v_lshl_add_u64 v[228:229], s[64:65], 0, v[132:133]
	global_load_lds_dwordx4 v[226:227], off
	v_lshl_add_u64 v[226:227], s[84:85], 0, v[134:135]
	s_add_i32 m0, s86, 0x2000
	s_nop 0
	global_load_lds_dwordx4 v[226:227], off
	v_lshl_add_u64 v[226:227], s[64:65], 0, v[128:129]
	s_mov_b32 m0, s68
	s_nop 0
	global_load_lds_dwordx4 v[226:227], off
	s_mov_b32 m0, s69
	s_nop 0
	global_load_lds_dwordx4 v[228:229], off
	s_waitcnt vmcnt(8)
	s_waitcnt lgkmcnt(0)
	s_barrier
; #define PG8_STAGE(bufoff, gbase, voff) do { _Pragma("unroll") for (int _i = 0; _i < 2; ++_i) \
;         __builtin_amdgcn_global_load_lds((const unsigned*)((const char*)(gbase) + (voff)[_i]), (LAS unsigned*)(lds + (bufoff) + ldsw + _i * 8192), 16, 0, 0); } while (0)
; #define PG8_LDA(dst, b, h) do { _Pragma("unroll") for (int m = 0; m < 4; ++m) _Pragma("unroll") for (int k = 0; k < 2; ++k) dst[m][k] = *(const LAS bf16x8*)(lds + PG8_SA(b, h) + aoff + m * 2048 + k * 1024); } while (0)
; #define PG8_LDB(dst, b, h) do { _Pragma("unroll") for (int n = 0; n < 2; ++n) _Pragma("unroll") for (int k = 0; k < 2; ++k) dst[n][k] = *(const LAS bf16x8*)(lds + PG8_SB(b, h) + boff + n * 2048 + k * 1024); } while (0)
; #define PG8_MMA(ai, bj, At, Bt) do { __builtin_amdgcn_s_setprio(1); _Pragma("unroll") for (int m = 0; m < 4; ++m) _Pragma("unroll") for (int n = 0; n < 2; ++n) _Pragma("unroll") for (int k = 0; k < 2; ++k) \
;         acc[ai][bj][m][n] = __builtin_amdgcn_mfma_f32_16x16x32_bf16(Bt[n][k], At[m][k], acc[ai][bj][m][n], 0, 0, 0); __builtin_amdgcn_s_setprio(0); } while (0)
; #define PG8_WAIT_V(n) asm volatile("s_waitcnt vmcnt(" #n ")" ::: "memory")
; #define PG8_WAIT_L(n) asm volatile("s_waitcnt lgkmcnt(" #n ")" ::: "memory")
; #define PG8_BAR __builtin_amdgcn_s_barrier()
; #define PG8_SCHED __builtin_amdgcn_sched_barrier(0)
; template <class Epi, bool ALIGN_EPI = false, bool SP2 = true>
; __device__ __forceinline__ void gemm_phase(LAS unsigned char* lds, const Gemm g, const StaticOrder& S, const Epi& E) {
;     ...
;             PG8_WAIT_V(8); PG8_WAIT_L(0); PG8_BAR; PG8_MMA(1, 0, At, B0); PG8_MMA(1, 1, At, B1); PG8_BAR; PG8_SCHED;
;             PG8_LDB(B0, 1, 0); PG8_LDB(B1, 1, 1); PG8_SCHED; PG8_LDA(At, 1, 0); PG8_STAGE(PG8_SA(0, 1), a2 + hstep, voffA);
;             PG8_WAIT_V(8); PG8_WAIT_L(0); PG8_BAR; PG8_MMA(0, 0, At, B0); PG8_MMA(0, 1, At, B1); PG8_BAR; PG8_SCHED;
	s_setprio 1
	s_waitcnt lgkmcnt(0)
	v_mfma_f32_16x16x32_bf16 v[60:63], v[152:155], v[190:193], v[60:63]
	v_mfma_f32_16x16x32_bf16 v[56:59], v[166:169], v[190:193], v[56:59]
	v_mfma_f32_16x16x32_bf16 v[44:47], v[152:155], v[198:201], v[44:47]
	v_mfma_f32_16x16x32_bf16 v[40:43], v[166:169], v[198:201], v[40:43]
	v_mfma_f32_16x16x32_bf16 v[28:31], v[152:155], v[206:209], v[28:31]
	v_mfma_f32_16x16x32_bf16 v[24:27], v[166:169], v[206:209], v[24:27]
	v_mfma_f32_16x16x32_bf16 v[12:15], v[152:155], v[216:219], v[12:15]
	v_mfma_f32_16x16x32_bf16 v[8:11], v[166:169], v[216:219], v[8:11]
	v_mfma_f32_16x16x32_bf16 v[60:63], v[156:159], v[194:197], v[60:63]
	v_mfma_f32_16x16x32_bf16 v[56:59], v[170:173], v[194:197], v[56:59]
	v_mfma_f32_16x16x32_bf16 v[44:47], v[156:159], v[202:205], v[44:47]
	v_mfma_f32_16x16x32_bf16 v[40:43], v[170:173], v[202:205], v[40:43]
	v_mfma_f32_16x16x32_bf16 v[28:31], v[156:159], v[210:213], v[28:31]
	v_mfma_f32_16x16x32_bf16 v[24:27], v[170:173], v[210:213], v[24:27]
	v_mfma_f32_16x16x32_bf16 v[12:15], v[156:159], v[220:223], v[12:15]
	v_mfma_f32_16x16x32_bf16 v[8:11], v[170:173], v[220:223], v[8:11]
	s_setprio 0
	s_setprio 1
	v_mfma_f32_16x16x32_bf16 v[52:55], v[174:177], v[190:193], v[52:55]
	v_mfma_f32_16x16x32_bf16 v[48:51], v[182:185], v[190:193], v[48:51]
	v_mfma_f32_16x16x32_bf16 v[36:39], v[174:177], v[198:201], v[36:39]
	v_mfma_f32_16x16x32_bf16 v[32:35], v[182:185], v[198:201], v[32:35]
	v_mfma_f32_16x16x32_bf16 v[20:23], v[174:177], v[206:209], v[20:23]
	v_mfma_f32_16x16x32_bf16 v[16:19], v[182:185], v[206:209], v[16:19]
	v_mfma_f32_16x16x32_bf16 v[4:7], v[174:177], v[216:219], v[4:7]
	v_mfma_f32_16x16x32_bf16 v[0:3], v[182:185], v[216:219], v[0:3]
	v_mfma_f32_16x16x32_bf16 v[52:55], v[178:181], v[194:197], v[52:55]
	v_mfma_f32_16x16x32_bf16 v[48:51], v[186:189], v[194:197], v[48:51]
	v_mfma_f32_16x16x32_bf16 v[36:39], v[178:181], v[202:205], v[36:39]
	v_mfma_f32_16x16x32_bf16 v[32:35], v[186:189], v[202:205], v[32:35]
	v_mfma_f32_16x16x32_bf16 v[20:23], v[178:181], v[210:213], v[20:23]
	v_mfma_f32_16x16x32_bf16 v[16:19], v[186:189], v[210:213], v[16:19]
	v_mfma_f32_16x16x32_bf16 v[4:7], v[178:181], v[220:223], v[4:7]
	v_mfma_f32_16x16x32_bf16 v[0:3], v[186:189], v[220:223], v[0:3]
	s_setprio 0
	s_barrier
	s_add_i32 s84, 0, 0x18000
	v_add_u32_e32 v161, s84, v150
	s_add_i32 s85, 0, 0x1c000
	ds_read_b128 v[152:155], v161
	ds_read_b128 v[156:159], v161 offset:1024
	ds_read_b128 v[166:169], v161 offset:2048
	ds_read_b128 v[170:173], v161 offset:3072
	v_add_u32_e32 v161, s85, v150
	ds_read_b128 v[174:177], v161
	ds_read_b128 v[178:181], v161 offset:1024
	ds_read_b128 v[182:185], v161 offset:2048
	ds_read_b128 v[186:189], v161 offset:3072
	s_add_u32 s64, s64, 0x80000
	s_addc_u32 s65, s65, 0
	s_mov_b32 m0, s70
	v_lshl_add_u64 v[230:231], s[64:65], 0, v[128:129]
	ds_read_b128 v[190:193], v151 offset:32768
	ds_read_b128 v[194:197], v151 offset:33792
	ds_read_b128 v[198:201], v151 offset:34816
	ds_read_b128 v[202:205], v151 offset:35840
	ds_read_b128 v[206:209], v151 offset:36864
	ds_read_b128 v[210:213], v151 offset:37888
	ds_read_b128 v[216:219], v151 offset:38912
	ds_read_b128 v[220:223], v151 offset:39936
	global_load_lds_dwordx4 v[230:231], off
	v_lshl_add_u64 v[230:231], s[64:65], 0, v[132:133]
	s_mov_b32 m0, s71
	s_nop 0
	global_load_lds_dwordx4 v[230:231], off
	s_waitcnt vmcnt(8)
	s_waitcnt lgkmcnt(0)
	s_barrier
	s_setprio 1
	s_waitcnt lgkmcnt(0)
	v_mfma_f32_16x16x32_bf16 v[124:127], v[152:155], v[190:193], v[124:127]
	v_mfma_f32_16x16x32_bf16 v[120:123], v[166:169], v[190:193], v[120:123]
	v_mfma_f32_16x16x32_bf16 v[108:111], v[152:155], v[198:201], v[108:111]
	v_mfma_f32_16x16x32_bf16 v[104:107], v[166:169], v[198:201], v[104:107]
	v_mfma_f32_16x16x32_bf16 v[92:95], v[152:155], v[206:209], v[92:95]
	v_mfma_f32_16x16x32_bf16 v[88:91], v[166:169], v[206:209], v[88:91]
	v_mfma_f32_16x16x32_bf16 v[76:79], v[152:155], v[216:219], v[76:79]
	v_mfma_f32_16x16x32_bf16 v[72:75], v[166:169], v[216:219], v[72:75]
	v_mfma_f32_16x16x32_bf16 v[124:127], v[156:159], v[194:197], v[124:127]
	v_mfma_f32_16x16x32_bf16 v[120:123], v[170:173], v[194:197], v[120:123]
	v_mfma_f32_16x16x32_bf16 v[108:111], v[156:159], v[202:205], v[108:111]
	v_mfma_f32_16x16x32_bf16 v[104:107], v[170:173], v[202:205], v[104:107]
	v_mfma_f32_16x16x32_bf16 v[92:95], v[156:159], v[210:213], v[92:95]
	v_mfma_f32_16x16x32_bf16 v[88:91], v[170:173], v[210:213], v[88:91]
	v_mfma_f32_16x16x32_bf16 v[76:79], v[156:159], v[220:223], v[76:79]
	v_mfma_f32_16x16x32_bf16 v[72:75], v[170:173], v[220:223], v[72:75]
	s_setprio 0
	s_setprio 1
	v_mfma_f32_16x16x32_bf16 v[116:119], v[174:177], v[190:193], v[116:119]
	v_mfma_f32_16x16x32_bf16 v[112:115], v[182:185], v[190:193], v[112:115]
	v_mfma_f32_16x16x32_bf16 v[100:103], v[174:177], v[198:201], v[100:103]
	v_mfma_f32_16x16x32_bf16 v[96:99], v[182:185], v[198:201], v[96:99]
	v_mfma_f32_16x16x32_bf16 v[84:87], v[174:177], v[206:209], v[84:87]
	v_mfma_f32_16x16x32_bf16 v[80:83], v[182:185], v[206:209], v[80:83]
	v_mfma_f32_16x16x32_bf16 v[68:71], v[174:177], v[216:219], v[68:71]
	v_mfma_f32_16x16x32_bf16 v[64:67], v[182:185], v[216:219], v[64:67]
	v_mfma_f32_16x16x32_bf16 v[116:119], v[178:181], v[194:197], v[116:119]
	v_mfma_f32_16x16x32_bf16 v[112:115], v[186:189], v[194:197], v[112:115]
	v_mfma_f32_16x16x32_bf16 v[100:103], v[178:181], v[202:205], v[100:103]
	v_mfma_f32_16x16x32_bf16 v[96:99], v[186:189], v[202:205], v[96:99]
	v_mfma_f32_16x16x32_bf16 v[84:87], v[178:181], v[210:213], v[84:87]
	v_mfma_f32_16x16x32_bf16 v[80:83], v[186:189], v[210:213], v[80:83]
	v_mfma_f32_16x16x32_bf16 v[68:71], v[178:181], v[220:223], v[68:71]
	v_mfma_f32_16x16x32_bf16 v[64:67], v[186:189], v[220:223], v[64:67]
	s_setprio 0
	s_barrier
; #define PG8_STAGE(bufoff, gbase, voff) do { _Pragma("unroll") for (int _i = 0; _i < 2; ++_i) \
;         __builtin_amdgcn_global_load_lds((const unsigned*)((const char*)(gbase) + (voff)[_i]), (LAS unsigned*)(lds + (bufoff) + ldsw + _i * 8192), 16, 0, 0); } while (0)
; #define PG8_LDA(dst, b, h) do { _Pragma("unroll") for (int m = 0; m < 4; ++m) _Pragma("unroll") for (int k = 0; k < 2; ++k) dst[m][k] = *(const LAS bf16x8*)(lds + PG8_SA(b, h) + aoff + m * 2048 + k * 1024); } while (0)
; #define PG8_MMA(ai, bj, At, Bt) do { __builtin_amdgcn_s_setprio(1); _Pragma("unroll") for (int m = 0; m < 4; ++m) _Pragma("unroll") for (int n = 0; n < 2; ++n) _Pragma("unroll") for (int k = 0; k < 2; ++k) \
;         acc[ai][bj][m][n] = __builtin_amdgcn_mfma_f32_16x16x32_bf16(Bt[n][k], At[m][k], acc[ai][bj][m][n], 0, 0, 0); __builtin_amdgcn_s_setprio(0); } while (0)
; #define PG8_WAIT_V(n) asm volatile("s_waitcnt vmcnt(" #n ")" ::: "memory")
; #define PG8_WAIT_L(n) asm volatile("s_waitcnt lgkmcnt(" #n ")" ::: "memory")
; #define PG8_BAR __builtin_amdgcn_s_barrier()
; #define PG8_SCHED __builtin_amdgcn_sched_barrier(0)
; template <class Epi, bool ALIGN_EPI = false, bool SP2 = true>
; __device__ __forceinline__ void gemm_phase(LAS unsigned char* lds, const Gemm g, const StaticOrder& S, const Epi& E) {
;     ...
;             PG8_LDA(At, 1, 1); PG8_STAGE(PG8_SB(1, 0), b3, voffB); PG8_STAGE(PG8_SB(1, 1), b3 + hstep, voffB); PG8_STAGE(PG8_SA(1, 0), a3, voffA);
;             PG8_WAIT_V(8); PG8_WAIT_L(0); PG8_BAR; PG8_MMA(1, 0, At, B0); PG8_MMA(1, 1, At, B1); PG8_BAR; PG8_SCHED;
;     ...
;         if (!has_next) break;
; #pragma unroll
;         for (int a = 0; a < 2; ++a)
; #pragma unroll
;             for (int b = 0; b < 2; ++b)
; #pragma unroll
;                 for (int m = 0; m < 4; ++m)
; #pragma unroll
;                     for (int n = 0; n < 2; ++n) acc[a][b][m][n] = (f32x4){0.f, 0.f, 0.f, 0.f};
;         cur = nxt; cA = nA; cB = nB; ++ui;
	s_add_i32 s64, s84, s67
	v_lshl_add_u64 v[162:163], v[162:163], 0, s[24:25]
	s_mov_b32 m0, s64
	ds_read_b128 v[190:193], v151 offset:49152
	ds_read_b128 v[194:197], v151 offset:50176
	ds_read_b128 v[198:201], v151 offset:51200
	ds_read_b128 v[202:205], v151 offset:52224
	ds_read_b128 v[206:209], v151 offset:53248
	ds_read_b128 v[210:213], v151 offset:54272
	ds_read_b128 v[216:219], v151 offset:55296
	ds_read_b128 v[220:223], v151 offset:56320
	global_load_lds_dwordx4 v[162:163], off
	s_add_i32 m0, s64, 0x2000
	s_add_u32 s62, s62, 0x80080
	v_lshl_add_u64 v[162:163], v[224:225], 0, s[24:25]
	s_addc_u32 s63, s63, 0
	s_add_i32 s64, s85, s67
	global_load_lds_dwordx4 v[162:163], off
	v_lshl_add_u64 v[162:163], s[62:63], 0, v[130:131]
	s_mov_b32 m0, s64
	s_nop 0
	global_load_lds_dwordx4 v[162:163], off
	v_lshl_add_u64 v[162:163], s[62:63], 0, v[134:135]
	s_add_i32 m0, s64, 0x2000
	s_nop 0
	global_load_lds_dwordx4 v[162:163], off
	v_lshl_add_u64 v[162:163], v[226:227], 0, s[24:25]
	s_mov_b32 m0, s73
	s_nop 0
	global_load_lds_dwordx4 v[162:163], off
	v_lshl_add_u64 v[162:163], v[228:229], 0, s[24:25]
	s_mov_b32 m0, s74
	s_nop 0
	global_load_lds_dwordx4 v[162:163], off
	s_waitcnt vmcnt(8)
	s_waitcnt lgkmcnt(0)
	s_barrier
	s_setprio 1
	s_waitcnt lgkmcnt(0)
	v_mfma_f32_16x16x32_bf16 v[60:63], v[152:155], v[190:193], v[60:63]
	v_mfma_f32_16x16x32_bf16 v[56:59], v[166:169], v[190:193], v[56:59]
	v_mfma_f32_16x16x32_bf16 v[44:47], v[152:155], v[198:201], v[44:47]
	v_mfma_f32_16x16x32_bf16 v[40:43], v[166:169], v[198:201], v[40:43]
	v_mfma_f32_16x16x32_bf16 v[28:31], v[152:155], v[206:209], v[28:31]
	v_mfma_f32_16x16x32_bf16 v[24:27], v[166:169], v[206:209], v[24:27]
	v_mfma_f32_16x16x32_bf16 v[12:15], v[152:155], v[216:219], v[12:15]
	v_mfma_f32_16x16x32_bf16 v[8:11], v[166:169], v[216:219], v[8:11]
	v_mfma_f32_16x16x32_bf16 v[60:63], v[156:159], v[194:197], v[60:63]
	v_mfma_f32_16x16x32_bf16 v[56:59], v[170:173], v[194:197], v[56:59]
	v_mfma_f32_16x16x32_bf16 v[44:47], v[156:159], v[202:205], v[44:47]
	v_mfma_f32_16x16x32_bf16 v[40:43], v[170:173], v[202:205], v[40:43]
	v_mfma_f32_16x16x32_bf16 v[28:31], v[156:159], v[210:213], v[28:31]
	v_mfma_f32_16x16x32_bf16 v[24:27], v[170:173], v[210:213], v[24:27]
	v_mfma_f32_16x16x32_bf16 v[12:15], v[156:159], v[220:223], v[12:15]
	v_mfma_f32_16x16x32_bf16 v[8:11], v[170:173], v[220:223], v[8:11]
	s_setprio 0
	s_setprio 1
	v_mfma_f32_16x16x32_bf16 v[52:55], v[174:177], v[190:193], v[52:55]
	v_mfma_f32_16x16x32_bf16 v[48:51], v[182:185], v[190:193], v[48:51]
	v_mfma_f32_16x16x32_bf16 v[36:39], v[174:177], v[198:201], v[36:39]
	v_mfma_f32_16x16x32_bf16 v[32:35], v[182:185], v[198:201], v[32:35]
	v_mfma_f32_16x16x32_bf16 v[20:23], v[174:177], v[206:209], v[20:23]
	v_mfma_f32_16x16x32_bf16 v[16:19], v[182:185], v[206:209], v[16:19]
	v_mfma_f32_16x16x32_bf16 v[4:7], v[174:177], v[216:219], v[4:7]
	v_mfma_f32_16x16x32_bf16 v[0:3], v[182:185], v[216:219], v[0:3]
	v_mfma_f32_16x16x32_bf16 v[52:55], v[178:181], v[194:197], v[52:55]
	v_mfma_f32_16x16x32_bf16 v[48:51], v[186:189], v[194:197], v[48:51]
	v_mfma_f32_16x16x32_bf16 v[36:39], v[178:181], v[202:205], v[36:39]
	v_mfma_f32_16x16x32_bf16 v[32:35], v[186:189], v[202:205], v[32:35]
	v_mfma_f32_16x16x32_bf16 v[20:23], v[178:181], v[210:213], v[20:23]
	v_mfma_f32_16x16x32_bf16 v[16:19], v[186:189], v[210:213], v[16:19]
	v_mfma_f32_16x16x32_bf16 v[4:7], v[178:181], v[220:223], v[4:7]
	v_mfma_f32_16x16x32_bf16 v[0:3], v[186:189], v[220:223], v[0:3]
	s_add_i32 s83, s83, 2
	s_add_u32 s60, s60, 0x100
	s_addc_u32 s61, s61, 0
	s_cmp_gt_u32 s83, 29
	s_setprio 0
	s_barrier
	s_cbranch_scc0 .LBB0_325
	s_add_u32 s60, s79, 0xffffff00
	s_addc_u32 s61, s80, -1
	s_andn2_b64 vcc, exec, s[6:7]
	s_cbranch_vccnz .LBB0_328
	v_mov_b32_e32 v0, 0
	s_mov_b32 s22, s26
	s_mov_b32 s18, s28
	s_mov_b64 s[0:1], s[58:59]
	s_mov_b32 s75, s78
	v_mov_b32_e32 v1, v0
	v_mov_b32_e32 v2, v0
	v_mov_b32_e32 v3, v0
	v_mov_b32_e32 v4, v0
	v_mov_b32_e32 v5, v0
	v_mov_b32_e32 v6, v0
	v_mov_b32_e32 v7, v0
	v_mov_b32_e32 v16, v0
	v_mov_b32_e32 v17, v0
	v_mov_b32_e32 v18, v0
	v_mov_b32_e32 v19, v0
	v_mov_b32_e32 v20, v0
	v_mov_b32_e32 v21, v0
	v_mov_b32_e32 v22, v0
	v_mov_b32_e32 v23, v0
	v_mov_b32_e32 v32, v0
	v_mov_b32_e32 v33, v0
	v_mov_b32_e32 v34, v0
	v_mov_b32_e32 v35, v0
	v_mov_b32_e32 v36, v0
	v_mov_b32_e32 v37, v0
	v_mov_b32_e32 v38, v0
	v_mov_b32_e32 v39, v0
	v_mov_b32_e32 v48, v0
	v_mov_b32_e32 v49, v0
	v_mov_b32_e32 v50, v0
	v_mov_b32_e32 v51, v0
	v_mov_b32_e32 v52, v0
	v_mov_b32_e32 v53, v0
	v_mov_b32_e32 v54, v0
	v_mov_b32_e32 v55, v0
	v_mov_b32_e32 v8, v0
	v_mov_b32_e32 v9, v0
	v_mov_b32_e32 v10, v0
	v_mov_b32_e32 v11, v0
	v_mov_b32_e32 v12, v0
	v_mov_b32_e32 v13, v0
	v_mov_b32_e32 v14, v0
	v_mov_b32_e32 v15, v0
	v_mov_b32_e32 v24, v0
	v_mov_b32_e32 v25, v0
	v_mov_b32_e32 v26, v0
	v_mov_b32_e32 v27, v0
	v_mov_b32_e32 v28, v0
	v_mov_b32_e32 v29, v0
	v_mov_b32_e32 v30, v0
	v_mov_b32_e32 v31, v0
	v_mov_b32_e32 v40, v0
	v_mov_b32_e32 v41, v0
	v_mov_b32_e32 v42, v0
	v_mov_b32_e32 v43, v0
	v_mov_b32_e32 v44, v0
	v_mov_b32_e32 v45, v0
	v_mov_b32_e32 v46, v0
	v_mov_b32_e32 v47, v0
	v_mov_b32_e32 v56, v0
	v_mov_b32_e32 v57, v0
	v_mov_b32_e32 v58, v0
	v_mov_b32_e32 v59, v0
	v_mov_b32_e32 v60, v0
	v_mov_b32_e32 v61, v0
	v_mov_b32_e32 v62, v0
	v_mov_b32_e32 v63, v0
	v_mov_b32_e32 v64, v0
	v_mov_b32_e32 v65, v0
	v_mov_b32_e32 v66, v0
	v_mov_b32_e32 v67, v0
	v_mov_b32_e32 v68, v0
	v_mov_b32_e32 v69, v0
	v_mov_b32_e32 v70, v0
	v_mov_b32_e32 v71, v0
	v_mov_b32_e32 v80, v0
	v_mov_b32_e32 v81, v0
	v_mov_b32_e32 v82, v0
	v_mov_b32_e32 v83, v0
	v_mov_b32_e32 v84, v0
	v_mov_b32_e32 v85, v0
	v_mov_b32_e32 v86, v0
	v_mov_b32_e32 v87, v0
	v_mov_b32_e32 v96, v0
	v_mov_b32_e32 v97, v0
	v_mov_b32_e32 v98, v0
	v_mov_b32_e32 v99, v0
	v_mov_b32_e32 v100, v0
	v_mov_b32_e32 v101, v0
	v_mov_b32_e32 v102, v0
	v_mov_b32_e32 v103, v0
	v_mov_b32_e32 v112, v0
	v_mov_b32_e32 v113, v0
	v_mov_b32_e32 v114, v0
	v_mov_b32_e32 v115, v0
	v_mov_b32_e32 v116, v0
	v_mov_b32_e32 v117, v0
	v_mov_b32_e32 v118, v0
	v_mov_b32_e32 v119, v0
	v_mov_b32_e32 v72, v0
	v_mov_b32_e32 v73, v0
	v_mov_b32_e32 v74, v0
	v_mov_b32_e32 v75, v0
	v_mov_b32_e32 v76, v0
	v_mov_b32_e32 v77, v0
	v_mov_b32_e32 v78, v0
	v_mov_b32_e32 v79, v0
	v_mov_b32_e32 v88, v0
	v_mov_b32_e32 v89, v0
	v_mov_b32_e32 v90, v0
	v_mov_b32_e32 v91, v0
	v_mov_b32_e32 v92, v0
	v_mov_b32_e32 v93, v0
	v_mov_b32_e32 v94, v0
	v_mov_b32_e32 v95, v0
	v_mov_b32_e32 v104, v0
	v_mov_b32_e32 v105, v0
	v_mov_b32_e32 v106, v0
	v_mov_b32_e32 v107, v0
	v_mov_b32_e32 v108, v0
	v_mov_b32_e32 v109, v0
	v_mov_b32_e32 v110, v0
	v_mov_b32_e32 v111, v0
	v_mov_b32_e32 v120, v0
	v_mov_b32_e32 v121, v0
	v_mov_b32_e32 v122, v0
	v_mov_b32_e32 v123, v0
	v_mov_b32_e32 v124, v0
	v_mov_b32_e32 v125, v0
	v_mov_b32_e32 v126, v0
	v_mov_b32_e32 v127, v0
	s_andn2_b64 vcc, exec, s[4:5]
	s_cbranch_vccnz .LBB0_329
	s_branch .LBB0_330

; #define PG8_STAGE(bufoff, gbase, voff) do { _Pragma("unroll") for (int _i = 0; _i < 2; ++_i) \
;         __builtin_amdgcn_global_load_lds((const unsigned*)((const char*)(gbase) + (voff)[_i]), (LAS unsigned*)(lds + (bufoff) + ldsw + _i * 8192), 16, 0, 0); } while (0)
; #define PG8_LDA(dst, b, h) do { _Pragma("unroll") for (int m = 0; m < 4; ++m) _Pragma("unroll") for (int k = 0; k < 2; ++k) dst[m][k] = *(const LAS bf16x8*)(lds + PG8_SA(b, h) + aoff + m * 2048 + k * 1024); } while (0)
; #define PG8_LDB(dst, b, h) do { _Pragma("unroll") for (int n = 0; n < 2; ++n) _Pragma("unroll") for (int k = 0; k < 2; ++k) dst[n][k] = *(const LAS bf16x8*)(lds + PG8_SB(b, h) + boff + n * 2048 + k * 1024); } while (0)
; #define PG8_MMA(ai, bj, At, Bt) do { __builtin_amdgcn_s_setprio(1); _Pragma("unroll") for (int m = 0; m < 4; ++m) _Pragma("unroll") for (int n = 0; n < 2; ++n) _Pragma("unroll") for (int k = 0; k < 2; ++k) \
;         acc[ai][bj][m][n] = __builtin_amdgcn_mfma_f32_16x16x32_bf16(Bt[n][k], At[m][k], acc[ai][bj][m][n], 0, 0, 0); __builtin_amdgcn_s_setprio(0); } while (0)
; #define PG8_WAIT_V(n) asm volatile("s_waitcnt vmcnt(" #n ")" ::: "memory")
; #define PG8_WAIT_L(n) asm volatile("s_waitcnt lgkmcnt(" #n ")" ::: "memory")
; #define PG8_BAR __builtin_amdgcn_s_barrier()
; template <class Epi, bool ALIGN_EPI = false, bool SP2 = true>
; __device__ __forceinline__ void gemm_phase(LAS unsigned char* lds, const Gemm g, const StaticOrder& S, const Epi& E) {
;     ...
;         for (int t = 0; t < nt; t += 2) {
;             const bool last = (t == nt - 2);
;             const char* a1 = cA + (size_t)(t + 1) * kstep;
;             const char* a2 = last ? nA : cA + (size_t)(t + 2) * kstep; const char* b2 = last ? nB : cB + (size_t)(t + 2) * kstep;
;             const char* a3 = a2 + kstep; const char* b3 = b2 + kstep;
;             if constexpr (SP2) {
;             PG8_LDB(B0, 0, 0); PG8_LDB(B1, 0, 1); PG8_SCHED; PG8_LDA(At, 0, 0); PG8_STAGE(PG8_SA(1, 1), a1 + hstep, voffA);
;             PG8_WAIT_V(8); PG8_WAIT_L(0); PG8_BAR; PG8_MMA(0, 0, At, B0); PG8_MMA(0, 1, At, B1); PG8_BAR; PG8_SCHED;
;             PG8_LDA(At, 0, 1); PG8_STAGE(PG8_SB(0, 0), b2, voffB); PG8_STAGE(PG8_SB(0, 1), b2 + hstep, voffB); PG8_STAGE(PG8_SA(0, 0), a2, voffA);
;             PG8_WAIT_V(8); PG8_WAIT_L(0); PG8_BAR; PG8_MMA(1, 0, At, B0); PG8_MMA(1, 1, At, B1); PG8_BAR; PG8_SCHED;
.LBB0_441:
	ds_read_b128 v[128:131], v188
	ds_read_b128 v[132:135], v188 offset:1024
	ds_read_b128 v[136:139], v188 offset:2048
	ds_read_b128 v[140:143], v188 offset:3072
	ds_read_b128 v[144:147], v189
	ds_read_b128 v[148:151], v189 offset:1024
	ds_read_b128 v[152:155], v189 offset:2048
	ds_read_b128 v[156:159], v189 offset:3072
	s_add_u32 s56, s36, 0xfff80080
	s_addc_u32 s57, s37, -1
	s_cmp_eq_u32 s79, 28
	s_cselect_b32 s59, s25, s57
	s_cselect_b32 s58, s75, s56
	s_cselect_b32 s57, s23, s78
	s_cselect_b32 s56, s76, s77
	v_lshl_add_u64 v[212:213], s[36:37], 0, v[174:175]
	s_add_i32 m0, s31, 0xc000
	ds_read_b128 v[160:163], v190
	ds_read_b128 v[182:185], v190 offset:1024
	ds_read_b128 v[192:195], v190 offset:2048
	ds_read_b128 v[196:199], v190 offset:3072
	ds_read_b128 v[200:203], v190 offset:4096
	ds_read_b128 v[204:207], v190 offset:5120
	ds_read_b128 v[208:211], v190 offset:6144
	ds_read_b128 v[216:219], v190 offset:7168
	global_load_lds_dwordx4 v[212:213], off
	v_lshl_add_u64 v[212:213], s[36:37], 0, v[176:177]
	s_add_i32 m0, s31, 0xe000
	s_nop 0
	global_load_lds_dwordx4 v[212:213], off
	s_waitcnt vmcnt(8)
	s_waitcnt lgkmcnt(0)
	s_barrier
	s_setprio 1
	s_waitcnt lgkmcnt(0)
	v_mfma_f32_16x16x32_bf16 v[124:127], v[128:131], v[160:163], v[124:127]
	v_mfma_f32_16x16x32_bf16 v[120:123], v[136:139], v[160:163], v[120:123]
	v_mfma_f32_16x16x32_bf16 v[108:111], v[128:131], v[192:195], v[108:111]
	v_mfma_f32_16x16x32_bf16 v[104:107], v[136:139], v[192:195], v[104:107]
	v_mfma_f32_16x16x32_bf16 v[92:95], v[128:131], v[200:203], v[92:95]
	v_mfma_f32_16x16x32_bf16 v[88:91], v[136:139], v[200:203], v[88:91]
	v_mfma_f32_16x16x32_bf16 v[76:79], v[128:131], v[208:211], v[76:79]
	v_mfma_f32_16x16x32_bf16 v[72:75], v[136:139], v[208:211], v[72:75]
	v_mfma_f32_16x16x32_bf16 v[124:127], v[132:135], v[182:185], v[124:127]
	v_mfma_f32_16x16x32_bf16 v[120:123], v[140:143], v[182:185], v[120:123]
	v_mfma_f32_16x16x32_bf16 v[108:111], v[132:135], v[196:199], v[108:111]
	v_mfma_f32_16x16x32_bf16 v[104:107], v[140:143], v[196:199], v[104:107]
	v_mfma_f32_16x16x32_bf16 v[92:95], v[132:135], v[204:207], v[92:95]
	v_mfma_f32_16x16x32_bf16 v[88:91], v[140:143], v[204:207], v[88:91]
	v_mfma_f32_16x16x32_bf16 v[76:79], v[132:135], v[216:219], v[76:79]
	v_mfma_f32_16x16x32_bf16 v[72:75], v[140:143], v[216:219], v[72:75]
	s_setprio 0
	s_setprio 1
	v_mfma_f32_16x16x32_bf16 v[116:119], v[144:147], v[160:163], v[116:119]
	v_mfma_f32_16x16x32_bf16 v[112:115], v[152:155], v[160:163], v[112:115]
	v_mfma_f32_16x16x32_bf16 v[100:103], v[144:147], v[192:195], v[100:103]
	v_mfma_f32_16x16x32_bf16 v[96:99], v[152:155], v[192:195], v[96:99]
	v_mfma_f32_16x16x32_bf16 v[84:87], v[144:147], v[200:203], v[84:87]
	v_mfma_f32_16x16x32_bf16 v[80:83], v[152:155], v[200:203], v[80:83]
	v_mfma_f32_16x16x32_bf16 v[68:71], v[144:147], v[208:211], v[68:71]
	v_mfma_f32_16x16x32_bf16 v[64:67], v[152:155], v[208:211], v[64:67]
	v_mfma_f32_16x16x32_bf16 v[116:119], v[148:151], v[182:185], v[116:119]
	v_mfma_f32_16x16x32_bf16 v[112:115], v[156:159], v[182:185], v[112:115]
	v_mfma_f32_16x16x32_bf16 v[100:103], v[148:151], v[196:199], v[100:103]
	v_mfma_f32_16x16x32_bf16 v[96:99], v[156:159], v[196:199], v[96:99]
	v_mfma_f32_16x16x32_bf16 v[84:87], v[148:151], v[204:207], v[84:87]
	v_mfma_f32_16x16x32_bf16 v[80:83], v[156:159], v[204:207], v[80:83]
	v_mfma_f32_16x16x32_bf16 v[68:71], v[148:151], v[216:219], v[68:71]
	v_mfma_f32_16x16x32_bf16 v[64:67], v[156:159], v[216:219], v[64:67]
	s_setprio 0
	s_barrier
	s_add_i32 s80, s70, s60
	v_lshl_add_u64 v[212:213], s[56:57], 0, v[168:169]
	s_mov_b32 m0, s80
	ds_read_b128 v[160:163], v190 offset:16384
	ds_read_b128 v[182:185], v190 offset:17408
	ds_read_b128 v[192:195], v190 offset:18432
	ds_read_b128 v[196:199], v190 offset:19456
	ds_read_b128 v[200:203], v190 offset:20480
	ds_read_b128 v[204:207], v190 offset:21504
	ds_read_b128 v[208:211], v190 offset:22528
	ds_read_b128 v[216:219], v190 offset:23552
	global_load_lds_dwordx4 v[212:213], off
	s_add_i32 m0, s80, 0x2000
	s_add_u32 s80, s56, 0x80000
	v_lshl_add_u64 v[220:221], s[56:57], 0, v[172:173]
	s_addc_u32 s81, s57, 0
	s_add_i32 s82, s71, s60
	global_load_lds_dwordx4 v[220:221], off
	v_lshl_add_u64 v[222:223], s[80:81], 0, v[168:169]
	s_mov_b32 m0, s82
	v_lshl_add_u64 v[224:225], s[58:59], 0, v[170:171]
	global_load_lds_dwordx4 v[222:223], off
	v_lshl_add_u64 v[222:223], s[80:81], 0, v[172:173]
	s_add_i32 m0, s82, 0x2000
	s_nop 0
	global_load_lds_dwordx4 v[222:223], off
	v_lshl_add_u64 v[222:223], s[58:59], 0, v[166:167]
	s_mov_b32 m0, s31
	s_nop 0
	global_load_lds_dwordx4 v[222:223], off
	s_mov_b32 m0, s61
	s_nop 0
	global_load_lds_dwordx4 v[224:225], off
	s_waitcnt vmcnt(8)
	s_waitcnt lgkmcnt(0)
	s_barrier
; #define PG8_STAGE(bufoff, gbase, voff) do { _Pragma("unroll") for (int _i = 0; _i < 2; ++_i) \
;         __builtin_amdgcn_global_load_lds((const unsigned*)((const char*)(gbase) + (voff)[_i]), (LAS unsigned*)(lds + (bufoff) + ldsw + _i * 8192), 16, 0, 0); } while (0)
; #define PG8_LDA(dst, b, h) do { _Pragma("unroll") for (int m = 0; m < 4; ++m) _Pragma("unroll") for (int k = 0; k < 2; ++k) dst[m][k] = *(const LAS bf16x8*)(lds + PG8_SA(b, h) + aoff + m * 2048 + k * 1024); } while (0)
; #define PG8_LDB(dst, b, h) do { _Pragma("unroll") for (int n = 0; n < 2; ++n) _Pragma("unroll") for (int k = 0; k < 2; ++k) dst[n][k] = *(const LAS bf16x8*)(lds + PG8_SB(b, h) + boff + n * 2048 + k * 1024); } while (0)
; #define PG8_MMA(ai, bj, At, Bt) do { __builtin_amdgcn_s_setprio(1); _Pragma("unroll") for (int m = 0; m < 4; ++m) _Pragma("unroll") for (int n = 0; n < 2; ++n) _Pragma("unroll") for (int k = 0; k < 2; ++k) \
;         acc[ai][bj][m][n] = __builtin_amdgcn_mfma_f32_16x16x32_bf16(Bt[n][k], At[m][k], acc[ai][bj][m][n], 0, 0, 0); __builtin_amdgcn_s_setprio(0); } while (0)
; #define PG8_WAIT_V(n) asm volatile("s_waitcnt vmcnt(" #n ")" ::: "memory")
; #define PG8_WAIT_L(n) asm volatile("s_waitcnt lgkmcnt(" #n ")" ::: "memory")
; #define PG8_BAR __builtin_amdgcn_s_barrier()
; #define PG8_SCHED __builtin_amdgcn_sched_barrier(0)
; template <class Epi, bool ALIGN_EPI = false, bool SP2 = true>
; __device__ __forceinline__ void gemm_phase(LAS unsigned char* lds, const Gemm g, const StaticOrder& S, const Epi& E) {
;     ...
;             PG8_WAIT_V(8); PG8_WAIT_L(0); PG8_BAR; PG8_MMA(1, 0, At, B0); PG8_MMA(1, 1, At, B1); PG8_BAR; PG8_SCHED;
;             PG8_LDB(B0, 1, 0); PG8_LDB(B1, 1, 1); PG8_SCHED; PG8_LDA(At, 1, 0); PG8_STAGE(PG8_SA(0, 1), a2 + hstep, voffA);
;             PG8_WAIT_V(8); PG8_WAIT_L(0); PG8_BAR; PG8_MMA(0, 0, At, B0); PG8_MMA(0, 1, At, B1); PG8_BAR; PG8_SCHED;
	s_setprio 1
	s_waitcnt lgkmcnt(0)
	v_mfma_f32_16x16x32_bf16 v[60:63], v[128:131], v[160:163], v[60:63]
	v_mfma_f32_16x16x32_bf16 v[56:59], v[136:139], v[160:163], v[56:59]
	v_mfma_f32_16x16x32_bf16 v[44:47], v[128:131], v[192:195], v[44:47]
	v_mfma_f32_16x16x32_bf16 v[40:43], v[136:139], v[192:195], v[40:43]
	v_mfma_f32_16x16x32_bf16 v[28:31], v[128:131], v[200:203], v[28:31]
	v_mfma_f32_16x16x32_bf16 v[24:27], v[136:139], v[200:203], v[24:27]
	v_mfma_f32_16x16x32_bf16 v[12:15], v[128:131], v[208:211], v[12:15]
	v_mfma_f32_16x16x32_bf16 v[8:11], v[136:139], v[208:211], v[8:11]
	v_mfma_f32_16x16x32_bf16 v[60:63], v[132:135], v[182:185], v[60:63]
	v_mfma_f32_16x16x32_bf16 v[56:59], v[140:143], v[182:185], v[56:59]
	v_mfma_f32_16x16x32_bf16 v[44:47], v[132:135], v[196:199], v[44:47]
	v_mfma_f32_16x16x32_bf16 v[40:43], v[140:143], v[196:199], v[40:43]
	v_mfma_f32_16x16x32_bf16 v[28:31], v[132:135], v[204:207], v[28:31]
	v_mfma_f32_16x16x32_bf16 v[24:27], v[140:143], v[204:207], v[24:27]
	v_mfma_f32_16x16x32_bf16 v[12:15], v[132:135], v[216:219], v[12:15]
	v_mfma_f32_16x16x32_bf16 v[8:11], v[140:143], v[216:219], v[8:11]
	s_setprio 0
	s_setprio 1
	v_mfma_f32_16x16x32_bf16 v[52:55], v[144:147], v[160:163], v[52:55]
	v_mfma_f32_16x16x32_bf16 v[48:51], v[152:155], v[160:163], v[48:51]
	v_mfma_f32_16x16x32_bf16 v[36:39], v[144:147], v[192:195], v[36:39]
	v_mfma_f32_16x16x32_bf16 v[32:35], v[152:155], v[192:195], v[32:35]
	v_mfma_f32_16x16x32_bf16 v[20:23], v[144:147], v[200:203], v[20:23]
	v_mfma_f32_16x16x32_bf16 v[16:19], v[152:155], v[200:203], v[16:19]
	v_mfma_f32_16x16x32_bf16 v[4:7], v[144:147], v[208:211], v[4:7]
	v_mfma_f32_16x16x32_bf16 v[0:3], v[152:155], v[208:211], v[0:3]
	v_mfma_f32_16x16x32_bf16 v[52:55], v[148:151], v[182:185], v[52:55]
	v_mfma_f32_16x16x32_bf16 v[48:51], v[156:159], v[182:185], v[48:51]
	v_mfma_f32_16x16x32_bf16 v[36:39], v[148:151], v[196:199], v[36:39]
	v_mfma_f32_16x16x32_bf16 v[32:35], v[156:159], v[196:199], v[32:35]
	v_mfma_f32_16x16x32_bf16 v[20:23], v[148:151], v[204:207], v[20:23]
	v_mfma_f32_16x16x32_bf16 v[16:19], v[156:159], v[204:207], v[16:19]
	v_mfma_f32_16x16x32_bf16 v[4:7], v[148:151], v[216:219], v[4:7]
	v_mfma_f32_16x16x32_bf16 v[0:3], v[156:159], v[216:219], v[0:3]
	s_setprio 0
	s_barrier
	s_add_i32 s80, 0, 0x18000
	s_add_i32 s81, 0, 0x1c000
	v_add_u32_e32 v140, s80, v186
	v_add_u32_e32 v156, s81, v186
	ds_read_b128 v[128:131], v140
	ds_read_b128 v[132:135], v140 offset:1024
	ds_read_b128 v[136:139], v140 offset:2048
	ds_read_b128 v[140:143], v140 offset:3072
	ds_read_b128 v[144:147], v156
	ds_read_b128 v[148:151], v156 offset:1024
	ds_read_b128 v[152:155], v156 offset:2048
	ds_read_b128 v[156:159], v156 offset:3072
	s_add_u32 s58, s58, 0x80000
	s_addc_u32 s59, s59, 0
	s_mov_b32 m0, s62
	v_lshl_add_u64 v[226:227], s[58:59], 0, v[166:167]
	ds_read_b128 v[160:163], v190 offset:32768
	ds_read_b128 v[182:185], v190 offset:33792
	ds_read_b128 v[192:195], v190 offset:34816
	ds_read_b128 v[196:199], v190 offset:35840
	ds_read_b128 v[200:203], v190 offset:36864
	ds_read_b128 v[204:207], v190 offset:37888
	ds_read_b128 v[208:211], v190 offset:38912
	ds_read_b128 v[216:219], v190 offset:39936
	global_load_lds_dwordx4 v[226:227], off
	v_lshl_add_u64 v[226:227], s[58:59], 0, v[170:171]
	s_mov_b32 m0, s63
	s_nop 0
	global_load_lds_dwordx4 v[226:227], off
	s_waitcnt vmcnt(8)
	s_waitcnt lgkmcnt(0)
	s_barrier
	s_setprio 1
	s_waitcnt lgkmcnt(0)
	v_mfma_f32_16x16x32_bf16 v[124:127], v[128:131], v[160:163], v[124:127]
	v_mfma_f32_16x16x32_bf16 v[120:123], v[136:139], v[160:163], v[120:123]
	v_mfma_f32_16x16x32_bf16 v[108:111], v[128:131], v[192:195], v[108:111]
	v_mfma_f32_16x16x32_bf16 v[104:107], v[136:139], v[192:195], v[104:107]
	v_mfma_f32_16x16x32_bf16 v[92:95], v[128:131], v[200:203], v[92:95]
	v_mfma_f32_16x16x32_bf16 v[88:91], v[136:139], v[200:203], v[88:91]
	v_mfma_f32_16x16x32_bf16 v[76:79], v[128:131], v[208:211], v[76:79]
	v_mfma_f32_16x16x32_bf16 v[72:75], v[136:139], v[208:211], v[72:75]
	v_mfma_f32_16x16x32_bf16 v[124:127], v[132:135], v[182:185], v[124:127]
	v_mfma_f32_16x16x32_bf16 v[120:123], v[140:143], v[182:185], v[120:123]
	v_mfma_f32_16x16x32_bf16 v[108:111], v[132:135], v[196:199], v[108:111]
	v_mfma_f32_16x16x32_bf16 v[104:107], v[140:143], v[196:199], v[104:107]
	v_mfma_f32_16x16x32_bf16 v[92:95], v[132:135], v[204:207], v[92:95]
	v_mfma_f32_16x16x32_bf16 v[88:91], v[140:143], v[204:207], v[88:91]
	v_mfma_f32_16x16x32_bf16 v[76:79], v[132:135], v[216:219], v[76:79]
	v_mfma_f32_16x16x32_bf16 v[72:75], v[140:143], v[216:219], v[72:75]
	s_setprio 0
	s_setprio 1
	v_mfma_f32_16x16x32_bf16 v[116:119], v[144:147], v[160:163], v[116:119]
	v_mfma_f32_16x16x32_bf16 v[112:115], v[152:155], v[160:163], v[112:115]
	v_mfma_f32_16x16x32_bf16 v[100:103], v[144:147], v[192:195], v[100:103]
	v_mfma_f32_16x16x32_bf16 v[96:99], v[152:155], v[192:195], v[96:99]
	v_mfma_f32_16x16x32_bf16 v[84:87], v[144:147], v[200:203], v[84:87]
	v_mfma_f32_16x16x32_bf16 v[80:83], v[152:155], v[200:203], v[80:83]
	v_mfma_f32_16x16x32_bf16 v[68:71], v[144:147], v[208:211], v[68:71]
	v_mfma_f32_16x16x32_bf16 v[64:67], v[152:155], v[208:211], v[64:67]
	v_mfma_f32_16x16x32_bf16 v[116:119], v[148:151], v[182:185], v[116:119]
	v_mfma_f32_16x16x32_bf16 v[112:115], v[156:159], v[182:185], v[112:115]
	v_mfma_f32_16x16x32_bf16 v[100:103], v[148:151], v[196:199], v[100:103]
	v_mfma_f32_16x16x32_bf16 v[96:99], v[156:159], v[196:199], v[96:99]
	v_mfma_f32_16x16x32_bf16 v[84:87], v[148:151], v[204:207], v[84:87]
	v_mfma_f32_16x16x32_bf16 v[80:83], v[156:159], v[204:207], v[80:83]
	v_mfma_f32_16x16x32_bf16 v[68:71], v[148:151], v[216:219], v[68:71]
	v_mfma_f32_16x16x32_bf16 v[64:67], v[156:159], v[216:219], v[64:67]
	s_setprio 0
	s_barrier
; #define PG8_STAGE(bufoff, gbase, voff) do { _Pragma("unroll") for (int _i = 0; _i < 2; ++_i) \
;         __builtin_amdgcn_global_load_lds((const unsigned*)((const char*)(gbase) + (voff)[_i]), (LAS unsigned*)(lds + (bufoff) + ldsw + _i * 8192), 16, 0, 0); } while (0)
; #define PG8_LDA(dst, b, h) do { _Pragma("unroll") for (int m = 0; m < 4; ++m) _Pragma("unroll") for (int k = 0; k < 2; ++k) dst[m][k] = *(const LAS bf16x8*)(lds + PG8_SA(b, h) + aoff + m * 2048 + k * 1024); } while (0)
; #define PG8_MMA(ai, bj, At, Bt) do { __builtin_amdgcn_s_setprio(1); _Pragma("unroll") for (int m = 0; m < 4; ++m) _Pragma("unroll") for (int n = 0; n < 2; ++n) _Pragma("unroll") for (int k = 0; k < 2; ++k) \
;         acc[ai][bj][m][n] = __builtin_amdgcn_mfma_f32_16x16x32_bf16(Bt[n][k], At[m][k], acc[ai][bj][m][n], 0, 0, 0); __builtin_amdgcn_s_setprio(0); } while (0)
; #define PG8_WAIT_V(n) asm volatile("s_waitcnt vmcnt(" #n ")" ::: "memory")
; #define PG8_WAIT_L(n) asm volatile("s_waitcnt lgkmcnt(" #n ")" ::: "memory")
; #define PG8_BAR __builtin_amdgcn_s_barrier()
; #define PG8_SCHED __builtin_amdgcn_sched_barrier(0)
; template <class Epi, bool ALIGN_EPI = false, bool SP2 = true>
; __device__ __forceinline__ void gemm_phase(LAS unsigned char* lds, const Gemm g, const StaticOrder& S, const Epi& E) {
;     ...
;             PG8_LDA(At, 1, 1); PG8_STAGE(PG8_SB(1, 0), b3, voffB); PG8_STAGE(PG8_SB(1, 1), b3 + hstep, voffB); PG8_STAGE(PG8_SA(1, 0), a3, voffA);
;             PG8_WAIT_V(8); PG8_WAIT_L(0); PG8_BAR; PG8_MMA(1, 0, At, B0); PG8_MMA(1, 1, At, B1); PG8_BAR; PG8_SCHED;
;     ...
;         if constexpr (ALIGN_EPI) { if (wr == 0) PG8_BAR; }
	s_add_i32 s58, s80, s60
	v_lshl_add_u64 v[212:213], v[212:213], 0, s[16:17]
	s_mov_b32 m0, s58
	ds_read_b128 v[160:163], v190 offset:49152
	ds_read_b128 v[182:185], v190 offset:50176
	ds_read_b128 v[192:195], v190 offset:51200
	ds_read_b128 v[196:199], v190 offset:52224
	ds_read_b128 v[200:203], v190 offset:53248
	ds_read_b128 v[204:207], v190 offset:54272
	ds_read_b128 v[208:211], v190 offset:55296
	ds_read_b128 v[216:219], v190 offset:56320
	global_load_lds_dwordx4 v[212:213], off
	s_add_i32 m0, s58, 0x2000
	s_add_u32 s56, s56, 0x80080
	v_lshl_add_u64 v[212:213], v[220:221], 0, s[16:17]
	s_addc_u32 s57, s57, 0
	s_add_i32 s58, s81, s60
	global_load_lds_dwordx4 v[212:213], off
	v_lshl_add_u64 v[212:213], s[56:57], 0, v[168:169]
	s_mov_b32 m0, s58
	s_nop 0
	global_load_lds_dwordx4 v[212:213], off
	v_lshl_add_u64 v[212:213], s[56:57], 0, v[172:173]
	s_add_i32 m0, s58, 0x2000
	s_nop 0
	global_load_lds_dwordx4 v[212:213], off
	v_lshl_add_u64 v[212:213], v[222:223], 0, s[16:17]
	s_mov_b32 m0, s66
	s_nop 0
	global_load_lds_dwordx4 v[212:213], off
	v_lshl_add_u64 v[212:213], v[224:225], 0, s[16:17]
	s_mov_b32 m0, s67
	s_nop 0
	global_load_lds_dwordx4 v[212:213], off
	s_waitcnt vmcnt(8)
	s_waitcnt lgkmcnt(0)
	s_barrier
	s_setprio 1
	s_waitcnt lgkmcnt(0)
	v_mfma_f32_16x16x32_bf16 v[60:63], v[128:131], v[160:163], v[60:63]
	v_mfma_f32_16x16x32_bf16 v[56:59], v[136:139], v[160:163], v[56:59]
	v_mfma_f32_16x16x32_bf16 v[44:47], v[128:131], v[192:195], v[44:47]
	v_mfma_f32_16x16x32_bf16 v[40:43], v[136:139], v[192:195], v[40:43]
	v_mfma_f32_16x16x32_bf16 v[28:31], v[128:131], v[200:203], v[28:31]
	v_mfma_f32_16x16x32_bf16 v[24:27], v[136:139], v[200:203], v[24:27]
	v_mfma_f32_16x16x32_bf16 v[12:15], v[128:131], v[208:211], v[12:15]
	v_mfma_f32_16x16x32_bf16 v[8:11], v[136:139], v[208:211], v[8:11]
	v_mfma_f32_16x16x32_bf16 v[60:63], v[132:135], v[182:185], v[60:63]
	v_mfma_f32_16x16x32_bf16 v[56:59], v[140:143], v[182:185], v[56:59]
	v_mfma_f32_16x16x32_bf16 v[44:47], v[132:135], v[196:199], v[44:47]
	v_mfma_f32_16x16x32_bf16 v[40:43], v[140:143], v[196:199], v[40:43]
	v_mfma_f32_16x16x32_bf16 v[28:31], v[132:135], v[204:207], v[28:31]
	v_mfma_f32_16x16x32_bf16 v[24:27], v[140:143], v[204:207], v[24:27]
	v_mfma_f32_16x16x32_bf16 v[12:15], v[132:135], v[216:219], v[12:15]
	v_mfma_f32_16x16x32_bf16 v[8:11], v[140:143], v[216:219], v[8:11]
	s_setprio 0
	s_setprio 1
	v_mfma_f32_16x16x32_bf16 v[52:55], v[144:147], v[160:163], v[52:55]
	v_mfma_f32_16x16x32_bf16 v[48:51], v[152:155], v[160:163], v[48:51]
	v_mfma_f32_16x16x32_bf16 v[36:39], v[144:147], v[192:195], v[36:39]
	v_mfma_f32_16x16x32_bf16 v[32:35], v[152:155], v[192:195], v[32:35]
	v_mfma_f32_16x16x32_bf16 v[20:23], v[144:147], v[200:203], v[20:23]
	v_mfma_f32_16x16x32_bf16 v[16:19], v[152:155], v[200:203], v[16:19]
	v_mfma_f32_16x16x32_bf16 v[4:7], v[144:147], v[208:211], v[4:7]
	v_mfma_f32_16x16x32_bf16 v[0:3], v[152:155], v[208:211], v[0:3]
	v_mfma_f32_16x16x32_bf16 v[52:55], v[148:151], v[182:185], v[52:55]
	v_mfma_f32_16x16x32_bf16 v[48:51], v[156:159], v[182:185], v[48:51]
	v_mfma_f32_16x16x32_bf16 v[36:39], v[148:151], v[196:199], v[36:39]
	v_mfma_f32_16x16x32_bf16 v[32:35], v[156:159], v[196:199], v[32:35]
	v_mfma_f32_16x16x32_bf16 v[20:23], v[148:151], v[204:207], v[20:23]
	v_mfma_f32_16x16x32_bf16 v[16:19], v[156:159], v[204:207], v[16:19]
	v_mfma_f32_16x16x32_bf16 v[4:7], v[148:151], v[216:219], v[4:7]
	v_mfma_f32_16x16x32_bf16 v[0:3], v[156:159], v[216:219], v[0:3]
	s_add_i32 s79, s79, 2
	s_add_u32 s36, s36, 0x100
	s_addc_u32 s37, s37, 0
	s_add_u32 s77, s77, 0x100
	s_addc_u32 s78, s78, 0
	s_cmp_gt_u32 s79, 29
	s_setprio 0
	s_barrier
	s_cbranch_scc0 .LBB0_441
	s_and_b64 vcc, exec, s[18:19]
	s_cbranch_vccz .LBB0_444
	s_barrier

; #define PG8_STAGE(bufoff, gbase, voff) do { _Pragma("unroll") for (int _i = 0; _i < 2; ++_i) \
;         __builtin_amdgcn_global_load_lds((const unsigned*)((const char*)(gbase) + (voff)[_i]), (LAS unsigned*)(lds + (bufoff) + ldsw + _i * 8192), 16, 0, 0); } while (0)
; #define PG8_LDA(dst, b, h) do { _Pragma("unroll") for (int m = 0; m < 4; ++m) _Pragma("unroll") for (int k = 0; k < 2; ++k) dst[m][k] = *(const LAS bf16x8*)(lds + PG8_SA(b, h) + aoff + m * 2048 + k * 1024); } while (0)
; #define PG8_LDB(dst, b, h) do { _Pragma("unroll") for (int n = 0; n < 2; ++n) _Pragma("unroll") for (int k = 0; k < 2; ++k) dst[n][k] = *(const LAS bf16x8*)(lds + PG8_SB(b, h) + boff + n * 2048 + k * 1024); } while (0)
; #define PG8_MMA(ai, bj, At, Bt) do { __builtin_amdgcn_s_setprio(1); _Pragma("unroll") for (int m = 0; m < 4; ++m) _Pragma("unroll") for (int n = 0; n < 2; ++n) _Pragma("unroll") for (int k = 0; k < 2; ++k) \
;         acc[ai][bj][m][n] = __builtin_amdgcn_mfma_f32_16x16x32_bf16(Bt[n][k], At[m][k], acc[ai][bj][m][n], 0, 0, 0); __builtin_amdgcn_s_setprio(0); } while (0)
; #define PG8_WAIT_V(n) asm volatile("s_waitcnt vmcnt(" #n ")" ::: "memory")
; #define PG8_WAIT_L(n) asm volatile("s_waitcnt lgkmcnt(" #n ")" ::: "memory")
; #define PG8_BAR __builtin_amdgcn_s_barrier()
; template <class Epi, bool ALIGN_EPI = false, bool SP2 = true>
; __device__ __forceinline__ void gemm_phase(LAS unsigned char* lds, const Gemm g, const StaticOrder& S, const Epi& E) {
;     ...
;         for (int t = 0; t < nt; t += 2) {
;             const bool last = (t == nt - 2);
;             const char* a1 = cA + (size_t)(t + 1) * kstep;
;             const char* a2 = last ? nA : cA + (size_t)(t + 2) * kstep; const char* b2 = last ? nB : cB + (size_t)(t + 2) * kstep;
;             const char* a3 = a2 + kstep; const char* b3 = b2 + kstep;
;             if constexpr (SP2) {
;             PG8_LDB(B0, 0, 0); PG8_LDB(B1, 0, 1); PG8_SCHED; PG8_LDA(At, 0, 0); PG8_STAGE(PG8_SA(1, 1), a1 + hstep, voffA);
;             PG8_WAIT_V(8); PG8_WAIT_L(0); PG8_BAR; PG8_MMA(0, 0, At, B0); PG8_MMA(0, 1, At, B1); PG8_BAR; PG8_SCHED;
;             PG8_LDA(At, 0, 1); PG8_STAGE(PG8_SB(0, 0), b2, voffB); PG8_STAGE(PG8_SB(0, 1), b2 + hstep, voffB); PG8_STAGE(PG8_SA(0, 0), a2, voffA);
;             PG8_WAIT_V(8); PG8_WAIT_L(0); PG8_BAR; PG8_MMA(1, 0, At, B0); PG8_MMA(1, 1, At, B1); PG8_BAR; PG8_SCHED;
.LBB0_518:
	ds_read_b128 v[148:151], v166
	s_waitcnt lgkmcnt(0)
	ds_read_b128 v[152:155], v166 offset:1024
	ds_read_b128 v[156:159], v166 offset:2048
	ds_read_b128 v[170:173], v166 offset:3072
	ds_read_b128 v[174:177], v167
	ds_read_b128 v[178:181], v167 offset:1024
	ds_read_b128 v[182:185], v167 offset:2048
	ds_read_b128 v[186:189], v167 offset:3072
	s_add_u32 s60, s10, 0xfff80080
	s_addc_u32 s61, s11, -1
	s_cmp_eq_u32 s82, 28
	s_cselect_b32 s63, s9, s61
	s_cselect_b32 s62, s37, s60
	s_cselect_b32 s61, s31, s81
	s_cselect_b32 s60, s79, s80
	v_lshl_add_u64 v[160:161], s[10:11], 0, v[138:139]
	s_add_i32 m0, s65, 0xc000
	ds_read_b128 v[190:193], v168
	ds_read_b128 v[194:197], v168 offset:1024
	ds_read_b128 v[198:201], v168 offset:2048
	ds_read_b128 v[202:205], v168 offset:3072
	ds_read_b128 v[206:209], v168 offset:4096
	ds_read_b128 v[210:213], v168 offset:5120
	ds_read_b128 v[216:219], v168 offset:6144
	ds_read_b128 v[220:223], v168 offset:7168
	global_load_lds_dwordx4 v[160:161], off
	v_lshl_add_u64 v[160:161], s[10:11], 0, v[140:141]
	s_add_i32 m0, s65, 0xe000
	s_nop 0
	global_load_lds_dwordx4 v[160:161], off
	s_waitcnt vmcnt(8)
	s_waitcnt lgkmcnt(0)
	s_barrier
	s_setprio 1
	s_waitcnt lgkmcnt(0)
	v_mfma_f32_16x16x32_bf16 v[124:127], v[148:151], v[190:193], v[124:127]
	v_mfma_f32_16x16x32_bf16 v[92:95], v[156:159], v[190:193], v[92:95]
	v_mfma_f32_16x16x32_bf16 v[120:123], v[148:151], v[198:201], v[120:123]
	v_mfma_f32_16x16x32_bf16 v[88:91], v[156:159], v[198:201], v[88:91]
	v_mfma_f32_16x16x32_bf16 v[116:119], v[148:151], v[206:209], v[116:119]
	v_mfma_f32_16x16x32_bf16 v[84:87], v[156:159], v[206:209], v[84:87]
	v_mfma_f32_16x16x32_bf16 v[112:115], v[148:151], v[216:219], v[112:115]
	v_mfma_f32_16x16x32_bf16 v[80:83], v[156:159], v[216:219], v[80:83]
	v_mfma_f32_16x16x32_bf16 v[124:127], v[152:155], v[194:197], v[124:127]
	v_mfma_f32_16x16x32_bf16 v[92:95], v[170:173], v[194:197], v[92:95]
	v_mfma_f32_16x16x32_bf16 v[120:123], v[152:155], v[202:205], v[120:123]
	v_mfma_f32_16x16x32_bf16 v[88:91], v[170:173], v[202:205], v[88:91]
	v_mfma_f32_16x16x32_bf16 v[116:119], v[152:155], v[210:213], v[116:119]
	v_mfma_f32_16x16x32_bf16 v[84:87], v[170:173], v[210:213], v[84:87]
	v_mfma_f32_16x16x32_bf16 v[112:115], v[152:155], v[220:223], v[112:115]
	v_mfma_f32_16x16x32_bf16 v[80:83], v[170:173], v[220:223], v[80:83]
	s_setprio 0
	s_setprio 1
	v_mfma_f32_16x16x32_bf16 v[60:63], v[174:177], v[190:193], v[60:63]
	v_mfma_f32_16x16x32_bf16 v[28:31], v[182:185], v[190:193], v[28:31]
	v_mfma_f32_16x16x32_bf16 v[56:59], v[174:177], v[198:201], v[56:59]
	v_mfma_f32_16x16x32_bf16 v[24:27], v[182:185], v[198:201], v[24:27]
	v_mfma_f32_16x16x32_bf16 v[52:55], v[174:177], v[206:209], v[52:55]
	v_mfma_f32_16x16x32_bf16 v[20:23], v[182:185], v[206:209], v[20:23]
	v_mfma_f32_16x16x32_bf16 v[48:51], v[174:177], v[216:219], v[48:51]
	v_mfma_f32_16x16x32_bf16 v[16:19], v[182:185], v[216:219], v[16:19]
	v_mfma_f32_16x16x32_bf16 v[60:63], v[178:181], v[194:197], v[60:63]
	v_mfma_f32_16x16x32_bf16 v[28:31], v[186:189], v[194:197], v[28:31]
	v_mfma_f32_16x16x32_bf16 v[56:59], v[178:181], v[202:205], v[56:59]
	v_mfma_f32_16x16x32_bf16 v[24:27], v[186:189], v[202:205], v[24:27]
	v_mfma_f32_16x16x32_bf16 v[52:55], v[178:181], v[210:213], v[52:55]
	v_mfma_f32_16x16x32_bf16 v[20:23], v[186:189], v[210:213], v[20:23]
	v_mfma_f32_16x16x32_bf16 v[48:51], v[178:181], v[220:223], v[48:51]
	v_mfma_f32_16x16x32_bf16 v[16:19], v[186:189], v[220:223], v[16:19]
	s_setprio 0
	s_barrier
	s_add_i32 s83, s75, s64
	v_lshl_add_u64 v[160:161], s[60:61], 0, v[130:131]
	s_mov_b32 m0, s83
	ds_read_b128 v[190:193], v168 offset:16384
	ds_read_b128 v[194:197], v168 offset:17408
	ds_read_b128 v[198:201], v168 offset:18432
	ds_read_b128 v[202:205], v168 offset:19456
	ds_read_b128 v[206:209], v168 offset:20480
	ds_read_b128 v[210:213], v168 offset:21504
	ds_read_b128 v[216:219], v168 offset:22528
	ds_read_b128 v[220:223], v168 offset:23552
	global_load_lds_dwordx4 v[160:161], off
	s_add_i32 m0, s83, 0x2000
	s_add_u32 s84, s60, 0x80000
	v_lshl_add_u64 v[224:225], s[60:61], 0, v[134:135]
	s_addc_u32 s85, s61, 0
	s_add_i32 s83, s77, s64
	global_load_lds_dwordx4 v[224:225], off
	v_lshl_add_u64 v[226:227], s[84:85], 0, v[130:131]
	s_mov_b32 m0, s83
	v_lshl_add_u64 v[228:229], s[62:63], 0, v[132:133]
	global_load_lds_dwordx4 v[226:227], off
	v_lshl_add_u64 v[226:227], s[84:85], 0, v[134:135]
	s_add_i32 m0, s83, 0x2000
	s_nop 0
	global_load_lds_dwordx4 v[226:227], off
	v_lshl_add_u64 v[226:227], s[62:63], 0, v[128:129]
	s_mov_b32 m0, s65
	s_nop 0
	global_load_lds_dwordx4 v[226:227], off
	s_mov_b32 m0, s66
	s_nop 0
	global_load_lds_dwordx4 v[228:229], off
	s_waitcnt vmcnt(8)
	s_waitcnt lgkmcnt(0)
	s_barrier
; #define PG8_STAGE(bufoff, gbase, voff) do { _Pragma("unroll") for (int _i = 0; _i < 2; ++_i) \
;         __builtin_amdgcn_global_load_lds((const unsigned*)((const char*)(gbase) + (voff)[_i]), (LAS unsigned*)(lds + (bufoff) + ldsw + _i * 8192), 16, 0, 0); } while (0)
; #define PG8_LDA(dst, b, h) do { _Pragma("unroll") for (int m = 0; m < 4; ++m) _Pragma("unroll") for (int k = 0; k < 2; ++k) dst[m][k] = *(const LAS bf16x8*)(lds + PG8_SA(b, h) + aoff + m * 2048 + k * 1024); } while (0)
; #define PG8_LDB(dst, b, h) do { _Pragma("unroll") for (int n = 0; n < 2; ++n) _Pragma("unroll") for (int k = 0; k < 2; ++k) dst[n][k] = *(const LAS bf16x8*)(lds + PG8_SB(b, h) + boff + n * 2048 + k * 1024); } while (0)
; #define PG8_MMA(ai, bj, At, Bt) do { __builtin_amdgcn_s_setprio(1); _Pragma("unroll") for (int m = 0; m < 4; ++m) _Pragma("unroll") for (int n = 0; n < 2; ++n) _Pragma("unroll") for (int k = 0; k < 2; ++k) \
;         acc[ai][bj][m][n] = __builtin_amdgcn_mfma_f32_16x16x32_bf16(Bt[n][k], At[m][k], acc[ai][bj][m][n], 0, 0, 0); __builtin_amdgcn_s_setprio(0); } while (0)
; #define PG8_WAIT_V(n) asm volatile("s_waitcnt vmcnt(" #n ")" ::: "memory")
; #define PG8_WAIT_L(n) asm volatile("s_waitcnt lgkmcnt(" #n ")" ::: "memory")
; #define PG8_BAR __builtin_amdgcn_s_barrier()
; #define PG8_SCHED __builtin_amdgcn_sched_barrier(0)
; template <class Epi, bool ALIGN_EPI = false, bool SP2 = true>
; __device__ __forceinline__ void gemm_phase(LAS unsigned char* lds, const Gemm g, const StaticOrder& S, const Epi& E) {
;     ...
;             PG8_WAIT_V(8); PG8_WAIT_L(0); PG8_BAR; PG8_MMA(1, 0, At, B0); PG8_MMA(1, 1, At, B1); PG8_BAR; PG8_SCHED;
;             PG8_LDB(B0, 1, 0); PG8_LDB(B1, 1, 1); PG8_SCHED; PG8_LDA(At, 1, 0); PG8_STAGE(PG8_SA(0, 1), a2 + hstep, voffA);
;             PG8_WAIT_V(8); PG8_WAIT_L(0); PG8_BAR; PG8_MMA(0, 0, At, B0); PG8_MMA(0, 1, At, B1); PG8_BAR; PG8_SCHED;
	s_setprio 1
	s_waitcnt lgkmcnt(0)
	v_mfma_f32_16x16x32_bf16 v[108:111], v[148:151], v[190:193], v[108:111]
	v_mfma_f32_16x16x32_bf16 v[76:79], v[156:159], v[190:193], v[76:79]
	v_mfma_f32_16x16x32_bf16 v[104:107], v[148:151], v[198:201], v[104:107]
	v_mfma_f32_16x16x32_bf16 v[72:75], v[156:159], v[198:201], v[72:75]
	v_mfma_f32_16x16x32_bf16 v[100:103], v[148:151], v[206:209], v[100:103]
	v_mfma_f32_16x16x32_bf16 v[68:71], v[156:159], v[206:209], v[68:71]
	v_mfma_f32_16x16x32_bf16 v[96:99], v[148:151], v[216:219], v[96:99]
	v_mfma_f32_16x16x32_bf16 v[64:67], v[156:159], v[216:219], v[64:67]
	v_mfma_f32_16x16x32_bf16 v[108:111], v[152:155], v[194:197], v[108:111]
	v_mfma_f32_16x16x32_bf16 v[76:79], v[170:173], v[194:197], v[76:79]
	v_mfma_f32_16x16x32_bf16 v[104:107], v[152:155], v[202:205], v[104:107]
	v_mfma_f32_16x16x32_bf16 v[72:75], v[170:173], v[202:205], v[72:75]
	v_mfma_f32_16x16x32_bf16 v[100:103], v[152:155], v[210:213], v[100:103]
	v_mfma_f32_16x16x32_bf16 v[68:71], v[170:173], v[210:213], v[68:71]
	v_mfma_f32_16x16x32_bf16 v[96:99], v[152:155], v[220:223], v[96:99]
	v_mfma_f32_16x16x32_bf16 v[64:67], v[170:173], v[220:223], v[64:67]
	s_setprio 0
	s_setprio 1
	v_mfma_f32_16x16x32_bf16 v[44:47], v[174:177], v[190:193], v[44:47]
	v_mfma_f32_16x16x32_bf16 v[12:15], v[182:185], v[190:193], v[12:15]
	v_mfma_f32_16x16x32_bf16 v[40:43], v[174:177], v[198:201], v[40:43]
	v_mfma_f32_16x16x32_bf16 v[8:11], v[182:185], v[198:201], v[8:11]
	v_mfma_f32_16x16x32_bf16 v[36:39], v[174:177], v[206:209], v[36:39]
	v_mfma_f32_16x16x32_bf16 v[4:7], v[182:185], v[206:209], v[4:7]
	v_mfma_f32_16x16x32_bf16 v[32:35], v[174:177], v[216:219], v[32:35]
	v_mfma_f32_16x16x32_bf16 v[0:3], v[182:185], v[216:219], v[0:3]
	v_mfma_f32_16x16x32_bf16 v[44:47], v[178:181], v[194:197], v[44:47]
	v_mfma_f32_16x16x32_bf16 v[12:15], v[186:189], v[194:197], v[12:15]
	v_mfma_f32_16x16x32_bf16 v[40:43], v[178:181], v[202:205], v[40:43]
	v_mfma_f32_16x16x32_bf16 v[8:11], v[186:189], v[202:205], v[8:11]
	v_mfma_f32_16x16x32_bf16 v[36:39], v[178:181], v[210:213], v[36:39]
	v_mfma_f32_16x16x32_bf16 v[4:7], v[186:189], v[210:213], v[4:7]
	v_mfma_f32_16x16x32_bf16 v[32:35], v[178:181], v[220:223], v[32:35]
	v_mfma_f32_16x16x32_bf16 v[0:3], v[186:189], v[220:223], v[0:3]
	s_setprio 0
	s_barrier
	s_add_i32 s83, 0, 0x18000
	v_add_u32_e32 v136, s83, v163
	s_add_i32 s84, 0, 0x1c000
	ds_read_b128 v[148:151], v136
	ds_read_b128 v[152:155], v136 offset:1024
	ds_read_b128 v[156:159], v136 offset:2048
	ds_read_b128 v[170:173], v136 offset:3072
	v_add_u32_e32 v136, s84, v163
	ds_read_b128 v[174:177], v136
	ds_read_b128 v[178:181], v136 offset:1024
	ds_read_b128 v[182:185], v136 offset:2048
	ds_read_b128 v[186:189], v136 offset:3072
	s_add_u32 s62, s62, 0x80000
	s_addc_u32 s63, s63, 0
	s_mov_b32 m0, s67
	v_lshl_add_u64 v[230:231], s[62:63], 0, v[128:129]
	ds_read_b128 v[190:193], v168 offset:32768
	ds_read_b128 v[194:197], v168 offset:33792
	ds_read_b128 v[198:201], v168 offset:34816
	ds_read_b128 v[202:205], v168 offset:35840
	ds_read_b128 v[206:209], v168 offset:36864
	ds_read_b128 v[210:213], v168 offset:37888
	ds_read_b128 v[216:219], v168 offset:38912
	ds_read_b128 v[220:223], v168 offset:39936
	global_load_lds_dwordx4 v[230:231], off
	v_lshl_add_u64 v[230:231], s[62:63], 0, v[132:133]
	s_mov_b32 m0, s68
	s_nop 0
	global_load_lds_dwordx4 v[230:231], off
	s_waitcnt vmcnt(8)
	s_waitcnt lgkmcnt(0)
	s_barrier
	s_setprio 1
	s_waitcnt lgkmcnt(0)
	v_mfma_f32_16x16x32_bf16 v[124:127], v[148:151], v[190:193], v[124:127]
	v_mfma_f32_16x16x32_bf16 v[92:95], v[156:159], v[190:193], v[92:95]
	v_mfma_f32_16x16x32_bf16 v[120:123], v[148:151], v[198:201], v[120:123]
	v_mfma_f32_16x16x32_bf16 v[88:91], v[156:159], v[198:201], v[88:91]
	v_mfma_f32_16x16x32_bf16 v[116:119], v[148:151], v[206:209], v[116:119]
	v_mfma_f32_16x16x32_bf16 v[84:87], v[156:159], v[206:209], v[84:87]
	v_mfma_f32_16x16x32_bf16 v[112:115], v[148:151], v[216:219], v[112:115]
	v_mfma_f32_16x16x32_bf16 v[80:83], v[156:159], v[216:219], v[80:83]
	v_mfma_f32_16x16x32_bf16 v[124:127], v[152:155], v[194:197], v[124:127]
	v_mfma_f32_16x16x32_bf16 v[92:95], v[170:173], v[194:197], v[92:95]
	v_mfma_f32_16x16x32_bf16 v[120:123], v[152:155], v[202:205], v[120:123]
	v_mfma_f32_16x16x32_bf16 v[88:91], v[170:173], v[202:205], v[88:91]
	v_mfma_f32_16x16x32_bf16 v[116:119], v[152:155], v[210:213], v[116:119]
	v_mfma_f32_16x16x32_bf16 v[84:87], v[170:173], v[210:213], v[84:87]
	v_mfma_f32_16x16x32_bf16 v[112:115], v[152:155], v[220:223], v[112:115]
	v_mfma_f32_16x16x32_bf16 v[80:83], v[170:173], v[220:223], v[80:83]
	s_setprio 0
	s_setprio 1
	v_mfma_f32_16x16x32_bf16 v[60:63], v[174:177], v[190:193], v[60:63]
	v_mfma_f32_16x16x32_bf16 v[28:31], v[182:185], v[190:193], v[28:31]
	v_mfma_f32_16x16x32_bf16 v[56:59], v[174:177], v[198:201], v[56:59]
	v_mfma_f32_16x16x32_bf16 v[24:27], v[182:185], v[198:201], v[24:27]
	v_mfma_f32_16x16x32_bf16 v[52:55], v[174:177], v[206:209], v[52:55]
	v_mfma_f32_16x16x32_bf16 v[20:23], v[182:185], v[206:209], v[20:23]
	v_mfma_f32_16x16x32_bf16 v[48:51], v[174:177], v[216:219], v[48:51]
	v_mfma_f32_16x16x32_bf16 v[16:19], v[182:185], v[216:219], v[16:19]
	v_mfma_f32_16x16x32_bf16 v[60:63], v[178:181], v[194:197], v[60:63]
	v_mfma_f32_16x16x32_bf16 v[28:31], v[186:189], v[194:197], v[28:31]
	v_mfma_f32_16x16x32_bf16 v[56:59], v[178:181], v[202:205], v[56:59]
	v_mfma_f32_16x16x32_bf16 v[24:27], v[186:189], v[202:205], v[24:27]
	v_mfma_f32_16x16x32_bf16 v[52:55], v[178:181], v[210:213], v[52:55]
	v_mfma_f32_16x16x32_bf16 v[20:23], v[186:189], v[210:213], v[20:23]
	v_mfma_f32_16x16x32_bf16 v[48:51], v[178:181], v[220:223], v[48:51]
	v_mfma_f32_16x16x32_bf16 v[16:19], v[186:189], v[220:223], v[16:19]
	s_setprio 0
	s_barrier
; #define PG8_STAGE(bufoff, gbase, voff) do { _Pragma("unroll") for (int _i = 0; _i < 2; ++_i) \
;         __builtin_amdgcn_global_load_lds((const unsigned*)((const char*)(gbase) + (voff)[_i]), (LAS unsigned*)(lds + (bufoff) + ldsw + _i * 8192), 16, 0, 0); } while (0)
; #define PG8_LDA(dst, b, h) do { _Pragma("unroll") for (int m = 0; m < 4; ++m) _Pragma("unroll") for (int k = 0; k < 2; ++k) dst[m][k] = *(const LAS bf16x8*)(lds + PG8_SA(b, h) + aoff + m * 2048 + k * 1024); } while (0)
; #define PG8_MMA(ai, bj, At, Bt) do { __builtin_amdgcn_s_setprio(1); _Pragma("unroll") for (int m = 0; m < 4; ++m) _Pragma("unroll") for (int n = 0; n < 2; ++n) _Pragma("unroll") for (int k = 0; k < 2; ++k) \
;         acc[ai][bj][m][n] = __builtin_amdgcn_mfma_f32_16x16x32_bf16(Bt[n][k], At[m][k], acc[ai][bj][m][n], 0, 0, 0); __builtin_amdgcn_s_setprio(0); } while (0)
; #define PG8_WAIT_V(n) asm volatile("s_waitcnt vmcnt(" #n ")" ::: "memory")
; #define PG8_WAIT_L(n) asm volatile("s_waitcnt lgkmcnt(" #n ")" ::: "memory")
; #define PG8_BAR __builtin_amdgcn_s_barrier()
; #define PG8_SCHED __builtin_amdgcn_sched_barrier(0)
; template <class Epi, bool ALIGN_EPI = false, bool SP2 = true>
; __device__ __forceinline__ void gemm_phase(LAS unsigned char* lds, const Gemm g, const StaticOrder& S, const Epi& E) {
;     ...
;             PG8_LDA(At, 1, 1); PG8_STAGE(PG8_SB(1, 0), b3, voffB); PG8_STAGE(PG8_SB(1, 1), b3 + hstep, voffB); PG8_STAGE(PG8_SA(1, 0), a3, voffA);
;             PG8_WAIT_V(8); PG8_WAIT_L(0); PG8_BAR; PG8_MMA(1, 0, At, B0); PG8_MMA(1, 1, At, B1); PG8_BAR; PG8_SCHED;
;     ...
;         if constexpr (ALIGN_EPI) { if (wr == 0) PG8_BAR; }
	s_add_i32 s62, s83, s64
	v_lshl_add_u64 v[160:161], v[160:161], 0, s[24:25]
	s_mov_b32 m0, s62
	ds_read_b128 v[190:193], v168 offset:49152
	ds_read_b128 v[194:197], v168 offset:50176
	ds_read_b128 v[198:201], v168 offset:51200
	ds_read_b128 v[202:205], v168 offset:52224
	ds_read_b128 v[206:209], v168 offset:53248
	ds_read_b128 v[210:213], v168 offset:54272
	ds_read_b128 v[216:219], v168 offset:55296
	ds_read_b128 v[220:223], v168 offset:56320
	global_load_lds_dwordx4 v[160:161], off
	s_add_i32 m0, s62, 0x2000
	s_add_u32 s60, s60, 0x80080
	v_lshl_add_u64 v[160:161], v[224:225], 0, s[24:25]
	s_addc_u32 s61, s61, 0
	s_add_i32 s62, s84, s64
	global_load_lds_dwordx4 v[160:161], off
	v_lshl_add_u64 v[160:161], s[60:61], 0, v[130:131]
	s_mov_b32 m0, s62
	s_nop 0
	global_load_lds_dwordx4 v[160:161], off
	v_lshl_add_u64 v[160:161], s[60:61], 0, v[134:135]
	s_add_i32 m0, s62, 0x2000
	s_nop 0
	global_load_lds_dwordx4 v[160:161], off
	v_lshl_add_u64 v[160:161], v[226:227], 0, s[24:25]
	s_mov_b32 m0, s70
	s_nop 0
	global_load_lds_dwordx4 v[160:161], off
	v_lshl_add_u64 v[160:161], v[228:229], 0, s[24:25]
	s_mov_b32 m0, s71
	s_nop 0
	global_load_lds_dwordx4 v[160:161], off
	s_waitcnt vmcnt(8)
	s_waitcnt lgkmcnt(0)
	s_barrier
	s_setprio 1
	s_waitcnt lgkmcnt(0)
	v_mfma_f32_16x16x32_bf16 v[108:111], v[148:151], v[190:193], v[108:111]
	v_mfma_f32_16x16x32_bf16 v[76:79], v[156:159], v[190:193], v[76:79]
	v_mfma_f32_16x16x32_bf16 v[104:107], v[148:151], v[198:201], v[104:107]
	v_mfma_f32_16x16x32_bf16 v[72:75], v[156:159], v[198:201], v[72:75]
	v_mfma_f32_16x16x32_bf16 v[100:103], v[148:151], v[206:209], v[100:103]
	v_mfma_f32_16x16x32_bf16 v[68:71], v[156:159], v[206:209], v[68:71]
	v_mfma_f32_16x16x32_bf16 v[96:99], v[148:151], v[216:219], v[96:99]
	v_mfma_f32_16x16x32_bf16 v[64:67], v[156:159], v[216:219], v[64:67]
	v_mfma_f32_16x16x32_bf16 v[108:111], v[152:155], v[194:197], v[108:111]
	v_mfma_f32_16x16x32_bf16 v[76:79], v[170:173], v[194:197], v[76:79]
	v_mfma_f32_16x16x32_bf16 v[104:107], v[152:155], v[202:205], v[104:107]
	v_mfma_f32_16x16x32_bf16 v[72:75], v[170:173], v[202:205], v[72:75]
	v_mfma_f32_16x16x32_bf16 v[100:103], v[152:155], v[210:213], v[100:103]
	v_mfma_f32_16x16x32_bf16 v[68:71], v[170:173], v[210:213], v[68:71]
	v_mfma_f32_16x16x32_bf16 v[96:99], v[152:155], v[220:223], v[96:99]
	v_mfma_f32_16x16x32_bf16 v[64:67], v[170:173], v[220:223], v[64:67]
	s_setprio 0
	s_setprio 1
	v_mfma_f32_16x16x32_bf16 v[44:47], v[174:177], v[190:193], v[44:47]
	v_mfma_f32_16x16x32_bf16 v[12:15], v[182:185], v[190:193], v[12:15]
	v_mfma_f32_16x16x32_bf16 v[40:43], v[174:177], v[198:201], v[40:43]
	v_mfma_f32_16x16x32_bf16 v[8:11], v[182:185], v[198:201], v[8:11]
	v_mfma_f32_16x16x32_bf16 v[36:39], v[174:177], v[206:209], v[36:39]
	v_mfma_f32_16x16x32_bf16 v[4:7], v[182:185], v[206:209], v[4:7]
	v_mfma_f32_16x16x32_bf16 v[32:35], v[174:177], v[216:219], v[32:35]
	v_mfma_f32_16x16x32_bf16 v[0:3], v[182:185], v[216:219], v[0:3]
	v_mfma_f32_16x16x32_bf16 v[44:47], v[178:181], v[194:197], v[44:47]
	v_mfma_f32_16x16x32_bf16 v[12:15], v[186:189], v[194:197], v[12:15]
	v_mfma_f32_16x16x32_bf16 v[40:43], v[178:181], v[202:205], v[40:43]
	v_mfma_f32_16x16x32_bf16 v[8:11], v[186:189], v[202:205], v[8:11]
	v_mfma_f32_16x16x32_bf16 v[36:39], v[178:181], v[210:213], v[36:39]
	v_mfma_f32_16x16x32_bf16 v[4:7], v[186:189], v[210:213], v[4:7]
	v_mfma_f32_16x16x32_bf16 v[32:35], v[178:181], v[220:223], v[32:35]
	v_mfma_f32_16x16x32_bf16 v[0:3], v[186:189], v[220:223], v[0:3]
	s_add_i32 s82, s82, 2
	s_add_u32 s10, s10, 0x100
	s_addc_u32 s11, s11, 0
	s_add_u32 s80, s80, 0x100
	s_addc_u32 s81, s81, 0
	s_cmp_gt_u32 s82, 29
	s_setprio 0
	s_barrier
	s_cbranch_scc0 .LBB0_518
	s_and_b64 vcc, exec, s[26:27]
	s_cbranch_vccz .LBB0_521
	s_barrier

; #define PG8_STAGE(bufoff, gbase, voff) do { _Pragma("unroll") for (int _i = 0; _i < 2; ++_i) \
;         __builtin_amdgcn_global_load_lds((const unsigned*)((const char*)(gbase) + (voff)[_i]), (LAS unsigned*)(lds + (bufoff) + ldsw + _i * 8192), 16, 0, 0); } while (0)
; #define PG8_LDA(dst, b, h) do { _Pragma("unroll") for (int m = 0; m < 4; ++m) _Pragma("unroll") for (int k = 0; k < 2; ++k) dst[m][k] = *(const LAS bf16x8*)(lds + PG8_SA(b, h) + aoff + m * 2048 + k * 1024); } while (0)
; #define PG8_LDB(dst, b, h) do { _Pragma("unroll") for (int n = 0; n < 2; ++n) _Pragma("unroll") for (int k = 0; k < 2; ++k) dst[n][k] = *(const LAS bf16x8*)(lds + PG8_SB(b, h) + boff + n * 2048 + k * 1024); } while (0)
; #define PG8_MMA(ai, bj, At, Bt) do { __builtin_amdgcn_s_setprio(1); _Pragma("unroll") for (int m = 0; m < 4; ++m) _Pragma("unroll") for (int n = 0; n < 2; ++n) _Pragma("unroll") for (int k = 0; k < 2; ++k) \
;         acc[ai][bj][m][n] = __builtin_amdgcn_mfma_f32_16x16x32_bf16(Bt[n][k], At[m][k], acc[ai][bj][m][n], 0, 0, 0); __builtin_amdgcn_s_setprio(0); } while (0)
; #define PG8_WAIT_V(n) asm volatile("s_waitcnt vmcnt(" #n ")" ::: "memory")
; #define PG8_WAIT_L(n) asm volatile("s_waitcnt lgkmcnt(" #n ")" ::: "memory")
; #define PG8_BAR __builtin_amdgcn_s_barrier()
; template <class Epi, bool ALIGN_EPI = false, bool SP2 = true>
; __device__ __forceinline__ void gemm_phase(LAS unsigned char* lds, const Gemm g, const StaticOrder& S, const Epi& E) {
;     ...
;         for (int t = 0; t < nt; t += 2) {
;             const bool last = (t == nt - 2);
;             const char* a1 = cA + (size_t)(t + 1) * kstep;
;             const char* a2 = last ? nA : cA + (size_t)(t + 2) * kstep; const char* b2 = last ? nB : cB + (size_t)(t + 2) * kstep;
;             const char* a3 = a2 + kstep; const char* b3 = b2 + kstep;
;             if constexpr (SP2) {
;             PG8_LDB(B0, 0, 0); PG8_LDB(B1, 0, 1); PG8_SCHED; PG8_LDA(At, 0, 0); PG8_STAGE(PG8_SA(1, 1), a1 + hstep, voffA);
;             PG8_WAIT_V(8); PG8_WAIT_L(0); PG8_BAR; PG8_MMA(0, 0, At, B0); PG8_MMA(0, 1, At, B1); PG8_BAR; PG8_SCHED;
;             PG8_LDA(At, 0, 1); PG8_STAGE(PG8_SB(0, 0), b2, voffB); PG8_STAGE(PG8_SB(0, 1), b2 + hstep, voffB); PG8_STAGE(PG8_SA(0, 0), a2, voffA);
;             PG8_WAIT_V(8); PG8_WAIT_L(0); PG8_BAR; PG8_MMA(1, 0, At, B0); PG8_MMA(1, 1, At, B1); PG8_BAR; PG8_SCHED;
.LBB0_746:
	v_add_u32_e32 v161, s66, v150
	s_waitcnt lgkmcnt(0)
	ds_read_b128 v[152:155], v161
	ds_read_b128 v[156:159], v161 offset:1024
	ds_read_b128 v[166:169], v161 offset:2048
	ds_read_b128 v[170:173], v161 offset:3072
	v_add_u32_e32 v161, s67, v150
	s_add_u32 s44, s0, s36
	ds_read_b128 v[174:177], v161
	ds_read_b128 v[178:181], v161 offset:1024
	ds_read_b128 v[182:185], v161 offset:2048
	ds_read_b128 v[186:189], v161 offset:3072
	s_addc_u32 s45, s1, s37
	s_add_u32 s44, s44, 0x100
	s_addc_u32 s45, s45, 0
	s_add_u32 s74, s69, s36
	s_addc_u32 s75, s70, s37
	s_cmpk_eq_i32 s36, 0xf00
	s_cselect_b32 s51, s27, s45
	s_cselect_b32 s50, s71, s44
	s_cselect_b32 s45, s19, s75
	s_cselect_b32 s44, s72, s74
	v_lshl_add_u64 v[162:163], v[144:145], 0, s[36:37]
	s_add_i32 m0, s58, 0xc000
	ds_read_b128 v[190:193], v151
	ds_read_b128 v[194:197], v151 offset:1024
	ds_read_b128 v[198:201], v151 offset:2048
	ds_read_b128 v[202:205], v151 offset:3072
	ds_read_b128 v[206:209], v151 offset:4096
	ds_read_b128 v[210:213], v151 offset:5120
	ds_read_b128 v[214:217], v151 offset:6144
	ds_read_b128 v[218:221], v151 offset:7168
	global_load_lds_dwordx4 v[162:163], off
	v_lshl_add_u64 v[162:163], v[146:147], 0, s[36:37]
	s_add_i32 m0, s58, 0xe000
	s_nop 0
	global_load_lds_dwordx4 v[162:163], off
	s_waitcnt vmcnt(8)
	s_waitcnt lgkmcnt(0)
	s_barrier
	s_setprio 1
	s_waitcnt lgkmcnt(0)
	v_mfma_f32_16x16x32_bf16 v[124:127], v[152:155], v[190:193], v[124:127]
	v_mfma_f32_16x16x32_bf16 v[120:123], v[166:169], v[190:193], v[120:123]
	v_mfma_f32_16x16x32_bf16 v[108:111], v[152:155], v[198:201], v[108:111]
	v_mfma_f32_16x16x32_bf16 v[104:107], v[166:169], v[198:201], v[104:107]
	v_mfma_f32_16x16x32_bf16 v[92:95], v[152:155], v[206:209], v[92:95]
	v_mfma_f32_16x16x32_bf16 v[88:91], v[166:169], v[206:209], v[88:91]
	v_mfma_f32_16x16x32_bf16 v[76:79], v[152:155], v[214:217], v[76:79]
	v_mfma_f32_16x16x32_bf16 v[72:75], v[166:169], v[214:217], v[72:75]
	v_mfma_f32_16x16x32_bf16 v[124:127], v[156:159], v[194:197], v[124:127]
	v_mfma_f32_16x16x32_bf16 v[120:123], v[170:173], v[194:197], v[120:123]
	v_mfma_f32_16x16x32_bf16 v[108:111], v[156:159], v[202:205], v[108:111]
	v_mfma_f32_16x16x32_bf16 v[104:107], v[170:173], v[202:205], v[104:107]
	v_mfma_f32_16x16x32_bf16 v[92:95], v[156:159], v[210:213], v[92:95]
	v_mfma_f32_16x16x32_bf16 v[88:91], v[170:173], v[210:213], v[88:91]
	v_mfma_f32_16x16x32_bf16 v[76:79], v[156:159], v[218:221], v[76:79]
	v_mfma_f32_16x16x32_bf16 v[72:75], v[170:173], v[218:221], v[72:75]
	s_setprio 0
	s_setprio 1
	v_mfma_f32_16x16x32_bf16 v[116:119], v[174:177], v[190:193], v[116:119]
	v_mfma_f32_16x16x32_bf16 v[112:115], v[182:185], v[190:193], v[112:115]
	v_mfma_f32_16x16x32_bf16 v[100:103], v[174:177], v[198:201], v[100:103]
	v_mfma_f32_16x16x32_bf16 v[96:99], v[182:185], v[198:201], v[96:99]
	v_mfma_f32_16x16x32_bf16 v[84:87], v[174:177], v[206:209], v[84:87]
	v_mfma_f32_16x16x32_bf16 v[80:83], v[182:185], v[206:209], v[80:83]
	v_mfma_f32_16x16x32_bf16 v[68:71], v[174:177], v[214:217], v[68:71]
	v_mfma_f32_16x16x32_bf16 v[64:67], v[182:185], v[214:217], v[64:67]
	v_mfma_f32_16x16x32_bf16 v[116:119], v[178:181], v[194:197], v[116:119]
	v_mfma_f32_16x16x32_bf16 v[112:115], v[186:189], v[194:197], v[112:115]
	v_mfma_f32_16x16x32_bf16 v[100:103], v[178:181], v[202:205], v[100:103]
	v_mfma_f32_16x16x32_bf16 v[96:99], v[186:189], v[202:205], v[96:99]
	v_mfma_f32_16x16x32_bf16 v[84:87], v[178:181], v[210:213], v[84:87]
	v_mfma_f32_16x16x32_bf16 v[80:83], v[186:189], v[210:213], v[80:83]
	v_mfma_f32_16x16x32_bf16 v[68:71], v[178:181], v[218:221], v[68:71]
	v_mfma_f32_16x16x32_bf16 v[64:67], v[186:189], v[218:221], v[64:67]
	s_setprio 0
	s_barrier
	s_add_i32 s74, s66, s57
	v_lshl_add_u64 v[162:163], s[44:45], 0, v[130:131]
	s_mov_b32 m0, s74
	ds_read_b128 v[190:193], v151 offset:16384
	ds_read_b128 v[194:197], v151 offset:17408
	ds_read_b128 v[198:201], v151 offset:18432
	ds_read_b128 v[202:205], v151 offset:19456
	ds_read_b128 v[206:209], v151 offset:20480
	ds_read_b128 v[210:213], v151 offset:21504
	ds_read_b128 v[214:217], v151 offset:22528
	ds_read_b128 v[218:221], v151 offset:23552
	global_load_lds_dwordx4 v[162:163], off
	s_add_i32 m0, s74, 0x2000
	s_add_u32 s74, s44, 0x80000
	v_lshl_add_u64 v[222:223], s[44:45], 0, v[134:135]
	s_addc_u32 s75, s45, 0
	s_add_i32 s76, s67, s57
	global_load_lds_dwordx4 v[222:223], off
	v_lshl_add_u64 v[224:225], s[74:75], 0, v[130:131]
	s_mov_b32 m0, s76
	v_lshl_add_u64 v[226:227], s[50:51], 0, v[132:133]
	global_load_lds_dwordx4 v[224:225], off
	v_lshl_add_u64 v[224:225], s[74:75], 0, v[134:135]
	s_add_i32 m0, s76, 0x2000
	s_nop 0
	global_load_lds_dwordx4 v[224:225], off
	v_lshl_add_u64 v[224:225], s[50:51], 0, v[128:129]
	s_mov_b32 m0, s58
	s_nop 0
	global_load_lds_dwordx4 v[224:225], off
	s_mov_b32 m0, s59
	s_nop 0
	global_load_lds_dwordx4 v[226:227], off
	s_waitcnt vmcnt(8)
	s_waitcnt lgkmcnt(0)
	s_barrier
; #define PG8_STAGE(bufoff, gbase, voff) do { _Pragma("unroll") for (int _i = 0; _i < 2; ++_i) \
;         __builtin_amdgcn_global_load_lds((const unsigned*)((const char*)(gbase) + (voff)[_i]), (LAS unsigned*)(lds + (bufoff) + ldsw + _i * 8192), 16, 0, 0); } while (0)
; #define PG8_LDA(dst, b, h) do { _Pragma("unroll") for (int m = 0; m < 4; ++m) _Pragma("unroll") for (int k = 0; k < 2; ++k) dst[m][k] = *(const LAS bf16x8*)(lds + PG8_SA(b, h) + aoff + m * 2048 + k * 1024); } while (0)
; #define PG8_LDB(dst, b, h) do { _Pragma("unroll") for (int n = 0; n < 2; ++n) _Pragma("unroll") for (int k = 0; k < 2; ++k) dst[n][k] = *(const LAS bf16x8*)(lds + PG8_SB(b, h) + boff + n * 2048 + k * 1024); } while (0)
; #define PG8_MMA(ai, bj, At, Bt) do { __builtin_amdgcn_s_setprio(1); _Pragma("unroll") for (int m = 0; m < 4; ++m) _Pragma("unroll") for (int n = 0; n < 2; ++n) _Pragma("unroll") for (int k = 0; k < 2; ++k) \
;         acc[ai][bj][m][n] = __builtin_amdgcn_mfma_f32_16x16x32_bf16(Bt[n][k], At[m][k], acc[ai][bj][m][n], 0, 0, 0); __builtin_amdgcn_s_setprio(0); } while (0)
; #define PG8_WAIT_V(n) asm volatile("s_waitcnt vmcnt(" #n ")" ::: "memory")
; #define PG8_WAIT_L(n) asm volatile("s_waitcnt lgkmcnt(" #n ")" ::: "memory")
; #define PG8_BAR __builtin_amdgcn_s_barrier()
; #define PG8_SCHED __builtin_amdgcn_sched_barrier(0)
; template <class Epi, bool ALIGN_EPI = false, bool SP2 = true>
; __device__ __forceinline__ void gemm_phase(LAS unsigned char* lds, const Gemm g, const StaticOrder& S, const Epi& E) {
;     ...
;             PG8_WAIT_V(8); PG8_WAIT_L(0); PG8_BAR; PG8_MMA(1, 0, At, B0); PG8_MMA(1, 1, At, B1); PG8_BAR; PG8_SCHED;
;             PG8_LDB(B0, 1, 0); PG8_LDB(B1, 1, 1); PG8_SCHED; PG8_LDA(At, 1, 0); PG8_STAGE(PG8_SA(0, 1), a2 + hstep, voffA);
;             PG8_WAIT_V(8); PG8_WAIT_L(0); PG8_BAR; PG8_MMA(0, 0, At, B0); PG8_MMA(0, 1, At, B1); PG8_BAR; PG8_SCHED;
	s_setprio 1
	s_waitcnt lgkmcnt(0)
	v_mfma_f32_16x16x32_bf16 v[60:63], v[152:155], v[190:193], v[60:63]
	v_mfma_f32_16x16x32_bf16 v[56:59], v[166:169], v[190:193], v[56:59]
	v_mfma_f32_16x16x32_bf16 v[44:47], v[152:155], v[198:201], v[44:47]
	v_mfma_f32_16x16x32_bf16 v[40:43], v[166:169], v[198:201], v[40:43]
	v_mfma_f32_16x16x32_bf16 v[28:31], v[152:155], v[206:209], v[28:31]
	v_mfma_f32_16x16x32_bf16 v[24:27], v[166:169], v[206:209], v[24:27]
	v_mfma_f32_16x16x32_bf16 v[12:15], v[152:155], v[214:217], v[12:15]
	v_mfma_f32_16x16x32_bf16 v[8:11], v[166:169], v[214:217], v[8:11]
	v_mfma_f32_16x16x32_bf16 v[60:63], v[156:159], v[194:197], v[60:63]
	v_mfma_f32_16x16x32_bf16 v[56:59], v[170:173], v[194:197], v[56:59]
	v_mfma_f32_16x16x32_bf16 v[44:47], v[156:159], v[202:205], v[44:47]
	v_mfma_f32_16x16x32_bf16 v[40:43], v[170:173], v[202:205], v[40:43]
	v_mfma_f32_16x16x32_bf16 v[28:31], v[156:159], v[210:213], v[28:31]
	v_mfma_f32_16x16x32_bf16 v[24:27], v[170:173], v[210:213], v[24:27]
	v_mfma_f32_16x16x32_bf16 v[12:15], v[156:159], v[218:221], v[12:15]
	v_mfma_f32_16x16x32_bf16 v[8:11], v[170:173], v[218:221], v[8:11]
	s_setprio 0
	s_setprio 1
	v_mfma_f32_16x16x32_bf16 v[52:55], v[174:177], v[190:193], v[52:55]
	v_mfma_f32_16x16x32_bf16 v[48:51], v[182:185], v[190:193], v[48:51]
	v_mfma_f32_16x16x32_bf16 v[36:39], v[174:177], v[198:201], v[36:39]
	v_mfma_f32_16x16x32_bf16 v[32:35], v[182:185], v[198:201], v[32:35]
	v_mfma_f32_16x16x32_bf16 v[20:23], v[174:177], v[206:209], v[20:23]
	v_mfma_f32_16x16x32_bf16 v[16:19], v[182:185], v[206:209], v[16:19]
	v_mfma_f32_16x16x32_bf16 v[4:7], v[174:177], v[214:217], v[4:7]
	v_mfma_f32_16x16x32_bf16 v[0:3], v[182:185], v[214:217], v[0:3]
	v_mfma_f32_16x16x32_bf16 v[52:55], v[178:181], v[194:197], v[52:55]
	v_mfma_f32_16x16x32_bf16 v[48:51], v[186:189], v[194:197], v[48:51]
	v_mfma_f32_16x16x32_bf16 v[36:39], v[178:181], v[202:205], v[36:39]
	v_mfma_f32_16x16x32_bf16 v[32:35], v[186:189], v[202:205], v[32:35]
	v_mfma_f32_16x16x32_bf16 v[20:23], v[178:181], v[210:213], v[20:23]
	v_mfma_f32_16x16x32_bf16 v[16:19], v[186:189], v[210:213], v[16:19]
	v_mfma_f32_16x16x32_bf16 v[4:7], v[178:181], v[218:221], v[4:7]
	v_mfma_f32_16x16x32_bf16 v[0:3], v[186:189], v[218:221], v[0:3]
	s_setprio 0
	s_barrier
	s_add_i32 s74, 0, 0x18000
	v_add_u32_e32 v161, s74, v150
	s_add_i32 s75, 0, 0x1c000
	ds_read_b128 v[152:155], v161
	ds_read_b128 v[156:159], v161 offset:1024
	ds_read_b128 v[166:169], v161 offset:2048
	ds_read_b128 v[170:173], v161 offset:3072
	v_add_u32_e32 v161, s75, v150
	ds_read_b128 v[174:177], v161
	ds_read_b128 v[178:181], v161 offset:1024
	ds_read_b128 v[182:185], v161 offset:2048
	ds_read_b128 v[186:189], v161 offset:3072
	s_add_u32 s50, s50, 0x80000
	s_addc_u32 s51, s51, 0
	s_mov_b32 m0, s60
	v_lshl_add_u64 v[228:229], s[50:51], 0, v[128:129]
	ds_read_b128 v[190:193], v151 offset:32768
	ds_read_b128 v[194:197], v151 offset:33792
	ds_read_b128 v[198:201], v151 offset:34816
	ds_read_b128 v[202:205], v151 offset:35840
	ds_read_b128 v[206:209], v151 offset:36864
	ds_read_b128 v[210:213], v151 offset:37888
	ds_read_b128 v[214:217], v151 offset:38912
	ds_read_b128 v[218:221], v151 offset:39936
	global_load_lds_dwordx4 v[228:229], off
	v_lshl_add_u64 v[228:229], s[50:51], 0, v[132:133]
	s_mov_b32 m0, s61
	s_nop 0
	global_load_lds_dwordx4 v[228:229], off
	s_waitcnt vmcnt(8)
	s_waitcnt lgkmcnt(0)
	s_barrier
	s_setprio 1
	s_waitcnt lgkmcnt(0)
	v_mfma_f32_16x16x32_bf16 v[124:127], v[152:155], v[190:193], v[124:127]
	v_mfma_f32_16x16x32_bf16 v[120:123], v[166:169], v[190:193], v[120:123]
	v_mfma_f32_16x16x32_bf16 v[108:111], v[152:155], v[198:201], v[108:111]
	v_mfma_f32_16x16x32_bf16 v[104:107], v[166:169], v[198:201], v[104:107]
	v_mfma_f32_16x16x32_bf16 v[92:95], v[152:155], v[206:209], v[92:95]
	v_mfma_f32_16x16x32_bf16 v[88:91], v[166:169], v[206:209], v[88:91]
	v_mfma_f32_16x16x32_bf16 v[76:79], v[152:155], v[214:217], v[76:79]
	v_mfma_f32_16x16x32_bf16 v[72:75], v[166:169], v[214:217], v[72:75]
	v_mfma_f32_16x16x32_bf16 v[124:127], v[156:159], v[194:197], v[124:127]
	v_mfma_f32_16x16x32_bf16 v[120:123], v[170:173], v[194:197], v[120:123]
	v_mfma_f32_16x16x32_bf16 v[108:111], v[156:159], v[202:205], v[108:111]
	v_mfma_f32_16x16x32_bf16 v[104:107], v[170:173], v[202:205], v[104:107]
	v_mfma_f32_16x16x32_bf16 v[92:95], v[156:159], v[210:213], v[92:95]
	v_mfma_f32_16x16x32_bf16 v[88:91], v[170:173], v[210:213], v[88:91]
	v_mfma_f32_16x16x32_bf16 v[76:79], v[156:159], v[218:221], v[76:79]
	v_mfma_f32_16x16x32_bf16 v[72:75], v[170:173], v[218:221], v[72:75]
	s_setprio 0
	s_setprio 1
	v_mfma_f32_16x16x32_bf16 v[116:119], v[174:177], v[190:193], v[116:119]
	v_mfma_f32_16x16x32_bf16 v[112:115], v[182:185], v[190:193], v[112:115]
	v_mfma_f32_16x16x32_bf16 v[100:103], v[174:177], v[198:201], v[100:103]
	v_mfma_f32_16x16x32_bf16 v[96:99], v[182:185], v[198:201], v[96:99]
	v_mfma_f32_16x16x32_bf16 v[84:87], v[174:177], v[206:209], v[84:87]
	v_mfma_f32_16x16x32_bf16 v[80:83], v[182:185], v[206:209], v[80:83]
	v_mfma_f32_16x16x32_bf16 v[68:71], v[174:177], v[214:217], v[68:71]
	v_mfma_f32_16x16x32_bf16 v[64:67], v[182:185], v[214:217], v[64:67]
	v_mfma_f32_16x16x32_bf16 v[116:119], v[178:181], v[194:197], v[116:119]
	v_mfma_f32_16x16x32_bf16 v[112:115], v[186:189], v[194:197], v[112:115]
	v_mfma_f32_16x16x32_bf16 v[100:103], v[178:181], v[202:205], v[100:103]
	v_mfma_f32_16x16x32_bf16 v[96:99], v[186:189], v[202:205], v[96:99]
	v_mfma_f32_16x16x32_bf16 v[84:87], v[178:181], v[210:213], v[84:87]
	v_mfma_f32_16x16x32_bf16 v[80:83], v[186:189], v[210:213], v[80:83]
	v_mfma_f32_16x16x32_bf16 v[68:71], v[178:181], v[218:221], v[68:71]
	v_mfma_f32_16x16x32_bf16 v[64:67], v[186:189], v[218:221], v[64:67]
	s_setprio 0
	s_barrier
; #define PG8_STAGE(bufoff, gbase, voff) do { _Pragma("unroll") for (int _i = 0; _i < 2; ++_i) \
;         __builtin_amdgcn_global_load_lds((const unsigned*)((const char*)(gbase) + (voff)[_i]), (LAS unsigned*)(lds + (bufoff) + ldsw + _i * 8192), 16, 0, 0); } while (0)
; #define PG8_LDA(dst, b, h) do { _Pragma("unroll") for (int m = 0; m < 4; ++m) _Pragma("unroll") for (int k = 0; k < 2; ++k) dst[m][k] = *(const LAS bf16x8*)(lds + PG8_SA(b, h) + aoff + m * 2048 + k * 1024); } while (0)
; #define PG8_MMA(ai, bj, At, Bt) do { __builtin_amdgcn_s_setprio(1); _Pragma("unroll") for (int m = 0; m < 4; ++m) _Pragma("unroll") for (int n = 0; n < 2; ++n) _Pragma("unroll") for (int k = 0; k < 2; ++k) \
;         acc[ai][bj][m][n] = __builtin_amdgcn_mfma_f32_16x16x32_bf16(Bt[n][k], At[m][k], acc[ai][bj][m][n], 0, 0, 0); __builtin_amdgcn_s_setprio(0); } while (0)
; #define PG8_WAIT_V(n) asm volatile("s_waitcnt vmcnt(" #n ")" ::: "memory")
; #define PG8_WAIT_L(n) asm volatile("s_waitcnt lgkmcnt(" #n ")" ::: "memory")
; #define PG8_BAR __builtin_amdgcn_s_barrier()
; #define PG8_SCHED __builtin_amdgcn_sched_barrier(0)
; template <class Epi, bool ALIGN_EPI = false, bool SP2 = true>
; __device__ __forceinline__ void gemm_phase(LAS unsigned char* lds, const Gemm g, const StaticOrder& S, const Epi& E) {
;     ...
;             PG8_LDA(At, 1, 1); PG8_STAGE(PG8_SB(1, 0), b3, voffB); PG8_STAGE(PG8_SB(1, 1), b3 + hstep, voffB); PG8_STAGE(PG8_SA(1, 0), a3, voffA);
;             PG8_WAIT_V(8); PG8_WAIT_L(0); PG8_BAR; PG8_MMA(1, 0, At, B0); PG8_MMA(1, 1, At, B1); PG8_BAR; PG8_SCHED;
;     ...
;         if (!has_next) break;
; #pragma unroll
;         for (int a = 0; a < 2; ++a)
; #pragma unroll
;             for (int b = 0; b < 2; ++b)
; #pragma unroll
;                 for (int m = 0; m < 4; ++m)
; #pragma unroll
;                     for (int n = 0; n < 2; ++n) acc[a][b][m][n] = (f32x4){0.f, 0.f, 0.f, 0.f};
;         cur = nxt; cA = nA; cB = nB; ++ui;
	s_add_i32 s50, s74, s57
	v_lshl_add_u64 v[162:163], v[162:163], 0, s[16:17]
	s_mov_b32 m0, s50
	ds_read_b128 v[190:193], v151 offset:49152
	ds_read_b128 v[194:197], v151 offset:50176
	ds_read_b128 v[198:201], v151 offset:51200
	ds_read_b128 v[202:205], v151 offset:52224
	ds_read_b128 v[206:209], v151 offset:53248
	ds_read_b128 v[210:213], v151 offset:54272
	ds_read_b128 v[214:217], v151 offset:55296
	ds_read_b128 v[218:221], v151 offset:56320
	global_load_lds_dwordx4 v[162:163], off
	s_add_i32 m0, s50, 0x2000
	s_add_u32 s44, s44, 0x80080
	v_lshl_add_u64 v[162:163], v[222:223], 0, s[16:17]
	s_addc_u32 s45, s45, 0
	s_add_i32 s50, s75, s57
	global_load_lds_dwordx4 v[162:163], off
	v_lshl_add_u64 v[162:163], s[44:45], 0, v[130:131]
	s_mov_b32 m0, s50
	s_nop 0
	global_load_lds_dwordx4 v[162:163], off
	v_lshl_add_u64 v[162:163], s[44:45], 0, v[134:135]
	s_add_i32 m0, s50, 0x2000
	s_nop 0
	global_load_lds_dwordx4 v[162:163], off
	v_lshl_add_u64 v[162:163], v[224:225], 0, s[16:17]
	s_mov_b32 m0, s63
	s_nop 0
	global_load_lds_dwordx4 v[162:163], off
	v_lshl_add_u64 v[162:163], v[226:227], 0, s[16:17]
	s_mov_b32 m0, s64
	s_nop 0
	global_load_lds_dwordx4 v[162:163], off
	s_waitcnt vmcnt(8)
	s_waitcnt lgkmcnt(0)
	s_barrier
	s_setprio 1
	s_waitcnt lgkmcnt(0)
	v_mfma_f32_16x16x32_bf16 v[60:63], v[152:155], v[190:193], v[60:63]
	v_mfma_f32_16x16x32_bf16 v[56:59], v[166:169], v[190:193], v[56:59]
	v_mfma_f32_16x16x32_bf16 v[44:47], v[152:155], v[198:201], v[44:47]
	v_mfma_f32_16x16x32_bf16 v[40:43], v[166:169], v[198:201], v[40:43]
	v_mfma_f32_16x16x32_bf16 v[28:31], v[152:155], v[206:209], v[28:31]
	v_mfma_f32_16x16x32_bf16 v[24:27], v[166:169], v[206:209], v[24:27]
	v_mfma_f32_16x16x32_bf16 v[12:15], v[152:155], v[214:217], v[12:15]
	v_mfma_f32_16x16x32_bf16 v[8:11], v[166:169], v[214:217], v[8:11]
	v_mfma_f32_16x16x32_bf16 v[60:63], v[156:159], v[194:197], v[60:63]
	v_mfma_f32_16x16x32_bf16 v[56:59], v[170:173], v[194:197], v[56:59]
	v_mfma_f32_16x16x32_bf16 v[44:47], v[156:159], v[202:205], v[44:47]
	v_mfma_f32_16x16x32_bf16 v[40:43], v[170:173], v[202:205], v[40:43]
	v_mfma_f32_16x16x32_bf16 v[28:31], v[156:159], v[210:213], v[28:31]
	v_mfma_f32_16x16x32_bf16 v[24:27], v[170:173], v[210:213], v[24:27]
	v_mfma_f32_16x16x32_bf16 v[12:15], v[156:159], v[218:221], v[12:15]
	v_mfma_f32_16x16x32_bf16 v[8:11], v[170:173], v[218:221], v[8:11]
	s_setprio 0
	s_setprio 1
	v_mfma_f32_16x16x32_bf16 v[52:55], v[174:177], v[190:193], v[52:55]
	v_mfma_f32_16x16x32_bf16 v[48:51], v[182:185], v[190:193], v[48:51]
	v_mfma_f32_16x16x32_bf16 v[36:39], v[174:177], v[198:201], v[36:39]
	v_mfma_f32_16x16x32_bf16 v[32:35], v[182:185], v[198:201], v[32:35]
	v_mfma_f32_16x16x32_bf16 v[20:23], v[174:177], v[206:209], v[20:23]
	v_mfma_f32_16x16x32_bf16 v[16:19], v[182:185], v[206:209], v[16:19]
	v_mfma_f32_16x16x32_bf16 v[4:7], v[174:177], v[214:217], v[4:7]
	v_mfma_f32_16x16x32_bf16 v[0:3], v[182:185], v[214:217], v[0:3]
	v_mfma_f32_16x16x32_bf16 v[52:55], v[178:181], v[194:197], v[52:55]
	v_mfma_f32_16x16x32_bf16 v[48:51], v[186:189], v[194:197], v[48:51]
	v_mfma_f32_16x16x32_bf16 v[36:39], v[178:181], v[202:205], v[36:39]
	v_mfma_f32_16x16x32_bf16 v[32:35], v[186:189], v[202:205], v[32:35]
	v_mfma_f32_16x16x32_bf16 v[20:23], v[178:181], v[210:213], v[20:23]
	v_mfma_f32_16x16x32_bf16 v[16:19], v[186:189], v[210:213], v[16:19]
	v_mfma_f32_16x16x32_bf16 v[4:7], v[178:181], v[218:221], v[4:7]
	v_mfma_f32_16x16x32_bf16 v[0:3], v[186:189], v[218:221], v[0:3]
	s_add_i32 s73, s73, 2
	s_add_u32 s36, s36, 0x100
	s_addc_u32 s37, s37, 0
	s_cmp_gt_u32 s73, 29
	s_setprio 0
	s_barrier
	s_cbranch_scc0 .LBB0_746
	s_add_u32 s36, s69, 0xffffff00
	s_addc_u32 s37, s70, -1
	s_andn2_b64 vcc, exec, s[6:7]
	s_cbranch_vccnz .LBB0_749
	v_mov_b32_e32 v0, 0
	s_mov_b32 s14, s18
	s_mov_b32 s10, s26
	s_mov_b64 s[0:1], s[30:31]
	s_mov_b32 s65, s68
	v_mov_b32_e32 v1, v0
	v_mov_b32_e32 v2, v0
	v_mov_b32_e32 v3, v0
	v_mov_b32_e32 v4, v0
	v_mov_b32_e32 v5, v0
	v_mov_b32_e32 v6, v0
	v_mov_b32_e32 v7, v0
	v_mov_b32_e32 v16, v0
	v_mov_b32_e32 v17, v0
	v_mov_b32_e32 v18, v0
	v_mov_b32_e32 v19, v0
	v_mov_b32_e32 v20, v0
	v_mov_b32_e32 v21, v0
	v_mov_b32_e32 v22, v0
	v_mov_b32_e32 v23, v0
	v_mov_b32_e32 v32, v0
	v_mov_b32_e32 v33, v0
	v_mov_b32_e32 v34, v0
	v_mov_b32_e32 v35, v0
	v_mov_b32_e32 v36, v0
	v_mov_b32_e32 v37, v0
	v_mov_b32_e32 v38, v0
	v_mov_b32_e32 v39, v0
	v_mov_b32_e32 v48, v0
	v_mov_b32_e32 v49, v0
	v_mov_b32_e32 v50, v0
	v_mov_b32_e32 v51, v0
	v_mov_b32_e32 v52, v0
	v_mov_b32_e32 v53, v0
	v_mov_b32_e32 v54, v0
	v_mov_b32_e32 v55, v0
	v_mov_b32_e32 v8, v0
	v_mov_b32_e32 v9, v0
	v_mov_b32_e32 v10, v0
	v_mov_b32_e32 v11, v0
	v_mov_b32_e32 v12, v0
	v_mov_b32_e32 v13, v0
	v_mov_b32_e32 v14, v0
	v_mov_b32_e32 v15, v0
	v_mov_b32_e32 v24, v0
	v_mov_b32_e32 v25, v0
	v_mov_b32_e32 v26, v0
	v_mov_b32_e32 v27, v0
	v_mov_b32_e32 v28, v0
	v_mov_b32_e32 v29, v0
	v_mov_b32_e32 v30, v0
	v_mov_b32_e32 v31, v0
	v_mov_b32_e32 v40, v0
	v_mov_b32_e32 v41, v0
	v_mov_b32_e32 v42, v0
	v_mov_b32_e32 v43, v0
	v_mov_b32_e32 v44, v0
	v_mov_b32_e32 v45, v0
	v_mov_b32_e32 v46, v0
	v_mov_b32_e32 v47, v0
	v_mov_b32_e32 v56, v0
	v_mov_b32_e32 v57, v0
	v_mov_b32_e32 v58, v0
	v_mov_b32_e32 v59, v0
	v_mov_b32_e32 v60, v0
	v_mov_b32_e32 v61, v0
	v_mov_b32_e32 v62, v0
	v_mov_b32_e32 v63, v0
	v_mov_b32_e32 v64, v0
	v_mov_b32_e32 v65, v0
	v_mov_b32_e32 v66, v0
	v_mov_b32_e32 v67, v0
	v_mov_b32_e32 v68, v0
	v_mov_b32_e32 v69, v0
	v_mov_b32_e32 v70, v0
	v_mov_b32_e32 v71, v0
	v_mov_b32_e32 v80, v0
	v_mov_b32_e32 v81, v0
	v_mov_b32_e32 v82, v0
	v_mov_b32_e32 v83, v0
	v_mov_b32_e32 v84, v0
	v_mov_b32_e32 v85, v0
	v_mov_b32_e32 v86, v0
	v_mov_b32_e32 v87, v0
	v_mov_b32_e32 v96, v0
	v_mov_b32_e32 v97, v0
	v_mov_b32_e32 v98, v0
	v_mov_b32_e32 v99, v0
	v_mov_b32_e32 v100, v0
	v_mov_b32_e32 v101, v0
	v_mov_b32_e32 v102, v0
	v_mov_b32_e32 v103, v0
	v_mov_b32_e32 v112, v0
	v_mov_b32_e32 v113, v0
	v_mov_b32_e32 v114, v0
	v_mov_b32_e32 v115, v0
	v_mov_b32_e32 v116, v0
	v_mov_b32_e32 v117, v0
	v_mov_b32_e32 v118, v0
	v_mov_b32_e32 v119, v0
	v_mov_b32_e32 v72, v0
	v_mov_b32_e32 v73, v0
	v_mov_b32_e32 v74, v0
	v_mov_b32_e32 v75, v0
	v_mov_b32_e32 v76, v0
	v_mov_b32_e32 v77, v0
	v_mov_b32_e32 v78, v0
	v_mov_b32_e32 v79, v0
	v_mov_b32_e32 v88, v0
	v_mov_b32_e32 v89, v0
	v_mov_b32_e32 v90, v0
	v_mov_b32_e32 v91, v0
	v_mov_b32_e32 v92, v0
	v_mov_b32_e32 v93, v0
	v_mov_b32_e32 v94, v0
	v_mov_b32_e32 v95, v0
	v_mov_b32_e32 v104, v0
	v_mov_b32_e32 v105, v0
	v_mov_b32_e32 v106, v0
	v_mov_b32_e32 v107, v0
	v_mov_b32_e32 v108, v0
	v_mov_b32_e32 v109, v0
	v_mov_b32_e32 v110, v0
	v_mov_b32_e32 v111, v0
	v_mov_b32_e32 v120, v0
	v_mov_b32_e32 v121, v0
	v_mov_b32_e32 v122, v0
	v_mov_b32_e32 v123, v0
	v_mov_b32_e32 v124, v0
	v_mov_b32_e32 v125, v0
	v_mov_b32_e32 v126, v0
	v_mov_b32_e32 v127, v0
	s_andn2_b64 vcc, exec, s[4:5]
	s_cbranch_vccnz .LBB0_750
	s_branch .LBB0_751

; #define PG8_STAGE(bufoff, gbase, voff) do { _Pragma("unroll") for (int _i = 0; _i < 2; ++_i) \
;         __builtin_amdgcn_global_load_lds((const unsigned*)((const char*)(gbase) + (voff)[_i]), (LAS unsigned*)(lds + (bufoff) + ldsw + _i * 8192), 16, 0, 0); } while (0)
; #define PG8_LDA(dst, b, h) do { _Pragma("unroll") for (int m = 0; m < 4; ++m) _Pragma("unroll") for (int k = 0; k < 2; ++k) dst[m][k] = *(const LAS bf16x8*)(lds + PG8_SA(b, h) + aoff + m * 2048 + k * 1024); } while (0)
; #define PG8_LDB(dst, b, h) do { _Pragma("unroll") for (int n = 0; n < 2; ++n) _Pragma("unroll") for (int k = 0; k < 2; ++k) dst[n][k] = *(const LAS bf16x8*)(lds + PG8_SB(b, h) + boff + n * 2048 + k * 1024); } while (0)
; #define PG8_MMA(ai, bj, At, Bt) do { __builtin_amdgcn_s_setprio(1); _Pragma("unroll") for (int m = 0; m < 4; ++m) _Pragma("unroll") for (int n = 0; n < 2; ++n) _Pragma("unroll") for (int k = 0; k < 2; ++k) \
;         acc[ai][bj][m][n] = __builtin_amdgcn_mfma_f32_16x16x32_bf16(Bt[n][k], At[m][k], acc[ai][bj][m][n], 0, 0, 0); __builtin_amdgcn_s_setprio(0); } while (0)
; #define PG8_WAIT_V(n) asm volatile("s_waitcnt vmcnt(" #n ")" ::: "memory")
; #define PG8_WAIT_L(n) asm volatile("s_waitcnt lgkmcnt(" #n ")" ::: "memory")
; #define PG8_BAR __builtin_amdgcn_s_barrier()
; template <class Epi, bool ALIGN_EPI = false, bool SP2 = true>
; __device__ __forceinline__ void gemm_phase(LAS unsigned char* lds, const Gemm g, const StaticOrder& S, const Epi& E) {
;     ...
;         for (int t = 0; t < nt; t += 2) {
;             const bool last = (t == nt - 2);
;             const char* a1 = cA + (size_t)(t + 1) * kstep;
;             const char* a2 = last ? nA : cA + (size_t)(t + 2) * kstep; const char* b2 = last ? nB : cB + (size_t)(t + 2) * kstep;
;             const char* a3 = a2 + kstep; const char* b3 = b2 + kstep;
;             if constexpr (SP2) {
;             PG8_LDB(B0, 0, 0); PG8_LDB(B1, 0, 1); PG8_SCHED; PG8_LDA(At, 0, 0); PG8_STAGE(PG8_SA(1, 1), a1 + hstep, voffA);
;             PG8_WAIT_V(8); PG8_WAIT_L(0); PG8_BAR; PG8_MMA(0, 0, At, B0); PG8_MMA(0, 1, At, B1); PG8_BAR; PG8_SCHED;
;             PG8_LDA(At, 0, 1); PG8_STAGE(PG8_SB(0, 0), b2, voffB); PG8_STAGE(PG8_SB(0, 1), b2 + hstep, voffB); PG8_STAGE(PG8_SA(0, 0), a2, voffA);
;             PG8_WAIT_V(8); PG8_WAIT_L(0); PG8_BAR; PG8_MMA(1, 0, At, B0); PG8_MMA(1, 1, At, B1); PG8_BAR; PG8_SCHED;
.LBB0_855:
	ds_read_b128 v[128:131], v187
	ds_read_b128 v[132:135], v187 offset:1024
	ds_read_b128 v[136:139], v187 offset:2048
	ds_read_b128 v[140:143], v187 offset:3072
	ds_read_b128 v[144:147], v188
	ds_read_b128 v[148:151], v188 offset:1024
	s_waitcnt lgkmcnt(0)
	ds_read_b128 v[152:155], v188 offset:2048
	ds_read_b128 v[156:159], v188 offset:3072
	s_add_u32 s44, s40, 0xfff80080
	s_addc_u32 s45, s41, -1
	s_cmp_eq_u32 s68, 28
	s_cselect_b32 s47, s29, s45
	s_cselect_b32 s46, s64, s44
	s_cselect_b32 s45, s27, s67
	s_cselect_b32 s44, s65, s66
	v_lshl_add_u64 v[214:215], s[40:41], 0, v[164:165]
	s_add_i32 m0, s35, 0xc000
	ds_read_b128 v[160:163], v189
	ds_read_b128 v[180:183], v189 offset:1024
	ds_read_b128 v[190:193], v189 offset:2048
	ds_read_b128 v[194:197], v189 offset:3072
	ds_read_b128 v[198:201], v189 offset:4096
	ds_read_b128 v[202:205], v189 offset:5120
	ds_read_b128 v[206:209], v189 offset:6144
	ds_read_b128 v[210:213], v189 offset:7168
	global_load_lds_dwordx4 v[214:215], off
	v_lshl_add_u64 v[214:215], s[40:41], 0, v[174:175]
	s_add_i32 m0, s35, 0xe000
	s_nop 0
	global_load_lds_dwordx4 v[214:215], off
	s_waitcnt vmcnt(8)
	s_waitcnt lgkmcnt(0)
	s_barrier
	s_setprio 1
	s_waitcnt lgkmcnt(0)
	v_mfma_f32_16x16x32_bf16 v[124:127], v[128:131], v[160:163], v[124:127]
	v_mfma_f32_16x16x32_bf16 v[120:123], v[136:139], v[160:163], v[120:123]
	v_mfma_f32_16x16x32_bf16 v[108:111], v[128:131], v[190:193], v[108:111]
	v_mfma_f32_16x16x32_bf16 v[104:107], v[136:139], v[190:193], v[104:107]
	v_mfma_f32_16x16x32_bf16 v[92:95], v[128:131], v[198:201], v[92:95]
	v_mfma_f32_16x16x32_bf16 v[88:91], v[136:139], v[198:201], v[88:91]
	v_mfma_f32_16x16x32_bf16 v[76:79], v[128:131], v[206:209], v[76:79]
	v_mfma_f32_16x16x32_bf16 v[72:75], v[136:139], v[206:209], v[72:75]
	v_mfma_f32_16x16x32_bf16 v[124:127], v[132:135], v[180:183], v[124:127]
	v_mfma_f32_16x16x32_bf16 v[120:123], v[140:143], v[180:183], v[120:123]
	v_mfma_f32_16x16x32_bf16 v[108:111], v[132:135], v[194:197], v[108:111]
	v_mfma_f32_16x16x32_bf16 v[104:107], v[140:143], v[194:197], v[104:107]
	v_mfma_f32_16x16x32_bf16 v[92:95], v[132:135], v[202:205], v[92:95]
	v_mfma_f32_16x16x32_bf16 v[88:91], v[140:143], v[202:205], v[88:91]
	v_mfma_f32_16x16x32_bf16 v[76:79], v[132:135], v[210:213], v[76:79]
	v_mfma_f32_16x16x32_bf16 v[72:75], v[140:143], v[210:213], v[72:75]
	s_setprio 0
	s_setprio 1
	v_mfma_f32_16x16x32_bf16 v[116:119], v[144:147], v[160:163], v[116:119]
	v_mfma_f32_16x16x32_bf16 v[112:115], v[152:155], v[160:163], v[112:115]
	v_mfma_f32_16x16x32_bf16 v[100:103], v[144:147], v[190:193], v[100:103]
	v_mfma_f32_16x16x32_bf16 v[96:99], v[152:155], v[190:193], v[96:99]
	v_mfma_f32_16x16x32_bf16 v[84:87], v[144:147], v[198:201], v[84:87]
	v_mfma_f32_16x16x32_bf16 v[80:83], v[152:155], v[198:201], v[80:83]
	v_mfma_f32_16x16x32_bf16 v[68:71], v[144:147], v[206:209], v[68:71]
	v_mfma_f32_16x16x32_bf16 v[64:67], v[152:155], v[206:209], v[64:67]
	v_mfma_f32_16x16x32_bf16 v[116:119], v[148:151], v[180:183], v[116:119]
	v_mfma_f32_16x16x32_bf16 v[112:115], v[156:159], v[180:183], v[112:115]
	v_mfma_f32_16x16x32_bf16 v[100:103], v[148:151], v[194:197], v[100:103]
	v_mfma_f32_16x16x32_bf16 v[96:99], v[156:159], v[194:197], v[96:99]
	v_mfma_f32_16x16x32_bf16 v[84:87], v[148:151], v[202:205], v[84:87]
	v_mfma_f32_16x16x32_bf16 v[80:83], v[156:159], v[202:205], v[80:83]
	v_mfma_f32_16x16x32_bf16 v[68:71], v[148:151], v[210:213], v[68:71]
	v_mfma_f32_16x16x32_bf16 v[64:67], v[156:159], v[210:213], v[64:67]
	s_setprio 0
	s_barrier
	s_add_i32 s69, s57, s33
	v_lshl_add_u64 v[214:215], s[44:45], 0, v[168:169]
	s_mov_b32 m0, s69
	ds_read_b128 v[160:163], v189 offset:16384
	ds_read_b128 v[180:183], v189 offset:17408
	ds_read_b128 v[190:193], v189 offset:18432
	ds_read_b128 v[194:197], v189 offset:19456
	ds_read_b128 v[198:201], v189 offset:20480
	ds_read_b128 v[202:205], v189 offset:21504
	ds_read_b128 v[206:209], v189 offset:22528
	ds_read_b128 v[210:213], v189 offset:23552
	global_load_lds_dwordx4 v[214:215], off
	s_add_i32 m0, s69, 0x2000
	s_add_u32 s70, s44, 0x80000
	v_lshl_add_u64 v[216:217], s[44:45], 0, v[172:173]
	s_addc_u32 s71, s45, 0
	s_add_i32 s69, s58, s33
	global_load_lds_dwordx4 v[216:217], off
	v_lshl_add_u64 v[218:219], s[70:71], 0, v[168:169]
	s_mov_b32 m0, s69
	v_lshl_add_u64 v[220:221], s[46:47], 0, v[170:171]
	global_load_lds_dwordx4 v[218:219], off
	v_lshl_add_u64 v[218:219], s[70:71], 0, v[172:173]
	s_add_i32 m0, s69, 0x2000
	s_nop 0
	global_load_lds_dwordx4 v[218:219], off
	v_lshl_add_u64 v[218:219], s[46:47], 0, v[166:167]
	s_mov_b32 m0, s35
	s_nop 0
	global_load_lds_dwordx4 v[218:219], off
	s_mov_b32 m0, s43
	s_nop 0
	global_load_lds_dwordx4 v[220:221], off
	s_waitcnt vmcnt(8)
	s_waitcnt lgkmcnt(0)
	s_barrier
; #define PG8_STAGE(bufoff, gbase, voff) do { _Pragma("unroll") for (int _i = 0; _i < 2; ++_i) \
;         __builtin_amdgcn_global_load_lds((const unsigned*)((const char*)(gbase) + (voff)[_i]), (LAS unsigned*)(lds + (bufoff) + ldsw + _i * 8192), 16, 0, 0); } while (0)
; #define PG8_LDA(dst, b, h) do { _Pragma("unroll") for (int m = 0; m < 4; ++m) _Pragma("unroll") for (int k = 0; k < 2; ++k) dst[m][k] = *(const LAS bf16x8*)(lds + PG8_SA(b, h) + aoff + m * 2048 + k * 1024); } while (0)
; #define PG8_LDB(dst, b, h) do { _Pragma("unroll") for (int n = 0; n < 2; ++n) _Pragma("unroll") for (int k = 0; k < 2; ++k) dst[n][k] = *(const LAS bf16x8*)(lds + PG8_SB(b, h) + boff + n * 2048 + k * 1024); } while (0)
; #define PG8_MMA(ai, bj, At, Bt) do { __builtin_amdgcn_s_setprio(1); _Pragma("unroll") for (int m = 0; m < 4; ++m) _Pragma("unroll") for (int n = 0; n < 2; ++n) _Pragma("unroll") for (int k = 0; k < 2; ++k) \
;         acc[ai][bj][m][n] = __builtin_amdgcn_mfma_f32_16x16x32_bf16(Bt[n][k], At[m][k], acc[ai][bj][m][n], 0, 0, 0); __builtin_amdgcn_s_setprio(0); } while (0)
; #define PG8_WAIT_V(n) asm volatile("s_waitcnt vmcnt(" #n ")" ::: "memory")
; #define PG8_WAIT_L(n) asm volatile("s_waitcnt lgkmcnt(" #n ")" ::: "memory")
; #define PG8_BAR __builtin_amdgcn_s_barrier()
; #define PG8_SCHED __builtin_amdgcn_sched_barrier(0)
; template <class Epi, bool ALIGN_EPI = false, bool SP2 = true>
; __device__ __forceinline__ void gemm_phase(LAS unsigned char* lds, const Gemm g, const StaticOrder& S, const Epi& E) {
;     ...
;             PG8_WAIT_V(8); PG8_WAIT_L(0); PG8_BAR; PG8_MMA(1, 0, At, B0); PG8_MMA(1, 1, At, B1); PG8_BAR; PG8_SCHED;
;             PG8_LDB(B0, 1, 0); PG8_LDB(B1, 1, 1); PG8_SCHED; PG8_LDA(At, 1, 0); PG8_STAGE(PG8_SA(0, 1), a2 + hstep, voffA);
;             PG8_WAIT_V(8); PG8_WAIT_L(0); PG8_BAR; PG8_MMA(0, 0, At, B0); PG8_MMA(0, 1, At, B1); PG8_BAR; PG8_SCHED;
	s_setprio 1
	s_waitcnt lgkmcnt(0)
	v_mfma_f32_16x16x32_bf16 v[60:63], v[128:131], v[160:163], v[60:63]
	v_mfma_f32_16x16x32_bf16 v[56:59], v[136:139], v[160:163], v[56:59]
	v_mfma_f32_16x16x32_bf16 v[44:47], v[128:131], v[190:193], v[44:47]
	v_mfma_f32_16x16x32_bf16 v[40:43], v[136:139], v[190:193], v[40:43]
	v_mfma_f32_16x16x32_bf16 v[28:31], v[128:131], v[198:201], v[28:31]
	v_mfma_f32_16x16x32_bf16 v[24:27], v[136:139], v[198:201], v[24:27]
	v_mfma_f32_16x16x32_bf16 v[12:15], v[128:131], v[206:209], v[12:15]
	v_mfma_f32_16x16x32_bf16 v[8:11], v[136:139], v[206:209], v[8:11]
	v_mfma_f32_16x16x32_bf16 v[60:63], v[132:135], v[180:183], v[60:63]
	v_mfma_f32_16x16x32_bf16 v[56:59], v[140:143], v[180:183], v[56:59]
	v_mfma_f32_16x16x32_bf16 v[44:47], v[132:135], v[194:197], v[44:47]
	v_mfma_f32_16x16x32_bf16 v[40:43], v[140:143], v[194:197], v[40:43]
	v_mfma_f32_16x16x32_bf16 v[28:31], v[132:135], v[202:205], v[28:31]
	v_mfma_f32_16x16x32_bf16 v[24:27], v[140:143], v[202:205], v[24:27]
	v_mfma_f32_16x16x32_bf16 v[12:15], v[132:135], v[210:213], v[12:15]
	v_mfma_f32_16x16x32_bf16 v[8:11], v[140:143], v[210:213], v[8:11]
	s_setprio 0
	s_setprio 1
	v_mfma_f32_16x16x32_bf16 v[52:55], v[144:147], v[160:163], v[52:55]
	v_mfma_f32_16x16x32_bf16 v[48:51], v[152:155], v[160:163], v[48:51]
	v_mfma_f32_16x16x32_bf16 v[36:39], v[144:147], v[190:193], v[36:39]
	v_mfma_f32_16x16x32_bf16 v[32:35], v[152:155], v[190:193], v[32:35]
	v_mfma_f32_16x16x32_bf16 v[20:23], v[144:147], v[198:201], v[20:23]
	v_mfma_f32_16x16x32_bf16 v[16:19], v[152:155], v[198:201], v[16:19]
	v_mfma_f32_16x16x32_bf16 v[4:7], v[144:147], v[206:209], v[4:7]
	v_mfma_f32_16x16x32_bf16 v[0:3], v[152:155], v[206:209], v[0:3]
	v_mfma_f32_16x16x32_bf16 v[52:55], v[148:151], v[180:183], v[52:55]
	v_mfma_f32_16x16x32_bf16 v[48:51], v[156:159], v[180:183], v[48:51]
	v_mfma_f32_16x16x32_bf16 v[36:39], v[148:151], v[194:197], v[36:39]
	v_mfma_f32_16x16x32_bf16 v[32:35], v[156:159], v[194:197], v[32:35]
	v_mfma_f32_16x16x32_bf16 v[20:23], v[148:151], v[202:205], v[20:23]
	v_mfma_f32_16x16x32_bf16 v[16:19], v[156:159], v[202:205], v[16:19]
	v_mfma_f32_16x16x32_bf16 v[4:7], v[148:151], v[210:213], v[4:7]
	v_mfma_f32_16x16x32_bf16 v[0:3], v[156:159], v[210:213], v[0:3]
	s_setprio 0
	s_barrier
	s_add_i32 s69, 0, 0x18000
	s_add_i32 s70, 0, 0x1c000
	v_add_u32_e32 v140, s69, v185
	v_add_u32_e32 v156, s70, v185
	ds_read_b128 v[128:131], v140
	ds_read_b128 v[132:135], v140 offset:1024
	ds_read_b128 v[136:139], v140 offset:2048
	ds_read_b128 v[140:143], v140 offset:3072
	ds_read_b128 v[144:147], v156
	ds_read_b128 v[148:151], v156 offset:1024
	ds_read_b128 v[152:155], v156 offset:2048
	ds_read_b128 v[156:159], v156 offset:3072
	s_add_u32 s46, s46, 0x80000
	s_addc_u32 s47, s47, 0
	s_mov_b32 m0, s48
	v_lshl_add_u64 v[222:223], s[46:47], 0, v[166:167]
	ds_read_b128 v[160:163], v189 offset:32768
	ds_read_b128 v[180:183], v189 offset:33792
	ds_read_b128 v[190:193], v189 offset:34816
	ds_read_b128 v[194:197], v189 offset:35840
	ds_read_b128 v[198:201], v189 offset:36864
	ds_read_b128 v[202:205], v189 offset:37888
	ds_read_b128 v[206:209], v189 offset:38912
	ds_read_b128 v[210:213], v189 offset:39936
	global_load_lds_dwordx4 v[222:223], off
	v_lshl_add_u64 v[222:223], s[46:47], 0, v[170:171]
	s_mov_b32 m0, s49
	s_nop 0
	global_load_lds_dwordx4 v[222:223], off
	s_waitcnt vmcnt(8)
	s_waitcnt lgkmcnt(0)
	s_barrier
	s_setprio 1
	s_waitcnt lgkmcnt(0)
	v_mfma_f32_16x16x32_bf16 v[124:127], v[128:131], v[160:163], v[124:127]
	v_mfma_f32_16x16x32_bf16 v[120:123], v[136:139], v[160:163], v[120:123]
	v_mfma_f32_16x16x32_bf16 v[108:111], v[128:131], v[190:193], v[108:111]
	v_mfma_f32_16x16x32_bf16 v[104:107], v[136:139], v[190:193], v[104:107]
	v_mfma_f32_16x16x32_bf16 v[92:95], v[128:131], v[198:201], v[92:95]
	v_mfma_f32_16x16x32_bf16 v[88:91], v[136:139], v[198:201], v[88:91]
	v_mfma_f32_16x16x32_bf16 v[76:79], v[128:131], v[206:209], v[76:79]
	v_mfma_f32_16x16x32_bf16 v[72:75], v[136:139], v[206:209], v[72:75]
	v_mfma_f32_16x16x32_bf16 v[124:127], v[132:135], v[180:183], v[124:127]
	v_mfma_f32_16x16x32_bf16 v[120:123], v[140:143], v[180:183], v[120:123]
	v_mfma_f32_16x16x32_bf16 v[108:111], v[132:135], v[194:197], v[108:111]
	v_mfma_f32_16x16x32_bf16 v[104:107], v[140:143], v[194:197], v[104:107]
	v_mfma_f32_16x16x32_bf16 v[92:95], v[132:135], v[202:205], v[92:95]
	v_mfma_f32_16x16x32_bf16 v[88:91], v[140:143], v[202:205], v[88:91]
	v_mfma_f32_16x16x32_bf16 v[76:79], v[132:135], v[210:213], v[76:79]
	v_mfma_f32_16x16x32_bf16 v[72:75], v[140:143], v[210:213], v[72:75]
	s_setprio 0
	s_setprio 1
	v_mfma_f32_16x16x32_bf16 v[116:119], v[144:147], v[160:163], v[116:119]
	v_mfma_f32_16x16x32_bf16 v[112:115], v[152:155], v[160:163], v[112:115]
	v_mfma_f32_16x16x32_bf16 v[100:103], v[144:147], v[190:193], v[100:103]
	v_mfma_f32_16x16x32_bf16 v[96:99], v[152:155], v[190:193], v[96:99]
	v_mfma_f32_16x16x32_bf16 v[84:87], v[144:147], v[198:201], v[84:87]
	v_mfma_f32_16x16x32_bf16 v[80:83], v[152:155], v[198:201], v[80:83]
	v_mfma_f32_16x16x32_bf16 v[68:71], v[144:147], v[206:209], v[68:71]
	v_mfma_f32_16x16x32_bf16 v[64:67], v[152:155], v[206:209], v[64:67]
	v_mfma_f32_16x16x32_bf16 v[116:119], v[148:151], v[180:183], v[116:119]
	v_mfma_f32_16x16x32_bf16 v[112:115], v[156:159], v[180:183], v[112:115]
	v_mfma_f32_16x16x32_bf16 v[100:103], v[148:151], v[194:197], v[100:103]
	v_mfma_f32_16x16x32_bf16 v[96:99], v[156:159], v[194:197], v[96:99]
	v_mfma_f32_16x16x32_bf16 v[84:87], v[148:151], v[202:205], v[84:87]
	v_mfma_f32_16x16x32_bf16 v[80:83], v[156:159], v[202:205], v[80:83]
	v_mfma_f32_16x16x32_bf16 v[68:71], v[148:151], v[210:213], v[68:71]
	v_mfma_f32_16x16x32_bf16 v[64:67], v[156:159], v[210:213], v[64:67]
	s_setprio 0
	s_barrier
; #define PG8_STAGE(bufoff, gbase, voff) do { _Pragma("unroll") for (int _i = 0; _i < 2; ++_i) \
;         __builtin_amdgcn_global_load_lds((const unsigned*)((const char*)(gbase) + (voff)[_i]), (LAS unsigned*)(lds + (bufoff) + ldsw + _i * 8192), 16, 0, 0); } while (0)
; #define PG8_LDA(dst, b, h) do { _Pragma("unroll") for (int m = 0; m < 4; ++m) _Pragma("unroll") for (int k = 0; k < 2; ++k) dst[m][k] = *(const LAS bf16x8*)(lds + PG8_SA(b, h) + aoff + m * 2048 + k * 1024); } while (0)
; #define PG8_MMA(ai, bj, At, Bt) do { __builtin_amdgcn_s_setprio(1); _Pragma("unroll") for (int m = 0; m < 4; ++m) _Pragma("unroll") for (int n = 0; n < 2; ++n) _Pragma("unroll") for (int k = 0; k < 2; ++k) \
;         acc[ai][bj][m][n] = __builtin_amdgcn_mfma_f32_16x16x32_bf16(Bt[n][k], At[m][k], acc[ai][bj][m][n], 0, 0, 0); __builtin_amdgcn_s_setprio(0); } while (0)
; #define PG8_WAIT_V(n) asm volatile("s_waitcnt vmcnt(" #n ")" ::: "memory")
; #define PG8_WAIT_L(n) asm volatile("s_waitcnt lgkmcnt(" #n ")" ::: "memory")
; #define PG8_BAR __builtin_amdgcn_s_barrier()
; #define PG8_SCHED __builtin_amdgcn_sched_barrier(0)
; template <class Epi, bool ALIGN_EPI = false, bool SP2 = true>
; __device__ __forceinline__ void gemm_phase(LAS unsigned char* lds, const Gemm g, const StaticOrder& S, const Epi& E) {
;     ...
;             PG8_LDA(At, 1, 1); PG8_STAGE(PG8_SB(1, 0), b3, voffB); PG8_STAGE(PG8_SB(1, 1), b3 + hstep, voffB); PG8_STAGE(PG8_SA(1, 0), a3, voffA);
;             PG8_WAIT_V(8); PG8_WAIT_L(0); PG8_BAR; PG8_MMA(1, 0, At, B0); PG8_MMA(1, 1, At, B1); PG8_BAR; PG8_SCHED;
;     ...
;         if constexpr (ALIGN_EPI) { if (wr == 0) PG8_BAR; }
	s_add_i32 s46, s69, s33
	v_lshl_add_u64 v[214:215], v[214:215], 0, s[8:9]
	s_mov_b32 m0, s46
	ds_read_b128 v[160:163], v189 offset:49152
	ds_read_b128 v[180:183], v189 offset:50176
	ds_read_b128 v[190:193], v189 offset:51200
	ds_read_b128 v[194:197], v189 offset:52224
	ds_read_b128 v[198:201], v189 offset:53248
	ds_read_b128 v[202:205], v189 offset:54272
	ds_read_b128 v[206:209], v189 offset:55296
	ds_read_b128 v[210:213], v189 offset:56320
	global_load_lds_dwordx4 v[214:215], off
	s_add_i32 m0, s46, 0x2000
	s_add_u32 s44, s44, 0x80080
	v_lshl_add_u64 v[214:215], v[216:217], 0, s[8:9]
	s_addc_u32 s45, s45, 0
	s_add_i32 s46, s70, s33
	global_load_lds_dwordx4 v[214:215], off
	v_lshl_add_u64 v[214:215], s[44:45], 0, v[168:169]
	s_mov_b32 m0, s46
	s_nop 0
	global_load_lds_dwordx4 v[214:215], off
	v_lshl_add_u64 v[214:215], s[44:45], 0, v[172:173]
	s_add_i32 m0, s46, 0x2000
	s_nop 0
	global_load_lds_dwordx4 v[214:215], off
	v_lshl_add_u64 v[214:215], v[218:219], 0, s[8:9]
	s_mov_b32 m0, s54
	s_nop 0
	global_load_lds_dwordx4 v[214:215], off
	v_lshl_add_u64 v[214:215], v[220:221], 0, s[8:9]
	s_mov_b32 m0, s55
	s_nop 0
	global_load_lds_dwordx4 v[214:215], off
	s_waitcnt vmcnt(8)
	s_waitcnt lgkmcnt(0)
	s_barrier
	s_setprio 1
	s_waitcnt lgkmcnt(0)
	v_mfma_f32_16x16x32_bf16 v[60:63], v[128:131], v[160:163], v[60:63]
	v_mfma_f32_16x16x32_bf16 v[56:59], v[136:139], v[160:163], v[56:59]
	v_mfma_f32_16x16x32_bf16 v[44:47], v[128:131], v[190:193], v[44:47]
	v_mfma_f32_16x16x32_bf16 v[40:43], v[136:139], v[190:193], v[40:43]
	v_mfma_f32_16x16x32_bf16 v[28:31], v[128:131], v[198:201], v[28:31]
	v_mfma_f32_16x16x32_bf16 v[24:27], v[136:139], v[198:201], v[24:27]
	v_mfma_f32_16x16x32_bf16 v[12:15], v[128:131], v[206:209], v[12:15]
	v_mfma_f32_16x16x32_bf16 v[8:11], v[136:139], v[206:209], v[8:11]
	v_mfma_f32_16x16x32_bf16 v[60:63], v[132:135], v[180:183], v[60:63]
	v_mfma_f32_16x16x32_bf16 v[56:59], v[140:143], v[180:183], v[56:59]
	v_mfma_f32_16x16x32_bf16 v[44:47], v[132:135], v[194:197], v[44:47]
	v_mfma_f32_16x16x32_bf16 v[40:43], v[140:143], v[194:197], v[40:43]
	v_mfma_f32_16x16x32_bf16 v[28:31], v[132:135], v[202:205], v[28:31]
	v_mfma_f32_16x16x32_bf16 v[24:27], v[140:143], v[202:205], v[24:27]
	v_mfma_f32_16x16x32_bf16 v[12:15], v[132:135], v[210:213], v[12:15]
	v_mfma_f32_16x16x32_bf16 v[8:11], v[140:143], v[210:213], v[8:11]
	s_setprio 0
	s_setprio 1
	v_mfma_f32_16x16x32_bf16 v[52:55], v[144:147], v[160:163], v[52:55]
	v_mfma_f32_16x16x32_bf16 v[48:51], v[152:155], v[160:163], v[48:51]
	v_mfma_f32_16x16x32_bf16 v[36:39], v[144:147], v[190:193], v[36:39]
	v_mfma_f32_16x16x32_bf16 v[32:35], v[152:155], v[190:193], v[32:35]
	v_mfma_f32_16x16x32_bf16 v[20:23], v[144:147], v[198:201], v[20:23]
	v_mfma_f32_16x16x32_bf16 v[16:19], v[152:155], v[198:201], v[16:19]
	v_mfma_f32_16x16x32_bf16 v[4:7], v[144:147], v[206:209], v[4:7]
	v_mfma_f32_16x16x32_bf16 v[0:3], v[152:155], v[206:209], v[0:3]
	v_mfma_f32_16x16x32_bf16 v[52:55], v[148:151], v[180:183], v[52:55]
	v_mfma_f32_16x16x32_bf16 v[48:51], v[156:159], v[180:183], v[48:51]
	v_mfma_f32_16x16x32_bf16 v[36:39], v[148:151], v[194:197], v[36:39]
	v_mfma_f32_16x16x32_bf16 v[32:35], v[156:159], v[194:197], v[32:35]
	v_mfma_f32_16x16x32_bf16 v[20:23], v[148:151], v[202:205], v[20:23]
	v_mfma_f32_16x16x32_bf16 v[16:19], v[156:159], v[202:205], v[16:19]
	v_mfma_f32_16x16x32_bf16 v[4:7], v[148:151], v[210:213], v[4:7]
	v_mfma_f32_16x16x32_bf16 v[0:3], v[156:159], v[210:213], v[0:3]
	s_add_i32 s68, s68, 2
	s_add_u32 s40, s40, 0x100
	s_addc_u32 s41, s41, 0
	s_add_u32 s66, s66, 0x100
	s_addc_u32 s67, s67, 0
	s_cmp_gt_u32 s68, 29
	s_setprio 0
	s_barrier
	s_cbranch_scc0 .LBB0_855
	s_and_b64 vcc, exec, s[10:11]
	s_cbranch_vccz .LBB0_858
	s_barrier
; __device__ __forceinline__ float bf_lo(unsigned w) { return __uint_as_float(w << 16); }
; __device__ __forceinline__ float bf_hi(unsigned w) { return __uint_as_float(w & 0xffff0000u); }
; __device__ __forceinline__ float fast_sigmoid(float v) { return __builtin_amdgcn_rcpf(1.0f + __builtin_amdgcn_exp2f(-1.4426950408889634f * v)); }
;     __device__ __forceinline__ void operator()(const Acc& acc, const Unit& u, int wr, int wc, int fr, int fq) const {
;         const int cb = u.pn * 256 + wc * 32 + 8 * fq;
; #pragma unroll
;         for (int ai = 0; ai < 2; ++ai) {
;             const size_t o0 = (size_t)(u.pm * 256 + ai * 128 + wr * 64 + fr) * DM + cb;
;             u32x4 xw[4][2], pw[4][2];
; #pragma unroll
;             for (int m = 0; m < 4; ++m)
; #pragma unroll
;                 for (int bj = 0; bj < 2; ++bj) { const size_t o = o0 + (size_t)m * 16 * DM + bj * 128; xw[m][bj] = *(const u32x4*)(xin + o); pw[m][bj] = *(const u32x4*)(pp + o); }
; #pragma unroll
;             for (int m = 0; m < 4; ++m)
; #pragma unroll
;                 for (int bj = 0; bj < 2; ++bj) {
;                     const size_t o = o0 + (size_t)m * 16 * DM + bj * 128;
;                     const u32x4 x = xw[m][bj], p = pw[m][bj];
;                     const f32x4 a0 = acc[ai][bj][m][0], a1 = acc[ai][bj][m][1];
;                     f32x4 r0, r1;
;                     r0[0] = bf_lo(x.x) + fast_sigmoid(a0[0]) * bf_lo(p.x); r0[1] = bf_hi(x.x) + fast_sigmoid(a0[1]) * bf_hi(p.x);
;                     r0[2] = bf_lo(x.y) + fast_sigmoid(a0[2]) * bf_lo(p.y); r0[3] = bf_hi(x.y) + fast_sigmoid(a0[3]) * bf_hi(p.y);
;                     r1[0] = bf_lo(x.z) + fast_sigmoid(a1[0]) * bf_lo(p.z); r1[1] = bf_hi(x.z) + fast_sigmoid(a1[1]) * bf_hi(p.z);
;                     r1[2] = bf_lo(x.w) + fast_sigmoid(a1[2]) * bf_lo(p.w); r1[3] = bf_hi(x.w) + fast_sigmoid(a1[3]) * bf_hi(p.w);
.LBB0_858:
	s_sub_u32 s98, s52, 0x42f5f00
	s_subb_u32 s99, s53, 0
	v_mov_b32_e32 v252, s98
	v_mov_b32_e32 v253, s99
	global_load_dword v250, v[252:253], off sc1
	v_lshl_add_u32 v182, s42, 8, v184
	v_lshl_or_b32 v180, s63, 8, v186
	v_ashrrev_i32_e32 v183, 31, v182
	v_ashrrev_i32_e32 v181, 31, v180
	v_lshlrev_b64 v[128:129], 11, v[182:183]
	v_lshl_add_u64 v[218:219], v[128:129], 0, v[180:181]
	v_lshlrev_b64 v[128:129], 1, v[218:219]
	v_lshl_add_u64 v[130:131], s[52:53], 0, v[128:129]
	v_lshl_add_u64 v[132:133], s[6:7], 0, v[128:129]
	global_load_dwordx4 v[190:193], v[130:131], off
	global_load_dwordx4 v[194:197], v[132:133], off
	v_mul_f32_e32 v124, 0xbfb8aa3b, v124
	v_mul_f32_e32 v125, 0xbfb8aa3b, v125
	v_mul_f32_e32 v120, 0xbfb8aa3b, v120
	v_mul_f32_e32 v121, 0xbfb8aa3b, v121
	v_exp_f32_e32 v124, v124
	v_exp_f32_e32 v125, v125
	v_exp_f32_e32 v120, v120
	v_exp_f32_e32 v121, v121
	v_or_b32_e32 v128, 0x100, v128
	v_add_f32_e32 v134, 1.0, v124
	v_add_f32_e32 v135, 1.0, v125
	v_add_f32_e32 v138, 1.0, v120
	v_add_f32_e32 v139, 1.0, v121
	v_lshl_add_u64 v[120:121], s[52:53], 0, v[128:129]
	v_lshl_add_u64 v[124:125], s[6:7], 0, v[128:129]
	global_load_dwordx4 v[198:201], v[120:121], off
	global_load_dwordx4 v[202:205], v[124:125], off
	v_mul_f32_e32 v126, 0xbfb8aa3b, v126
	v_mul_f32_e32 v127, 0xbfb8aa3b, v127
	v_exp_f32_e32 v126, v126
	v_add_co_u32_e32 v120, vcc, s51, v130
	v_exp_f32_e32 v127, v127
	s_nop 0
	v_addc_co_u32_e32 v121, vcc, 0, v131, vcc
	v_add_co_u32_e32 v124, vcc, s51, v132
	v_add_f32_e32 v136, 1.0, v126
	s_nop 0
	v_addc_co_u32_e32 v125, vcc, 0, v133, vcc
	v_add_co_u32_e32 v126, vcc, s59, v130
	v_add_f32_e32 v137, 1.0, v127
	s_nop 0
	v_addc_co_u32_e32 v127, vcc, 0, v131, vcc
	v_add_co_u32_e32 v128, vcc, s59, v132
	v_rcp_f32_e32 v216, v134
	s_nop 0
	v_addc_co_u32_e32 v129, vcc, 0, v133, vcc
	v_add_co_u32_e32 v130, vcc, s60, v130
	v_rcp_f32_e32 v217, v135
	s_nop 0
	v_addc_co_u32_e32 v131, vcc, 0, v131, vcc
	v_add_co_u32_e32 v214, vcc, s60, v132
	v_rcp_f32_e32 v220, v136
	s_nop 0
	v_addc_co_u32_e32 v215, vcc, 0, v133, vcc
	v_rcp_f32_e32 v221, v137
	v_rcp_f32_e32 v222, v138
	v_rcp_f32_e32 v223, v139
	global_load_dwordx4 v[206:209], v[120:121], off
	global_load_dwordx4 v[160:163], v[120:121], off offset:256
	global_load_dwordx4 v[210:213], v[124:125], off
	global_load_dwordx4 v[156:159], v[124:125], off offset:256
	global_load_dwordx4 v[152:155], v[126:127], off
	global_load_dwordx4 v[144:147], v[126:127], off offset:256
	global_load_dwordx4 v[148:151], v[128:129], off
	global_load_dwordx4 v[140:143], v[128:129], off offset:256
	global_load_dwordx4 v[136:139], v[130:131], off
	s_nop 0
	global_load_dwordx4 v[128:131], v[130:131], off offset:256
	s_nop 0
	global_load_dwordx4 v[132:135], v[214:215], off
	global_load_dwordx4 v[124:127], v[214:215], off offset:256
	v_mul_f32_e32 v122, 0xbfb8aa3b, v122
	v_mul_f32_e32 v123, 0xbfb8aa3b, v123
	v_exp_f32_e32 v122, v122
	v_exp_f32_e32 v123, v123
	v_mul_f32_e32 v116, 0xbfb8aa3b, v116
	v_mul_f32_e32 v117, 0xbfb8aa3b, v117
	v_exp_f32_e32 v116, v116
	v_exp_f32_e32 v117, v117
	v_mul_f32_e32 v118, 0xbfb8aa3b, v118
	v_mul_f32_e32 v119, 0xbfb8aa3b, v119
	v_exp_f32_e32 v118, v118
	v_exp_f32_e32 v119, v119
	v_mul_f32_e32 v112, 0xbfb8aa3b, v112
	v_mul_f32_e32 v113, 0xbfb8aa3b, v113
	v_exp_f32_e32 v112, v112
	v_exp_f32_e32 v113, v113
	v_mul_f32_e32 v114, 0xbfb8aa3b, v114
	v_mul_f32_e32 v115, 0xbfb8aa3b, v115
	v_exp_f32_e32 v114, v114
	v_exp_f32_e32 v115, v115
	v_add_f32_e32 v116, 1.0, v116
	v_add_f32_e32 v117, 1.0, v117
	v_mul_f32_e32 v108, 0xbfb8aa3b, v108
	v_mul_f32_e32 v109, 0xbfb8aa3b, v109
	s_waitcnt vmcnt(0)
	s_mov_b32 s99, 0
.Lp10_gchk:
	v_readfirstlane_b32 s98, v250
	s_cmp_ge_u32 s98, 0x100
	s_cbranch_scc1 .Lp10_gok
	s_sleep 1
	s_add_u32 s99, s99, 1
	s_cmp_gt_u32 s99, 0x40000
	s_cbranch_scc1 .Lp10_gok
	global_load_dword v250, v[252:253], off sc1
	s_waitcnt vmcnt(0)
	s_branch .Lp10_gchk
